# memory-attention phases (both layers): LDS fragment reads of the QK/PV MFMA chains issued one block of 7 MFMAs ahead into spare registers with counted lgkmcnt waits (bit-identical), on top of v39
# speedup vs baseline: 1.0023x; 1.0014x over previous
; #define LAS __attribute__((address_space(3)))
; template <bool SAMPLE>
; __device__ __forceinline__ void mem_unit(const Params& p, int l, LAS unsigned char* lds, int unit, int tid, int wave, int lane) {
;     ...
;         for (int hb = 0; hb < 2; ++hb) {
;             float kk[4][8], vv[4][8];
; #pragma unroll
;             for (int it = 0; it < 4; ++it) { const int s = (tid >> 4) + 32 * (4 * hb + it);
;                 const float* kp; const float* vp;
;                 if (!SAMPLE) { kp = (const float*)(p.ws + W_MKV) + ((size_t)l * 1024 + b * 256 + s) * 1024 + h * 128 + sub * 8; vp = kp + 512; }
;                 else { const size_t o = ((((size_t)l * 128 + b) * 256 + s) * 4 + h) * 128 + sub * 8; kp = p.in[I_CMK] + o; vp = p.in[I_CMV] + o; }
;                 if (SAMPLE) { pg8::ld8f_nt(kp, kk[it]); pg8::ld8f_nt(vp, vv[it]); } else { pg8::ld8f(kp, kk[it]); pg8::ld8f(vp, vv[it]); } }
; #pragma unroll
;             for (int it = 0; it < 4; ++it) { const int s = (tid >> 4) + 32 * (4 * hb + it);
;                 float (&k)[8] = kk[it]; float (&v)[8] = vv[it];
;                 if (!SAMPLE) { float ss = 0.f;
; #pragma unroll
;                     for (int e = 0; e < 8; ++e) ss += k[e] * k[e];
;                     ss += __shfl_xor(ss, 1); ss += __shfl_xor(ss, 2); ss += __shfl_xor(ss, 4); ss += __shfl_xor(ss, 8);
;                     const float rs = rsqrtf(ss * (1.f / 128.f) + EPS);
; #pragma unroll
;                     for (int e = 0; e < 8; ++e) k[e] *= rs * kg[e];
;                     if (qt == 0) { const size_t o = ((((size_t)l * 4 + b) * 256 + s) * 4 + h) * 128 + sub * 8;
;                         *(f32x4*)(p.out + O_MKP + o) = (f32x4){k[0], k[1], k[2], k[3]}; *(f32x4*)(p.out + O_MKP + o + 4) = (f32x4){k[4], k[5], k[6], k[7]};
;                         *(f32x4*)(p.out + O_MVP + o) = (f32x4){v[0], v[1], v[2], v[3]}; *(f32x4*)(p.out + O_MVP + o + 4) = (f32x4){v[4], v[5], v[6], v[7]}; }
;                 }
;                 *(LAS bf16x8*)(Kl + s * MEM_KS + sub * 8) = pack8(k);
;                 *(LAS bf16x8*)(Vt + s * MEM_VS + sub * 8) = pack8(v);
;             }
;         }
;     }
;     __syncthreads();
;     if (!SAMPLE || wave == 0) {
; #pragma unroll 1
;       for (int qq = 0; qq < (SAMPLE ? 1 : 4); ++qq) {
;         int q16 = lane & 15, kq = lane >> 4; asm volatile("" : "+v"(q16), "+v"(kq));
;         size_t row; bool st;
.LBB0_599:
	s_waitcnt vmcnt(1)
	v_add_u32_e32 v66, s8, v81
	v_ashrrev_i32_e32 v67, 31, v66
	v_add_u32_e32 v6, 0x60, v66
	v_lshl_add_u64 v[8:9], v[66:67], 0, s[10:11]
	v_add_u32_e32 v2, 32, v66
	v_add_u32_e32 v4, 64, v66
	v_ashrrev_i32_e32 v7, 31, v6
	v_lshlrev_b64 v[8:9], 11, v[8:9]
	v_ashrrev_i32_e32 v3, 31, v2
	v_ashrrev_i32_e32 v5, 31, v4
	v_lshl_add_u64 v[6:7], v[6:7], 0, s[10:11]
	v_or_b32_e32 v8, v8, v0
	v_lshl_add_u64 v[2:3], v[2:3], 0, s[10:11]
	v_lshl_add_u64 v[4:5], v[4:5], 0, s[10:11]
	v_lshlrev_b64 v[22:23], 11, v[6:7]
	v_lshl_add_u64 v[6:7], s[78:79], 0, v[8:9]
	v_lshl_add_u64 v[14:15], s[80:81], 0, v[8:9]
	v_lshlrev_b64 v[18:19], 11, v[2:3]
	v_lshlrev_b64 v[20:21], 11, v[4:5]
	global_load_dwordx4 v[2:5], v[6:7], off nt
	s_nop 0
	global_load_dwordx4 v[6:9], v[6:7], off offset:16 nt
	s_nop 0
	global_load_dwordx4 v[10:13], v[14:15], off offset:16 nt
	s_nop 0
	global_load_dwordx4 v[14:17], v[14:15], off nt
	v_or_b32_e32 v18, v18, v0
	v_or_b32_e32 v20, v20, v0
	v_or_b32_e32 v22, v22, v0
	v_lshl_add_u64 v[24:25], s[78:79], 0, v[18:19]
	v_lshl_add_u64 v[30:31], s[80:81], 0, v[18:19]
	s_waitcnt vmcnt(4)
	v_lshl_add_u64 v[38:39], s[78:79], 0, v[20:21]
	v_lshl_add_u64 v[46:47], s[80:81], 0, v[20:21]
	v_lshl_add_u64 v[54:55], s[78:79], 0, v[22:23]
	v_lshl_add_u64 v[62:63], s[80:81], 0, v[22:23]
	global_load_dwordx4 v[18:21], v[24:25], off nt
	s_nop 0
	global_load_dwordx4 v[22:25], v[24:25], off offset:16 nt
	s_nop 0
	global_load_dwordx4 v[26:29], v[30:31], off nt
	s_nop 0
	global_load_dwordx4 v[30:33], v[30:31], off offset:16 nt
	s_nop 0
	global_load_dwordx4 v[34:37], v[38:39], off nt
	s_nop 0
	global_load_dwordx4 v[38:41], v[38:39], off offset:16 nt
	s_nop 0
	global_load_dwordx4 v[42:45], v[46:47], off nt
	s_nop 0
	global_load_dwordx4 v[46:49], v[46:47], off offset:16 nt
	s_nop 0
	global_load_dwordx4 v[50:53], v[54:55], off nt
	s_nop 0
	global_load_dwordx4 v[54:57], v[54:55], off offset:16 nt
	s_nop 0
	global_load_dwordx4 v[58:61], v[62:63], off nt
	s_nop 0
	global_load_dwordx4 v[62:65], v[62:63], off offset:16 nt
	v_cndmask_b32_e64 v1, 0, 1, s[0:1]
	v_cmp_ne_u32_e32 vcc, 1, v1
	v_mul_lo_u32 v1, v66, s30
	v_add_u32_e32 v66, v96, v1
	v_add_u32_e32 v1, v97, v1
	s_movk_i32 s8, 0x80
	s_mov_b64 s[0:1], 0
	s_and_b64 vcc, exec, vcc
	s_waitcnt vmcnt(15)
	v_cvt_pk_bf16_f32 v2, v2, v3
	v_cvt_pk_bf16_f32 v3, v4, v5
	s_waitcnt vmcnt(14)
	v_cvt_pk_bf16_f32 v4, v6, v7
	v_cvt_pk_bf16_f32 v5, v8, v9
	ds_write_b128 v66, v[2:5]
	s_waitcnt vmcnt(12)
	v_cvt_pk_bf16_f32 v2, v14, v15
	v_cvt_pk_bf16_f32 v3, v16, v17
	v_cvt_pk_bf16_f32 v4, v10, v11
	v_cvt_pk_bf16_f32 v5, v12, v13
	ds_write_b128 v1, v[2:5]
	s_waitcnt vmcnt(11)
	v_cvt_pk_bf16_f32 v2, v18, v19
	v_cvt_pk_bf16_f32 v3, v20, v21
	s_waitcnt vmcnt(10)
	v_cvt_pk_bf16_f32 v4, v22, v23
	v_cvt_pk_bf16_f32 v5, v24, v25
	ds_write_b128 v66, v[2:5] offset:8704
	s_waitcnt vmcnt(9)
	v_cvt_pk_bf16_f32 v2, v26, v27
	v_cvt_pk_bf16_f32 v3, v28, v29
	s_waitcnt vmcnt(8)
	v_cvt_pk_bf16_f32 v4, v30, v31
	v_cvt_pk_bf16_f32 v5, v32, v33
	ds_write_b128 v1, v[2:5] offset:8704
	s_waitcnt vmcnt(7)
	v_cvt_pk_bf16_f32 v2, v34, v35
	v_cvt_pk_bf16_f32 v3, v36, v37
	s_waitcnt vmcnt(6)
	v_cvt_pk_bf16_f32 v4, v38, v39
	v_cvt_pk_bf16_f32 v5, v40, v41
	ds_write_b128 v66, v[2:5] offset:17408
	s_waitcnt vmcnt(5)
	v_cvt_pk_bf16_f32 v2, v42, v43
	v_cvt_pk_bf16_f32 v3, v44, v45
	s_waitcnt vmcnt(4)
	v_cvt_pk_bf16_f32 v4, v46, v47
	v_cvt_pk_bf16_f32 v5, v48, v49
	ds_write_b128 v1, v[2:5] offset:17408
	s_waitcnt vmcnt(3)
	v_cvt_pk_bf16_f32 v2, v50, v51
	v_cvt_pk_bf16_f32 v3, v52, v53
	s_waitcnt vmcnt(2)
	v_cvt_pk_bf16_f32 v4, v54, v55
	v_cvt_pk_bf16_f32 v5, v56, v57
	ds_write_b128 v66, v[2:5] offset:26112
	s_waitcnt vmcnt(1)
	v_cvt_pk_bf16_f32 v2, v58, v59
	v_cvt_pk_bf16_f32 v3, v60, v61
	s_waitcnt vmcnt(0)
	v_cvt_pk_bf16_f32 v4, v62, v63
	v_cvt_pk_bf16_f32 v5, v64, v65
	ds_write_b128 v1, v[2:5] offset:26112
	s_cbranch_vccz .LBB0_599
	s_andn2_b64 vcc, exec, s[4:5]
	s_waitcnt lgkmcnt(0)
	s_barrier
	s_cbranch_vccnz .LBB0_618
	s_lshl_b32 s0, s2, 3
	s_add_i32 s1, s0, 0x8000
	s_lshl_b32 s0, s3, 1
	v_mov_b32_e32 v37, v95
	v_mov_b32_e32 v36, v94
	s_add_u32 s2, s64, s0
	s_addc_u32 s3, s65, 0
	v_and_or_b32 v0, v36, 7, s1
	v_lshlrev_b32_e32 v82, 10, v0
	v_lshlrev_b32_e32 v16, 3, v37
	v_lshl_add_u64 v[0:1], s[2:3], 0, v[82:83]
	v_ashrrev_i32_e32 v17, 31, v16
	v_lshl_add_u64 v[12:13], v[16:17], 1, v[0:1]
	global_load_dwordx4 v[0:3], v[12:13], off
	global_load_dwordx4 v[4:7], v[12:13], off offset:64
	global_load_dwordx4 v[8:11], v[12:13], off offset:128
	s_nop 0
	global_load_dwordx4 v[12:15], v[12:13], off offset:192
	v_and_b32_e32 v19, 64, v99
	v_xor_b32_e32 v18, 16, v99
	v_add_u32_e32 v34, 64, v19
	v_cmp_lt_i32_e32 vcc, v18, v34
	v_lshl_add_u64 v[24:25], v[16:17], 2, s[46:47]
	s_waitcnt vmcnt(3)
	v_and_b32_e32 v40, 0xffff0000, v0
	v_cndmask_b32_e32 v18, v99, v18, vcc
	v_lshlrev_b32_e32 v38, 2, v18
	global_load_dwordx4 v[16:19], v[24:25], off offset:16
	global_load_dwordx4 v[20:23], v[24:25], off
	v_lshlrev_b32_e32 v35, 16, v0
	s_waitcnt vmcnt(3)
; __device__ __forceinline__ void unpack8(const v4u w, float (&o)[8]) { o[0] = bflo(w.x); o[1] = bfhi(w.x); o[2] = bflo(w.y); o[3] = bfhi(w.y); o[4] = bflo(w.z); o[5] = bfhi(w.z); o[6] = bflo(w.w); o[7] = bfhi(w.w); }
; __device__ __forceinline__ bf16x8 pack8(const float (&o)[8]) { v4u w; w.x = pk2(o[0], o[1]); w.y = pk2(o[2], o[3]); w.z = pk2(o[4], o[5]); w.w = pk2(o[6], o[7]); return __builtin_bit_cast(bf16x8, w); }
; template <bool SAMPLE>
; __device__ __forceinline__ void mem_unit(const Params& p, int l, LAS unsigned char* lds, int unit, int tid, int wave, int lane) {
;     ...
;         int q16 = lane & 15, kq = lane >> 4; asm volatile("" : "+v"(q16), "+v"(kq));
;         size_t row; bool st;
;         if (!SAMPLE) { row = (size_t)b * 8192 + (qt * 4 + qq) * 128 + 16 * wave + q16; st = true; } else { row = (size_t)MP + 8 * b + (q16 & 7); st = q16 < 8; }
;         bf16x8 qf[4];
;         {
;             float qv[4][8]; float ss = 0.f;
; #pragma unroll
;             for (int dc = 0; dc < 4; ++dc) { unpack8(*(const v4u*)(MQ + row * 512 + h * 128 + 32 * dc + 8 * kq), qv[dc]);
; #pragma unroll
;                 for (int e = 0; e < 8; ++e) ss += qv[dc][e] * qv[dc][e]; }
;             ss += __shfl_xor(ss, 16); ss += __shfl_xor(ss, 32);
;             const float rs = rsqrtf(ss * (1.f / 128.f) + EPS) * 0.08838834764831845f;
; #pragma unroll
;             for (int dc = 0; dc < 4; ++dc) { float qg[8]; pg8::ld8f(p.in[I_MQG] + l * 128 + 32 * dc + 8 * kq, qg);
; #pragma unroll
;                 for (int e = 0; e < 8; ++e) qv[dc][e] *= rs * qg[e];
;                 qf[dc] = pack8(qv[dc]); }
	v_lshlrev_b32_e32 v55, 16, v8
	v_and_b32_e32 v56, 0xffff0000, v8
	v_mul_f32_e32 v8, v40, v40
	v_lshlrev_b32_e32 v41, 16, v1
	v_fmac_f32_e32 v8, v35, v35
	v_and_b32_e32 v42, 0xffff0000, v1
	v_fmac_f32_e32 v8, v41, v41
	v_lshlrev_b32_e32 v43, 16, v2
	v_fmac_f32_e32 v8, v42, v42
	v_and_b32_e32 v44, 0xffff0000, v2
	v_fmac_f32_e32 v8, v43, v43
	v_lshlrev_b32_e32 v45, 16, v3
	v_fmac_f32_e32 v8, v44, v44
	v_and_b32_e32 v46, 0xffff0000, v3
	v_fmac_f32_e32 v8, v45, v45
	v_lshlrev_b32_e32 v47, 16, v4
	v_fmac_f32_e32 v8, v46, v46
	v_and_b32_e32 v48, 0xffff0000, v4
	v_fmac_f32_e32 v8, v47, v47
	v_lshlrev_b32_e32 v49, 16, v5
	v_fmac_f32_e32 v8, v48, v48
	v_and_b32_e32 v50, 0xffff0000, v5
	v_fmac_f32_e32 v8, v49, v49
	v_lshlrev_b32_e32 v51, 16, v6
	v_fmac_f32_e32 v8, v50, v50
	v_and_b32_e32 v52, 0xffff0000, v6
	v_fmac_f32_e32 v8, v51, v51
	v_lshlrev_b32_e32 v53, 16, v7
	v_fmac_f32_e32 v8, v52, v52
	v_and_b32_e32 v54, 0xffff0000, v7
	v_fmac_f32_e32 v8, v53, v53
	v_fmac_f32_e32 v8, v54, v54
	v_fmac_f32_e32 v8, v55, v55
	v_lshlrev_b32_e32 v57, 16, v9
	v_fmac_f32_e32 v8, v56, v56
	v_and_b32_e32 v58, 0xffff0000, v9
	v_fmac_f32_e32 v8, v57, v57
	v_lshlrev_b32_e32 v59, 16, v10
	v_fmac_f32_e32 v8, v58, v58
	v_and_b32_e32 v60, 0xffff0000, v10
	v_fmac_f32_e32 v8, v59, v59
	v_lshlrev_b32_e32 v61, 16, v11
	v_fmac_f32_e32 v8, v60, v60
	v_and_b32_e32 v62, 0xffff0000, v11
	s_waitcnt vmcnt(2)
	v_and_b32_e32 v26, 0xffff0000, v12
	v_lshlrev_b32_e32 v27, 16, v12
	v_fmac_f32_e32 v8, v61, v61
	v_pk_mul_f32 v[0:1], v[26:27], v[26:27]
	v_fmac_f32_e32 v8, v62, v62
	v_and_b32_e32 v28, 0xffff0000, v13
	v_lshlrev_b32_e32 v29, 16, v13
	v_add_f32_e32 v1, v1, v8
	v_pk_mul_f32 v[2:3], v[28:29], v[28:29]
	v_add_f32_e32 v0, v0, v1
	v_and_b32_e32 v30, 0xffff0000, v14
	v_lshlrev_b32_e32 v31, 16, v14
	v_add_f32_e32 v0, v3, v0
	v_pk_mul_f32 v[4:5], v[30:31], v[30:31]
	v_add_f32_e32 v0, v2, v0
	v_and_b32_e32 v32, 0xffff0000, v15
	v_lshlrev_b32_e32 v33, 16, v15
	v_add_f32_e32 v0, v5, v0
	v_pk_mul_f32 v[6:7], v[32:33], v[32:33]
	v_add_f32_e32 v0, v4, v0
	v_add_f32_e32 v0, v7, v0
	v_add_f32_e32 v0, v6, v0
	ds_bpermute_b32 v1, v38, v0
	v_xor_b32_e32 v2, 32, v99
	v_cmp_lt_i32_e32 vcc, v2, v34
	s_waitcnt lgkmcnt(0)
	v_add_f32_e32 v0, v0, v1
	v_cndmask_b32_e32 v2, v99, v2, vcc
	v_lshlrev_b32_e32 v39, 2, v2
	ds_bpermute_b32 v1, v39, v0
	s_waitcnt lgkmcnt(0)
	v_add_f32_e32 v0, v0, v1
	v_fmamk_f32 v0, v0, 0x3c000000, v98
	v_mul_f32_e32 v1, 0x4b800000, v0
	v_cmp_gt_f32_e32 vcc, s31, v0
	s_nop 1
	v_cndmask_b32_e32 v0, v0, v1, vcc
	v_rsq_f32_e32 v0, v0
	s_nop 0
	v_mul_f32_e32 v1, 0x45800000, v0
	v_cndmask_b32_e32 v0, v0, v1, vcc
	v_mul_f32_e32 v34, 0x3db504f3, v0
	s_waitcnt vmcnt(0)
	v_mul_f32_e32 v0, v20, v34
	v_mul_f32_e32 v1, v21, v34
	v_mul_f32_e32 v2, v22, v34
	v_mul_f32_e32 v3, v23, v34
	v_mul_f32_e32 v4, v16, v34
	v_mul_f32_e32 v5, v17, v34
	v_mul_f32_e32 v6, v18, v34
	v_mul_f32_e32 v7, v19, v34
	v_mul_f32_e32 v0, v0, v35
	v_mul_f32_e32 v1, v1, v40
	v_mul_f32_e32 v2, v2, v41
	v_mul_f32_e32 v3, v3, v42
	v_mul_f32_e32 v4, v4, v43
	v_mul_f32_e32 v5, v5, v44
	v_mul_f32_e32 v6, v6, v45
	v_mul_f32_e32 v7, v7, v46
	v_cvt_pk_bf16_f32 v0, v0, v1
	v_cvt_pk_bf16_f32 v1, v2, v3
	v_cvt_pk_bf16_f32 v2, v4, v5
	v_cvt_pk_bf16_f32 v3, v6, v7
	global_load_dwordx4 v[4:7], v[24:25], off offset:128
	global_load_dwordx4 v[8:11], v[24:25], off offset:144
	v_lshlrev_b32_e32 v20, 4, v37
	v_mul_lo_u32 v21, v36, s30
	v_add3_u32 v92, 0, v20, v21
	s_waitcnt vmcnt(1)
	v_mul_f32_e32 v4, v4, v34
	v_mul_f32_e32 v5, v5, v34
	v_mul_f32_e32 v6, v6, v34
	v_mul_f32_e32 v7, v7, v34
	s_waitcnt vmcnt(0)
	v_mul_f32_e32 v8, v8, v34
	v_mul_f32_e32 v9, v9, v34
	v_mul_f32_e32 v10, v10, v34
	v_mul_f32_e32 v11, v11, v34
	v_mul_f32_e32 v4, v4, v47
	v_mul_f32_e32 v5, v5, v48
	v_mul_f32_e32 v6, v6, v49
	v_mul_f32_e32 v7, v7, v50
	v_mul_f32_e32 v12, v8, v51
	v_mul_f32_e32 v13, v9, v52
	v_mul_f32_e32 v14, v10, v53
	v_mul_f32_e32 v11, v11, v54
	v_cvt_pk_bf16_f32 v8, v4, v5
	v_cvt_pk_bf16_f32 v9, v6, v7
	v_cvt_pk_bf16_f32 v10, v12, v13
	v_cvt_pk_bf16_f32 v11, v14, v11
	global_load_dwordx4 v[4:7], v[24:25], off offset:256
	global_load_dwordx4 v[12:15], v[24:25], off offset:272
	s_waitcnt vmcnt(1)
	v_mul_f32_e32 v4, v4, v34
	v_mul_f32_e32 v5, v5, v34
	v_mul_f32_e32 v6, v6, v34
	v_mul_f32_e32 v7, v7, v34
	s_waitcnt vmcnt(0)
	v_mul_f32_e32 v12, v12, v34
	v_mul_f32_e32 v13, v13, v34
	v_mul_f32_e32 v14, v14, v34
	v_mul_f32_e32 v15, v15, v34
	v_mul_f32_e32 v4, v4, v55
	v_mul_f32_e32 v5, v5, v56
	v_mul_f32_e32 v6, v6, v57
	v_mul_f32_e32 v7, v7, v58
	v_mul_f32_e32 v12, v12, v59
	v_mul_f32_e32 v13, v13, v60
	v_mul_f32_e32 v14, v14, v61
	v_mul_f32_e32 v15, v15, v62
	v_cvt_pk_bf16_f32 v4, v4, v5
	v_cvt_pk_bf16_f32 v5, v6, v7
	v_cvt_pk_bf16_f32 v6, v12, v13
	v_cvt_pk_bf16_f32 v7, v14, v15
	global_load_dwordx4 v[12:15], v[24:25], off offset:384
	global_load_dwordx4 v[16:19], v[24:25], off offset:400
	s_waitcnt vmcnt(1)
	v_mul_f32_e32 v12, v12, v34
	v_mul_f32_e32 v13, v13, v34
	v_mul_f32_e32 v14, v14, v34
	v_mul_f32_e32 v15, v15, v34
	s_waitcnt vmcnt(0)
; #define LAS __attribute__((address_space(3)))
; __device__ __forceinline__ bf16x8 pack8(const float (&o)[8]) { v4u w; w.x = pk2(o[0], o[1]); w.y = pk2(o[2], o[3]); w.z = pk2(o[4], o[5]); w.w = pk2(o[6], o[7]); return __builtin_bit_cast(bf16x8, w); }
; template <bool SAMPLE>
; __device__ __forceinline__ void mem_unit(const Params& p, int l, LAS unsigned char* lds, int unit, int tid, int wave, int lane) {
;     ...
;             for (int dc = 0; dc < 4; ++dc) { float qg[8]; pg8::ld8f(p.in[I_MQG] + l * 128 + 32 * dc + 8 * kq, qg);
; #pragma unroll
;                 for (int e = 0; e < 8; ++e) qv[dc][e] *= rs * qg[e];
;                 qf[dc] = pack8(qv[dc]); }
;         }
;         f32x4 S[8][2]; float mx = -INFINITY;
; #pragma unroll
;         for (int cc = 0; cc < 8; ++cc)
; #pragma unroll
;             for (int tt = 0; tt < 2; ++tt) { const int kb = 32 * cc + 16 * tt; f32x4 a = (f32x4){0.f, 0.f, 0.f, 0.f};
; #pragma unroll
;                 for (int dc = 0; dc < 4; ++dc) { const bf16x8 kf = *(const LAS bf16x8*)(Kl + (kb + q16) * MEM_KS + 32 * dc + 8 * kq);
;                     a = __builtin_amdgcn_mfma_f32_16x16x32_bf16(kf, qf[dc], a, 0, 0, 0); }
; #pragma unroll
;                 for (int e = 0; e < 4; ++e) mx = fmaxf(mx, a[e]);
;                 S[cc][tt] = a; }
	v_mul_f32_e32 v16, v16, v34
	v_mul_f32_e32 v17, v17, v34
	v_mul_f32_e32 v18, v18, v34
	v_mul_f32_e32 v19, v19, v34
	v_mul_f32_e32 v12, v12, v27
	v_mul_f32_e32 v13, v13, v26
	v_mul_f32_e32 v14, v14, v29
	v_mul_f32_e32 v15, v15, v28
	v_mul_f32_e32 v16, v16, v31
	v_mul_f32_e32 v17, v17, v30
	v_mul_f32_e32 v18, v18, v33
	v_mul_f32_e32 v19, v19, v32
	v_cvt_pk_bf16_f32 v32, v12, v13
	v_cvt_pk_bf16_f32 v33, v14, v15
	v_cvt_pk_bf16_f32 v34, v16, v17
	v_cvt_pk_bf16_f32 v35, v18, v19
	ds_read_b128 v[186:189], v92
	ds_read_b128 v[190:193], v92 offset:4352
	ds_read_b128 v[194:197], v92 offset:8704
	ds_read_b128 v[198:201], v92 offset:13056
	ds_read_b128 v[202:205], v92 offset:17408
	ds_read_b128 v[206:209], v92 offset:21760
	ds_read_b128 v[210:213], v92 offset:26112
	s_nop 0
	ds_read_b128 v[16:19], v92 offset:64
	s_nop 0
	ds_read_b128 v[24:27], v92 offset:4416
	s_nop 0
	ds_read_b128 v[40:43], v92 offset:8768
	s_nop 0
	ds_read_b128 v[48:51], v92 offset:13120
	s_nop 0
	ds_read_b128 v[56:59], v92 offset:17472
	s_nop 0
	ds_read_b128 v[64:67], v92 offset:21824
	s_nop 0
	ds_read_b128 v[72:75], v92 offset:26176
	ds_read_b128 v[76:79], v92 offset:30464
	ds_read_b128 v[88:91], v92 offset:30528
	ds_read_b128 v[100:103], v92 offset:34816
	ds_read_b128 v[104:107], v92 offset:34880
	ds_read_b128 v[108:111], v92 offset:39168
	ds_read_b128 v[112:115], v92 offset:39232
	ds_read_b128 v[116:119], v92 offset:43520
	ds_read_b128 v[120:123], v92 offset:43584
	ds_read_b128 v[124:127], v92 offset:47872
	ds_read_b128 v[128:131], v92 offset:47936
	ds_read_b128 v[132:135], v92 offset:52224
	ds_read_b128 v[136:139], v92 offset:52288
	ds_read_b128 v[140:143], v92 offset:56576
	ds_read_b128 v[144:147], v92 offset:56640
	ds_read_b128 v[148:151], v92 offset:60928
	ds_read_b128 v[152:155], v92 offset:60992
	ds_read_b128 v[156:159], v92 offset:65280
	ds_read_b128 v[160:163], v92 offset:65344
	s_waitcnt lgkmcnt(14)
	v_mfma_f32_16x16x32_bf16 v[12:15], v[186:189], v[0:3], 0
	v_mfma_f32_16x16x32_bf16 v[20:23], v[190:193], v[0:3], 0
	v_mfma_f32_16x16x32_bf16 v[28:31], v[194:197], v[0:3], 0
	v_mfma_f32_16x16x32_bf16 v[44:47], v[198:201], v[0:3], 0
	v_mfma_f32_16x16x32_bf16 v[52:55], v[202:205], v[0:3], 0
	v_mfma_f32_16x16x32_bf16 v[60:63], v[206:209], v[0:3], 0
	v_mfma_f32_16x16x32_bf16 v[68:71], v[210:213], v[0:3], 0
	v_mfma_f32_16x16x32_bf16 v[76:79], v[76:79], v[0:3], 0
	v_mfma_f32_16x16x32_bf16 v[100:103], v[100:103], v[0:3], 0
	s_waitcnt lgkmcnt(13)
	v_mfma_f32_16x16x32_bf16 v[108:111], v[108:111], v[0:3], 0
	s_waitcnt lgkmcnt(11)
	v_mfma_f32_16x16x32_bf16 v[116:119], v[116:119], v[0:3], 0
	s_waitcnt lgkmcnt(9)
	v_mfma_f32_16x16x32_bf16 v[124:127], v[124:127], v[0:3], 0
	s_waitcnt lgkmcnt(7)
	v_mfma_f32_16x16x32_bf16 v[132:135], v[132:135], v[0:3], 0
	s_waitcnt lgkmcnt(5)
	v_mfma_f32_16x16x32_bf16 v[140:143], v[140:143], v[0:3], 0
	s_waitcnt lgkmcnt(3)
	v_mfma_f32_16x16x32_bf16 v[148:151], v[148:151], v[0:3], 0
	s_waitcnt lgkmcnt(1)
	v_mfma_f32_16x16x32_bf16 v[0:3], v[156:159], v[0:3], 0
	v_mfma_f32_16x16x32_bf16 v[12:15], v[16:19], v[8:11], v[12:15]
	v_mfma_f32_16x16x32_bf16 v[16:19], v[24:27], v[8:11], v[20:23]
	v_mfma_f32_16x16x32_bf16 v[20:23], v[40:43], v[8:11], v[28:31]
	v_mfma_f32_16x16x32_bf16 v[24:27], v[48:51], v[8:11], v[44:47]
	v_mfma_f32_16x16x32_bf16 v[28:31], v[56:59], v[8:11], v[52:55]
	ds_read_b128 v[198:201], v92 offset:128
	ds_read_b128 v[202:205], v92 offset:4480
	ds_read_b128 v[206:209], v92 offset:8832
	ds_read_b128 v[210:213], v92 offset:13184
	v_mfma_f32_16x16x32_bf16 v[40:43], v[64:67], v[8:11], v[60:63]
	v_mfma_f32_16x16x32_bf16 v[44:47], v[72:75], v[8:11], v[68:71]
	v_mfma_f32_16x16x32_bf16 v[48:51], v[88:91], v[8:11], v[76:79]
	v_mfma_f32_16x16x32_bf16 v[52:55], v[104:107], v[8:11], v[100:103]
	v_mfma_f32_16x16x32_bf16 v[56:59], v[112:115], v[8:11], v[108:111]
	v_mfma_f32_16x16x32_bf16 v[60:63], v[120:123], v[8:11], v[116:119]
	v_mfma_f32_16x16x32_bf16 v[64:67], v[128:131], v[8:11], v[124:127]
	ds_read_b128 v[218:221], v92 offset:17536
	ds_read_b128 v[222:225], v92 offset:21888
	ds_read_b128 v[226:229], v92 offset:26240
	ds_read_b128 v[230:233], v92 offset:30592
	ds_read_b128 v[234:237], v92 offset:34944
	ds_read_b128 v[242:245], v92 offset:39296
	ds_read_b128 v[246:249], v92 offset:43648
	v_mfma_f32_16x16x32_bf16 v[68:71], v[136:139], v[8:11], v[132:135]
	v_mfma_f32_16x16x32_bf16 v[72:75], v[144:147], v[8:11], v[140:143]
	v_mfma_f32_16x16x32_bf16 v[76:79], v[152:155], v[8:11], v[148:151]
	s_waitcnt lgkmcnt(11)
	v_mfma_f32_16x16x32_bf16 v[0:3], v[160:163], v[8:11], v[0:3]
	s_nop 0
	ds_read_b128 v[88:91], v92 offset:192
	s_waitcnt lgkmcnt(11)
	v_mfma_f32_16x16x32_bf16 v[8:11], v[198:201], v[4:7], v[12:15]
	s_nop 2
	s_nop 0
	ds_read_b128 v[100:103], v92 offset:4544
	s_waitcnt lgkmcnt(11)
	v_mfma_f32_16x16x32_bf16 v[12:15], v[202:205], v[4:7], v[16:19]
	s_nop 2
	s_nop 0
	ds_read_b128 v[104:107], v92 offset:8896
	s_waitcnt lgkmcnt(11)
	v_mfma_f32_16x16x32_bf16 v[16:19], v[206:209], v[4:7], v[20:23]
	s_nop 2
	s_nop 0
	ds_read_b128 v[108:111], v92 offset:13248
	s_waitcnt lgkmcnt(11)
	v_mfma_f32_16x16x32_bf16 v[20:23], v[210:213], v[4:7], v[24:27]
	s_nop 2
	s_nop 0
	ds_read_b128 v[112:115], v92 offset:17600
	s_waitcnt lgkmcnt(11)
	ds_read_b128 v[186:189], v92 offset:48000
	ds_read_b128 v[190:193], v92 offset:52352
	ds_read_b128 v[194:197], v92 offset:56704
	ds_read_b128 v[198:201], v92 offset:61056
	ds_read_b128 v[202:205], v92 offset:65408
	v_mfma_f32_16x16x32_bf16 v[24:27], v[218:221], v[4:7], v[28:31]
	s_nop 2
	s_nop 0
	ds_read_b128 v[116:119], v92 offset:21952
	s_waitcnt lgkmcnt(15)
; #define LAS __attribute__((address_space(3)))
; template <bool SAMPLE>
; __device__ __forceinline__ void mem_unit(const Params& p, int l, LAS unsigned char* lds, int unit, int tid, int wave, int lane) {
;     ...
;         f32x4 S[8][2]; float mx = -INFINITY;
; #pragma unroll
;         for (int cc = 0; cc < 8; ++cc)
; #pragma unroll
;             for (int tt = 0; tt < 2; ++tt) { const int kb = 32 * cc + 16 * tt; f32x4 a = (f32x4){0.f, 0.f, 0.f, 0.f};
; #pragma unroll
;                 for (int dc = 0; dc < 4; ++dc) { const bf16x8 kf = *(const LAS bf16x8*)(Kl + (kb + q16) * MEM_KS + 32 * dc + 8 * kq);
;                     a = __builtin_amdgcn_mfma_f32_16x16x32_bf16(kf, qf[dc], a, 0, 0, 0); }
; #pragma unroll
;                 for (int e = 0; e < 4; ++e) mx = fmaxf(mx, a[e]);
;                 S[cc][tt] = a; }
;         mx = fmaxf(mx, __shfl_xor(mx, 16)); mx = fmaxf(mx, __shfl_xor(mx, 32));
;         float den = 0.f;
; #pragma unroll
;         for (int cc = 0; cc < 8; ++cc)
; #pragma unroll
;             for (int tt = 0; tt < 2; ++tt)
; #pragma unroll
;                 for (int e = 0; e < 4; ++e) { const float pe = __expf(S[cc][tt][e] - mx); S[cc][tt][e] = pe; den += pe; }
	v_mfma_f32_16x16x32_bf16 v[28:31], v[222:225], v[4:7], v[40:43]
	s_nop 2
	s_nop 0
	ds_read_b128 v[120:123], v92 offset:26304
	s_waitcnt lgkmcnt(15)
	v_mfma_f32_16x16x32_bf16 v[40:43], v[226:229], v[4:7], v[44:47]
	s_nop 2
	s_nop 0
	ds_read_b128 v[124:127], v92 offset:30656
	s_waitcnt lgkmcnt(15)
	v_mfma_f32_16x16x32_bf16 v[44:47], v[230:233], v[4:7], v[48:51]
	s_nop 2
	s_nop 0
	ds_read_b128 v[128:131], v92 offset:35008
	s_waitcnt lgkmcnt(15)
	v_mfma_f32_16x16x32_bf16 v[48:51], v[234:237], v[4:7], v[52:55]
	s_nop 2
	s_nop 0
	ds_read_b128 v[132:135], v92 offset:39360
	s_waitcnt lgkmcnt(15)
	v_mfma_f32_16x16x32_bf16 v[52:55], v[242:245], v[4:7], v[56:59]
	s_nop 2
	s_nop 0
	ds_read_b128 v[136:139], v92 offset:43712
	s_waitcnt lgkmcnt(15)
	v_mfma_f32_16x16x32_bf16 v[56:59], v[246:249], v[4:7], v[60:63]
	s_nop 2
	s_nop 0
	ds_read_b128 v[140:143], v92 offset:48064
	s_waitcnt lgkmcnt(11)
	v_mfma_f32_16x16x32_bf16 v[60:63], v[186:189], v[4:7], v[64:67]
	s_nop 2
	s_nop 0
	ds_read_b128 v[144:147], v92 offset:52416
	s_waitcnt lgkmcnt(11)
	v_mfma_f32_16x16x32_bf16 v[64:67], v[190:193], v[4:7], v[68:71]
	s_nop 2
	s_nop 0
	ds_read_b128 v[148:151], v92 offset:56768
	s_waitcnt lgkmcnt(11)
	v_mfma_f32_16x16x32_bf16 v[68:71], v[194:197], v[4:7], v[72:75]
	s_nop 2
	s_nop 0
	ds_read_b128 v[152:155], v92 offset:61120
	s_waitcnt lgkmcnt(11)
	v_mfma_f32_16x16x32_bf16 v[72:75], v[198:201], v[4:7], v[76:79]
	s_nop 2
	s_nop 0
	ds_read_b128 v[156:159], v92 offset:65472
	s_waitcnt lgkmcnt(11)
	v_mfma_f32_16x16x32_bf16 v[0:3], v[202:205], v[4:7], v[0:3]
	v_mfma_f32_16x16x32_bf16 v[76:79], v[88:91], v[32:35], v[8:11]
	v_mfma_f32_16x16x32_bf16 v[88:91], v[100:103], v[32:35], v[12:15]
	v_mfma_f32_16x16x32_bf16 v[100:103], v[104:107], v[32:35], v[16:19]
	v_mfma_f32_16x16x32_bf16 v[104:107], v[108:111], v[32:35], v[20:23]
	v_mfma_f32_16x16x32_bf16 v[108:111], v[112:115], v[32:35], v[24:27]
	v_mfma_f32_16x16x32_bf16 v[112:115], v[116:119], v[32:35], v[28:31]
	v_mfma_f32_16x16x32_bf16 v[40:43], v[120:123], v[32:35], v[40:43]
	v_mfma_f32_16x16x32_bf16 v[44:47], v[124:127], v[32:35], v[44:47]
	v_mfma_f32_16x16x32_bf16 v[28:31], v[128:131], v[32:35], v[48:51]
	v_mfma_f32_16x16x32_bf16 v[24:27], v[132:135], v[32:35], v[52:55]
	v_mfma_f32_16x16x32_bf16 v[20:23], v[136:139], v[32:35], v[56:59]
	v_mfma_f32_16x16x32_bf16 v[16:19], v[140:143], v[32:35], v[60:63]
	v_mfma_f32_16x16x32_bf16 v[12:15], v[144:147], v[32:35], v[64:67]
	v_mfma_f32_16x16x32_bf16 v[8:11], v[148:151], v[32:35], v[68:71]
	v_mfma_f32_16x16x32_bf16 v[4:7], v[152:155], v[32:35], v[72:75]
	s_waitcnt lgkmcnt(0)
	v_mfma_f32_16x16x32_bf16 v[0:3], v[156:159], v[32:35], v[0:3]
	v_max3_f32 v32, v76, s33, v77
	v_max3_f32 v32, v32, v78, v79
	v_max3_f32 v32, v32, v88, v89
	v_max3_f32 v32, v32, v90, v91
	v_max3_f32 v32, v32, v100, v101
	v_max3_f32 v32, v32, v102, v103
	v_max3_f32 v32, v32, v104, v105
	v_max3_f32 v32, v32, v106, v107
	v_max3_f32 v32, v32, v108, v109
	v_max3_f32 v32, v32, v110, v111
	v_max3_f32 v32, v32, v112, v113
	v_max3_f32 v32, v32, v114, v115
	v_max3_f32 v32, v32, v40, v41
	v_max3_f32 v32, v32, v42, v43
	v_max3_f32 v32, v32, v44, v45
	v_max3_f32 v32, v32, v46, v47
	v_max3_f32 v32, v32, v28, v29
	v_max3_f32 v32, v32, v30, v31
	v_max3_f32 v32, v32, v24, v25
	v_max3_f32 v32, v32, v26, v27
	v_max3_f32 v32, v32, v20, v21
	v_max3_f32 v32, v32, v22, v23
	v_max3_f32 v32, v32, v16, v17
	v_max3_f32 v32, v32, v18, v19
	v_max3_f32 v32, v32, v12, v13
	v_max3_f32 v32, v32, v14, v15
	v_max3_f32 v32, v32, v8, v9
	v_max3_f32 v32, v32, v10, v11
	v_max3_f32 v32, v32, v4, v5
	v_max3_f32 v32, v32, v6, v7
	v_max3_f32 v32, v32, v0, v1
	v_max3_f32 v32, v32, v2, v3
	ds_bpermute_b32 v33, v38, v32
	s_waitcnt lgkmcnt(0)
	v_max_f32_e32 v33, v33, v33
	v_max_f32_e32 v32, v32, v33
	ds_bpermute_b32 v33, v39, v32
	s_waitcnt lgkmcnt(0)
	v_max_f32_e32 v33, v33, v33
	v_max_f32_e32 v32, v32, v33
	v_sub_f32_e32 v33, v76, v32
	v_sub_f32_e32 v34, v77, v32
	v_mul_f32_e32 v33, 0x3fb8aa3b, v33
	v_sub_f32_e32 v35, v78, v32
	v_mul_f32_e32 v34, 0x3fb8aa3b, v34
	v_exp_f32_e32 v33, v33
	v_sub_f32_e32 v48, v79, v32
	v_mul_f32_e32 v35, 0x3fb8aa3b, v35
	v_exp_f32_e32 v34, v34
	v_sub_f32_e32 v49, v88, v32
	v_mul_f32_e32 v48, 0x3fb8aa3b, v48
	v_exp_f32_e32 v35, v35
	v_sub_f32_e32 v50, v89, v32
	v_mul_f32_e32 v49, 0x3fb8aa3b, v49
	v_exp_f32_e32 v48, v48
	v_sub_f32_e32 v51, v90, v32
	v_mul_f32_e32 v50, 0x3fb8aa3b, v50
	v_exp_f32_e32 v49, v49
	v_add_f32_e32 v69, 0, v33
	v_sub_f32_e32 v52, v91, v32
	v_mul_f32_e32 v51, 0x3fb8aa3b, v51
	v_exp_f32_e32 v50, v50
	v_add_f32_e32 v69, v34, v69
	v_sub_f32_e32 v53, v100, v32
	v_mul_f32_e32 v52, 0x3fb8aa3b, v52
	v_exp_f32_e32 v51, v51
	v_add_f32_e32 v69, v35, v69
	v_sub_f32_e32 v54, v101, v32
	v_mul_f32_e32 v53, 0x3fb8aa3b, v53
	v_exp_f32_e32 v52, v52
	v_add_f32_e32 v69, v48, v69
	v_sub_f32_e32 v55, v102, v32
	v_mul_f32_e32 v54, 0x3fb8aa3b, v54
	v_exp_f32_e32 v53, v53
	v_add_f32_e32 v69, v49, v69
	v_sub_f32_e32 v56, v103, v32
	v_mul_f32_e32 v55, 0x3fb8aa3b, v55
	v_exp_f32_e32 v54, v54
	v_add_f32_e32 v69, v50, v69
	v_sub_f32_e32 v57, v104, v32
	v_mul_f32_e32 v56, 0x3fb8aa3b, v56
	v_exp_f32_e32 v55, v55
	v_add_f32_e32 v69, v51, v69
	v_sub_f32_e32 v58, v105, v32
	v_mul_f32_e32 v57, 0x3fb8aa3b, v57
	v_exp_f32_e32 v56, v56
	v_add_f32_e32 v69, v52, v69
	v_sub_f32_e32 v59, v106, v32
	v_mul_f32_e32 v58, 0x3fb8aa3b, v58
	v_exp_f32_e32 v57, v57
	v_add_f32_e32 v69, v53, v69
	v_sub_f32_e32 v60, v107, v32
	v_mul_f32_e32 v59, 0x3fb8aa3b, v59
	v_exp_f32_e32 v58, v58
	v_add_f32_e32 v69, v54, v69
	v_sub_f32_e32 v61, v108, v32
	v_mul_f32_e32 v60, 0x3fb8aa3b, v60
	v_exp_f32_e32 v59, v59
	v_add_f32_e32 v69, v55, v69
	v_sub_f32_e32 v62, v109, v32
; __device__ __forceinline__ bf16x8 pack8(const float (&o)[8]) { v4u w; w.x = pk2(o[0], o[1]); w.y = pk2(o[2], o[3]); w.z = pk2(o[4], o[5]); w.w = pk2(o[6], o[7]); return __builtin_bit_cast(bf16x8, w); }
; template <bool SAMPLE>
; __device__ __forceinline__ void mem_unit(const Params& p, int l, LAS unsigned char* lds, int unit, int tid, int wave, int lane) {
;     ...
;         float den = 0.f;
; #pragma unroll
;         for (int cc = 0; cc < 8; ++cc)
; #pragma unroll
;             for (int tt = 0; tt < 2; ++tt)
; #pragma unroll
;                 for (int e = 0; e < 4; ++e) { const float pe = __expf(S[cc][tt][e] - mx); S[cc][tt][e] = pe; den += pe; }
;         den += __shfl_xor(den, 16); den += __shfl_xor(den, 32);
;         const float rden = 1.f / den;
;         bf16x8 pf[8];
; #pragma unroll
;         for (int cc = 0; cc < 8; ++cc) { float t8[8];
; #pragma unroll
;             for (int e = 0; e < 4; ++e) { t8[e] = S[cc][0][e]; t8[4 + e] = S[cc][1][e]; }
;             pf[cc] = pack8(t8); }
	v_mul_f32_e32 v61, 0x3fb8aa3b, v61
	v_exp_f32_e32 v60, v60
	v_add_f32_e32 v69, v56, v69
	v_sub_f32_e32 v63, v110, v32
	v_mul_f32_e32 v62, 0x3fb8aa3b, v62
	v_exp_f32_e32 v61, v61
	v_add_f32_e32 v69, v57, v69
	v_sub_f32_e32 v64, v111, v32
	v_mul_f32_e32 v63, 0x3fb8aa3b, v63
	v_exp_f32_e32 v62, v62
	v_add_f32_e32 v69, v58, v69
	v_sub_f32_e32 v65, v112, v32
	v_mul_f32_e32 v64, 0x3fb8aa3b, v64
	v_exp_f32_e32 v63, v63
	v_add_f32_e32 v69, v59, v69
	v_sub_f32_e32 v66, v113, v32
	v_mul_f32_e32 v65, 0x3fb8aa3b, v65
	v_exp_f32_e32 v64, v64
	v_add_f32_e32 v69, v60, v69
	v_sub_f32_e32 v67, v114, v32
	v_mul_f32_e32 v66, 0x3fb8aa3b, v66
	v_exp_f32_e32 v65, v65
	v_add_f32_e32 v69, v61, v69
	v_sub_f32_e32 v68, v115, v32
	v_mul_f32_e32 v67, 0x3fb8aa3b, v67
	v_exp_f32_e32 v66, v66
	v_add_f32_e32 v69, v62, v69
	v_sub_f32_e32 v40, v40, v32
	v_mul_f32_e32 v68, 0x3fb8aa3b, v68
	v_exp_f32_e32 v67, v67
	v_add_f32_e32 v69, v63, v69
	v_sub_f32_e32 v41, v41, v32
	v_mul_f32_e32 v40, 0x3fb8aa3b, v40
	v_exp_f32_e32 v68, v68
	v_add_f32_e32 v69, v64, v69
	v_sub_f32_e32 v42, v42, v32
	v_mul_f32_e32 v41, 0x3fb8aa3b, v41
	v_exp_f32_e32 v40, v40
	v_add_f32_e32 v69, v65, v69
	v_sub_f32_e32 v43, v43, v32
	v_mul_f32_e32 v42, 0x3fb8aa3b, v42
	v_exp_f32_e32 v41, v41
	v_add_f32_e32 v69, v66, v69
	v_sub_f32_e32 v44, v44, v32
	v_mul_f32_e32 v43, 0x3fb8aa3b, v43
	v_exp_f32_e32 v42, v42
	v_add_f32_e32 v69, v67, v69
	v_sub_f32_e32 v45, v45, v32
	v_mul_f32_e32 v44, 0x3fb8aa3b, v44
	v_exp_f32_e32 v43, v43
	v_add_f32_e32 v69, v68, v69
	v_sub_f32_e32 v46, v46, v32
	v_mul_f32_e32 v45, 0x3fb8aa3b, v45
	v_exp_f32_e32 v44, v44
	v_add_f32_e32 v69, v40, v69
	v_sub_f32_e32 v47, v47, v32
	v_mul_f32_e32 v46, 0x3fb8aa3b, v46
	v_exp_f32_e32 v45, v45
	v_add_f32_e32 v69, v41, v69
	v_sub_f32_e32 v28, v28, v32
	v_mul_f32_e32 v47, 0x3fb8aa3b, v47
	v_exp_f32_e32 v46, v46
	v_add_f32_e32 v69, v42, v69
	v_sub_f32_e32 v29, v29, v32
	v_mul_f32_e32 v28, 0x3fb8aa3b, v28
	v_exp_f32_e32 v47, v47
	v_add_f32_e32 v69, v43, v69
	v_exp_f32_e32 v28, v28
	v_add_f32_e32 v69, v44, v69
	v_mul_f32_e32 v29, 0x3fb8aa3b, v29
	v_sub_f32_e32 v30, v30, v32
	v_sub_f32_e32 v24, v24, v32
	v_add_f32_e32 v69, v45, v69
	v_exp_f32_e32 v29, v29
	v_mul_f32_e32 v30, 0x3fb8aa3b, v30
	v_sub_f32_e32 v31, v31, v32
	v_mul_f32_e32 v24, 0x3fb8aa3b, v24
	v_add_f32_e32 v69, v46, v69
	v_exp_f32_e32 v30, v30
	v_mul_f32_e32 v31, 0x3fb8aa3b, v31
	v_exp_f32_e32 v70, v24
	v_sub_f32_e32 v24, v25, v32
	v_add_f32_e32 v69, v47, v69
	v_exp_f32_e32 v31, v31
	v_mul_f32_e32 v24, 0x3fb8aa3b, v24
	v_add_f32_e32 v69, v28, v69
	v_exp_f32_e32 v71, v24
	v_sub_f32_e32 v24, v26, v32
	v_add_f32_e32 v69, v29, v69
	v_mul_f32_e32 v24, 0x3fb8aa3b, v24
	v_add_f32_e32 v69, v30, v69
	v_exp_f32_e32 v72, v24
	v_sub_f32_e32 v24, v27, v32
	v_sub_f32_e32 v20, v20, v32
	v_add_f32_e32 v69, v31, v69
	v_mul_f32_e32 v24, 0x3fb8aa3b, v24
	v_mul_f32_e32 v20, 0x3fb8aa3b, v20
	v_exp_f32_e32 v73, v24
	v_add_f32_e32 v24, v70, v69
	v_exp_f32_e32 v69, v20
	v_sub_f32_e32 v20, v21, v32
	v_mul_f32_e32 v20, 0x3fb8aa3b, v20
	v_exp_f32_e32 v74, v20
	v_sub_f32_e32 v20, v22, v32
	v_sub_f32_e32 v16, v16, v32
	v_mul_f32_e32 v20, 0x3fb8aa3b, v20
	v_mul_f32_e32 v16, 0x3fb8aa3b, v16
	v_add_f32_e32 v24, v71, v24
	v_exp_f32_e32 v75, v20
	v_sub_f32_e32 v20, v23, v32
	v_exp_f32_e32 v77, v16
	v_sub_f32_e32 v16, v17, v32
	v_add_f32_e32 v24, v72, v24
	v_mul_f32_e32 v20, 0x3fb8aa3b, v20
	v_mul_f32_e32 v16, 0x3fb8aa3b, v16
	v_add_f32_e32 v24, v73, v24
	v_exp_f32_e32 v76, v20
	v_exp_f32_e32 v78, v16
	v_sub_f32_e32 v16, v18, v32
	v_sub_f32_e32 v12, v12, v32
	v_add_f32_e32 v20, v69, v24
	v_mul_f32_e32 v16, 0x3fb8aa3b, v16
	v_mul_f32_e32 v12, 0x3fb8aa3b, v12
	v_add_f32_e32 v20, v74, v20
	v_exp_f32_e32 v79, v16
	v_sub_f32_e32 v16, v19, v32
	v_exp_f32_e32 v89, v12
	v_sub_f32_e32 v12, v13, v32
	v_add_f32_e32 v20, v75, v20
	v_mul_f32_e32 v16, 0x3fb8aa3b, v16
	v_mul_f32_e32 v12, 0x3fb8aa3b, v12
	v_add_f32_e32 v20, v76, v20
	v_exp_f32_e32 v88, v16
	v_exp_f32_e32 v90, v12
	v_sub_f32_e32 v12, v14, v32
	v_sub_f32_e32 v8, v8, v32
	v_add_f32_e32 v16, v77, v20
	v_mul_f32_e32 v12, 0x3fb8aa3b, v12
	v_mul_f32_e32 v8, 0x3fb8aa3b, v8
	v_add_f32_e32 v16, v78, v16
	v_exp_f32_e32 v91, v12
	v_sub_f32_e32 v12, v15, v32
	v_exp_f32_e32 v93, v8
	v_sub_f32_e32 v8, v9, v32
	v_add_f32_e32 v16, v79, v16
	v_mul_f32_e32 v12, 0x3fb8aa3b, v12
	v_mul_f32_e32 v8, 0x3fb8aa3b, v8
	v_add_f32_e32 v16, v88, v16
	v_exp_f32_e32 v92, v12
	v_exp_f32_e32 v100, v8
	v_sub_f32_e32 v8, v10, v32
	v_sub_f32_e32 v4, v4, v32
	v_add_f32_e32 v12, v89, v16
	v_mul_f32_e32 v8, 0x3fb8aa3b, v8
	v_mul_f32_e32 v4, 0x3fb8aa3b, v4
	v_add_f32_e32 v12, v90, v12
	v_exp_f32_e32 v101, v8
	v_sub_f32_e32 v8, v11, v32
	v_exp_f32_e32 v103, v4
	v_sub_f32_e32 v4, v5, v32
	v_add_f32_e32 v12, v91, v12
	v_mul_f32_e32 v8, 0x3fb8aa3b, v8
	v_mul_f32_e32 v4, 0x3fb8aa3b, v4
	v_add_f32_e32 v12, v92, v12
	v_exp_f32_e32 v102, v8
	v_exp_f32_e32 v104, v4
	v_sub_f32_e32 v4, v6, v32
	v_sub_f32_e32 v0, v0, v32
	v_add_f32_e32 v8, v93, v12
	v_mul_f32_e32 v4, 0x3fb8aa3b, v4
	v_mul_f32_e32 v0, 0x3fb8aa3b, v0
	v_add_f32_e32 v8, v100, v8
	v_exp_f32_e32 v105, v4
	v_sub_f32_e32 v4, v7, v32
	v_exp_f32_e32 v107, v0
	v_sub_f32_e32 v0, v1, v32
	v_add_f32_e32 v8, v101, v8
	v_mul_f32_e32 v4, 0x3fb8aa3b, v4
	v_mul_f32_e32 v0, 0x3fb8aa3b, v0
	v_add_f32_e32 v8, v102, v8
	v_exp_f32_e32 v106, v4
	v_exp_f32_e32 v108, v0
	v_sub_f32_e32 v0, v2, v32
	v_add_f32_e32 v4, v103, v8
	v_mul_f32_e32 v0, 0x3fb8aa3b, v0
	v_add_f32_e32 v4, v104, v4
	v_exp_f32_e32 v109, v0
	v_sub_f32_e32 v0, v3, v32
	v_add_f32_e32 v4, v105, v4
	v_mul_f32_e32 v0, 0x3fb8aa3b, v0
	v_add_f32_e32 v4, v106, v4
	v_exp_f32_e32 v32, v0
	v_add_f32_e32 v0, v107, v4
	v_add_f32_e32 v0, v108, v0
	v_add_f32_e32 v0, v109, v0
	v_add_f32_e32 v0, v32, v0
	ds_bpermute_b32 v1, v38, v0
	v_cvt_pk_bf16_f32 v24, v33, v34
	v_cvt_pk_bf16_f32 v25, v35, v48
	v_cvt_pk_bf16_f32 v26, v49, v50
	v_cvt_pk_bf16_f32 v27, v51, v52
	s_waitcnt lgkmcnt(0)
; #define LAS __attribute__((address_space(3)))
; __device__ __forceinline__ unsigned pk2(float lo, float hi) { return pg8::cvt_pk_bf16(lo, hi); }
; __device__ __forceinline__ bf16x8 pack8(const float (&o)[8]) { v4u w; w.x = pk2(o[0], o[1]); w.y = pk2(o[2], o[3]); w.z = pk2(o[4], o[5]); w.w = pk2(o[6], o[7]); return __builtin_bit_cast(bf16x8, w); }
; __device__ __forceinline__ v2u vtr(const LAS bf16* p) { return __builtin_bit_cast(v2u, __builtin_amdgcn_ds_read_tr16_b64_v4i16((LAS v4i16_t*)p)); }
; template <bool SAMPLE>
; __device__ __forceinline__ void mem_unit(const Params& p, int l, LAS unsigned char* lds, int unit, int tid, int wave, int lane) {
;     ...
;         den += __shfl_xor(den, 16); den += __shfl_xor(den, 32);
;         const float rden = 1.f / den;
;         bf16x8 pf[8];
; #pragma unroll
;         for (int cc = 0; cc < 8; ++cc) { float t8[8];
; #pragma unroll
;             for (int e = 0; e < 4; ++e) { t8[e] = S[cc][0][e]; t8[4 + e] = S[cc][1][e]; }
;             pf[cc] = pack8(t8); }
; #pragma unroll
;         for (int dt = 0; dt < 8; ++dt) { f32x4 o = (f32x4){0.f, 0.f, 0.f, 0.f};
; #pragma unroll
;             for (int cc = 0; cc < 8; ++cc) { const LAS bf16* vp = Vt + (32 * cc + 4 * kq + (q16 >> 2)) * MEM_VS + 16 * dt + 4 * (q16 & 3);
;                 const v2u lo = vtr(vp), hi = vtr(vp + 16 * MEM_VS);
;                 v4u av; av.x = lo.x; av.y = lo.y; av.z = hi.x; av.w = hi.y;
;                 o = __builtin_amdgcn_mfma_f32_16x16x32_bf16(__builtin_bit_cast(bf16x8, av), pf[cc], o, 0, 0, 0); }
;             if (st) { v2u w; w.x = pk2(o[0] * rden, o[1] * rden); w.y = pk2(o[2] * rden, o[3] * rden);
;                 *(v2u*)(MO + row * 512 + h * 128 + 16 * dt + 4 * kq) = w; } }
	v_add_f32_e32 v0, v0, v1
	ds_bpermute_b32 v1, v39, v0
	v_cvt_pk_bf16_f32 v20, v53, v54
	v_cvt_pk_bf16_f32 v21, v55, v56
	v_cvt_pk_bf16_f32 v22, v57, v58
	v_cvt_pk_bf16_f32 v23, v59, v60
	s_waitcnt lgkmcnt(0)
	v_add_f32_e32 v39, v0, v1
	v_cvt_pk_bf16_f32 v16, v61, v62
	v_cvt_pk_bf16_f32 v17, v63, v64
	v_cvt_pk_bf16_f32 v18, v65, v66
	v_cvt_pk_bf16_f32 v19, v67, v68
	v_cvt_pk_bf16_f32 v12, v40, v41
	v_cvt_pk_bf16_f32 v13, v42, v43
	v_cvt_pk_bf16_f32 v14, v44, v45
	v_cvt_pk_bf16_f32 v15, v46, v47
	v_cvt_pk_bf16_f32 v8, v28, v29
	v_cvt_pk_bf16_f32 v9, v30, v31
	v_cvt_pk_bf16_f32 v10, v70, v71
	v_cvt_pk_bf16_f32 v11, v72, v73
	v_cvt_pk_bf16_f32 v4, v69, v74
	v_cvt_pk_bf16_f32 v5, v75, v76
	v_cvt_pk_bf16_f32 v6, v77, v78
	v_cvt_pk_bf16_f32 v7, v79, v88
	v_cvt_pk_bf16_f32 v0, v89, v90
	v_cvt_pk_bf16_f32 v1, v91, v92
	v_cvt_pk_bf16_f32 v2, v93, v100
	v_cvt_pk_bf16_f32 v3, v101, v102
	v_cvt_pk_bf16_f32 v28, v103, v104
	v_cvt_pk_bf16_f32 v29, v105, v106
	v_cvt_pk_bf16_f32 v30, v107, v108
	v_cvt_pk_bf16_f32 v31, v109, v32
	v_lshlrev_b32_e32 v52, 2, v37
	v_lshrrev_b32_e32 v32, 2, v36
	v_add_u32_e32 v32, v32, v52
	v_lshlrev_b32_e32 v33, 3, v36
	v_and_b32_e32 v33, 24, v33
	v_mul_lo_u32 v32, v32, s30
	v_add3_u32 v38, s90, v33, v32
	ds_read_b64_tr_b16 v[32:33], v38
	ds_read_b64_tr_b16 v[34:35], v38 offset:4352
	ds_read_b64_tr_b16 v[40:41], v38 offset:8704
	ds_read_b64_tr_b16 v[42:43], v38 offset:13056
	s_waitcnt lgkmcnt(2)
	v_mfma_f32_16x16x32_bf16 v[32:35], v[32:35], v[24:27], 0
	ds_read_b64_tr_b16 v[44:45], v38 offset:17408
	ds_read_b64_tr_b16 v[46:47], v38 offset:21760
	ds_read_b64_tr_b16 v[48:49], v38 offset:26112
	ds_read_b64_tr_b16 v[50:51], v38 offset:30464
	v_div_scale_f32 v53, s[2:3], v39, v39, 1.0
	s_waitcnt lgkmcnt(4)
	v_mfma_f32_16x16x32_bf16 v[32:35], v[40:43], v[20:23], v[32:35]
	ds_read_b64_tr_b16 v[40:41], v38 offset:34816
	ds_read_b64_tr_b16 v[42:43], v38 offset:39168
	v_rcp_f32_e32 v37, v53
	s_add_u32 s2, s28, s0
	s_waitcnt lgkmcnt(4)
	v_mfma_f32_16x16x32_bf16 v[32:35], v[44:47], v[16:19], v[32:35]
	ds_read_b64_tr_b16 v[44:45], v38 offset:43520
	ds_read_b64_tr_b16 v[46:47], v38 offset:47872
	v_cmp_gt_i32_e64 s[0:1], 8, v36
	v_fma_f32 v36, -v53, v37, 1.0
	s_waitcnt lgkmcnt(4)
	v_mfma_f32_16x16x32_bf16 v[32:35], v[48:51], v[12:15], v[32:35]
	ds_read_b64_tr_b16 v[48:49], v38 offset:52224
	ds_read_b64_tr_b16 v[50:51], v38 offset:56576
	v_fmac_f32_e32 v37, v36, v37
	v_div_scale_f32 v36, vcc, 1.0, v39, 1.0
	s_waitcnt lgkmcnt(4)
	v_mfma_f32_16x16x32_bf16 v[32:35], v[40:43], v[8:11], v[32:35]
	ds_read_b64_tr_b16 v[40:41], v38 offset:60928
	ds_read_b64_tr_b16 v[42:43], v38 offset:65280
	v_mul_f32_e32 v54, v36, v37
	v_fma_f32 v55, -v53, v54, v36
	s_waitcnt lgkmcnt(4)
	v_mfma_f32_16x16x32_bf16 v[32:35], v[44:47], v[4:7], v[32:35]
	v_fmac_f32_e32 v54, v55, v37
	v_fma_f32 v36, -v53, v54, v36
	s_addc_u32 s3, s29, 0
	s_waitcnt lgkmcnt(2)
	v_mfma_f32_16x16x32_bf16 v[32:35], v[48:51], v[0:3], v[32:35]
	v_div_fmas_f32 v36, v36, v37, v54
	v_div_fixup_f32 v39, v36, v39, 1.0
	v_lshl_add_u64 v[36:37], s[2:3], 0, v[82:83]
	s_waitcnt lgkmcnt(0)
	v_mfma_f32_16x16x32_bf16 v[32:35], v[40:43], v[28:31], v[32:35]
	v_ashrrev_i32_e32 v53, 31, v52
	v_lshl_add_u64 v[36:37], v[52:53], 1, v[36:37]
	s_and_saveexec_b64 s[2:3], s[0:1]
	s_cbranch_execz .LBB0_603
	s_nop 3
	v_mul_f32_e32 v32, v32, v39
	v_mul_f32_e32 v33, v33, v39
	v_cvt_pk_bf16_f32 v32, v32, v33
	v_mul_f32_e32 v33, v34, v39
	v_mul_f32_e32 v34, v35, v39
	v_cvt_pk_bf16_f32 v33, v33, v34
	global_store_dwordx2 v[36:37], v[32:33], off
.LBB0_603:
	s_or_b64 exec, exec, s[2:3]
	s_nop 2
	ds_read_b64_tr_b16 v[186:187], v38 offset:32
	ds_read_b64_tr_b16 v[188:189], v38 offset:4384
	ds_read_b64_tr_b16 v[190:191], v38 offset:8736
	ds_read_b64_tr_b16 v[192:193], v38 offset:13088
	ds_read_b64_tr_b16 v[194:195], v38 offset:17440
	ds_read_b64_tr_b16 v[196:197], v38 offset:21792
	ds_read_b64_tr_b16 v[198:199], v38 offset:26144
	ds_read_b64_tr_b16 v[200:201], v38 offset:30496
	ds_read_b64_tr_b16 v[202:203], v38 offset:34848
	ds_read_b64_tr_b16 v[204:205], v38 offset:39200
	ds_read_b64_tr_b16 v[206:207], v38 offset:43552
	ds_read_b64_tr_b16 v[208:209], v38 offset:47904
	s_nop 5
	s_waitcnt lgkmcnt(10)
	v_mfma_f32_16x16x32_bf16 v[32:35], v[186:189], v[24:27], 0
	s_waitcnt lgkmcnt(8)
	v_mfma_f32_16x16x32_bf16 v[32:35], v[190:193], v[20:23], v[32:35]
	s_nop 1
	s_waitcnt lgkmcnt(6)
	v_mfma_f32_16x16x32_bf16 v[32:35], v[194:197], v[16:19], v[32:35]
	s_nop 1
	s_waitcnt lgkmcnt(4)
	v_mfma_f32_16x16x32_bf16 v[32:35], v[198:201], v[12:15], v[32:35]
	s_nop 1
	s_waitcnt lgkmcnt(2)
	v_mfma_f32_16x16x32_bf16 v[32:35], v[202:205], v[8:11], v[32:35]
	ds_read_b64_tr_b16 v[44:45], v38 offset:52256
	ds_read_b64_tr_b16 v[46:47], v38 offset:56608
	s_waitcnt lgkmcnt(2)
	v_mfma_f32_16x16x32_bf16 v[32:35], v[206:209], v[4:7], v[32:35]
	ds_read_b64_tr_b16 v[40:41], v38 offset:60960
	ds_read_b64_tr_b16 v[42:43], v38 offset:65312
	s_waitcnt lgkmcnt(2)
	v_mfma_f32_16x16x32_bf16 v[32:35], v[44:47], v[0:3], v[32:35]
	s_waitcnt lgkmcnt(0)
	v_mfma_f32_16x16x32_bf16 v[32:35], v[40:43], v[28:31], v[32:35]
	s_and_saveexec_b64 s[2:3], s[0:1]
	s_cbranch_execz .LBB0_605
	s_nop 5
	v_mul_f32_e32 v32, v39, v32
	v_mul_f32_e32 v33, v39, v33
	v_cvt_pk_bf16_f32 v32, v32, v33
	v_mul_f32_e32 v33, v39, v34
	v_mul_f32_e32 v34, v39, v35
	v_cvt_pk_bf16_f32 v33, v33, v34
	global_store_dwordx2 v[36:37], v[32:33], off offset:32
; #define LAS __attribute__((address_space(3)))
; __device__ __forceinline__ unsigned pk2(float lo, float hi) { return pg8::cvt_pk_bf16(lo, hi); }
; __device__ __forceinline__ v2u vtr(const LAS bf16* p) { return __builtin_bit_cast(v2u, __builtin_amdgcn_ds_read_tr16_b64_v4i16((LAS v4i16_t*)p)); }
; template <bool SAMPLE>
; __device__ __forceinline__ void mem_unit(const Params& p, int l, LAS unsigned char* lds, int unit, int tid, int wave, int lane) {
;     ...
; #pragma unroll
;         for (int dt = 0; dt < 8; ++dt) { f32x4 o = (f32x4){0.f, 0.f, 0.f, 0.f};
; #pragma unroll
;             for (int cc = 0; cc < 8; ++cc) { const LAS bf16* vp = Vt + (32 * cc + 4 * kq + (q16 >> 2)) * MEM_VS + 16 * dt + 4 * (q16 & 3);
;                 const v2u lo = vtr(vp), hi = vtr(vp + 16 * MEM_VS);
;                 v4u av; av.x = lo.x; av.y = lo.y; av.z = hi.x; av.w = hi.y;
;                 o = __builtin_amdgcn_mfma_f32_16x16x32_bf16(__builtin_bit_cast(bf16x8, av), pf[cc], o, 0, 0, 0); }
;             if (st) { v2u w; w.x = pk2(o[0] * rden, o[1] * rden); w.y = pk2(o[2] * rden, o[3] * rden);
;                 *(v2u*)(MO + row * 512 + h * 128 + 16 * dt + 4 * kq) = w; } }
.LBB0_605:
	s_or_b64 exec, exec, s[2:3]
	s_nop 4
	ds_read_b64_tr_b16 v[186:187], v38 offset:64
	ds_read_b64_tr_b16 v[188:189], v38 offset:4416
	ds_read_b64_tr_b16 v[190:191], v38 offset:8768
	ds_read_b64_tr_b16 v[192:193], v38 offset:13120
	ds_read_b64_tr_b16 v[194:195], v38 offset:17472
	ds_read_b64_tr_b16 v[196:197], v38 offset:21824
	ds_read_b64_tr_b16 v[198:199], v38 offset:26176
	ds_read_b64_tr_b16 v[200:201], v38 offset:30528
	ds_read_b64_tr_b16 v[202:203], v38 offset:34880
	ds_read_b64_tr_b16 v[204:205], v38 offset:39232
	ds_read_b64_tr_b16 v[206:207], v38 offset:43584
	ds_read_b64_tr_b16 v[208:209], v38 offset:47936
	s_nop 5
	s_waitcnt lgkmcnt(10)
	v_mfma_f32_16x16x32_bf16 v[32:35], v[186:189], v[24:27], 0
	s_waitcnt lgkmcnt(8)
	v_mfma_f32_16x16x32_bf16 v[32:35], v[190:193], v[20:23], v[32:35]
	s_nop 1
	s_waitcnt lgkmcnt(6)
	v_mfma_f32_16x16x32_bf16 v[32:35], v[194:197], v[16:19], v[32:35]
	s_nop 1
	s_waitcnt lgkmcnt(4)
	v_mfma_f32_16x16x32_bf16 v[32:35], v[198:201], v[12:15], v[32:35]
	s_nop 1
	s_waitcnt lgkmcnt(2)
	v_mfma_f32_16x16x32_bf16 v[32:35], v[202:205], v[8:11], v[32:35]
	ds_read_b64_tr_b16 v[44:45], v38 offset:52288
	ds_read_b64_tr_b16 v[46:47], v38 offset:56640
	s_waitcnt lgkmcnt(2)
	v_mfma_f32_16x16x32_bf16 v[32:35], v[206:209], v[4:7], v[32:35]
	ds_read_b64_tr_b16 v[40:41], v38 offset:60992
	ds_read_b64_tr_b16 v[42:43], v38 offset:65344
	s_waitcnt lgkmcnt(2)
	v_mfma_f32_16x16x32_bf16 v[32:35], v[44:47], v[0:3], v[32:35]
	s_waitcnt lgkmcnt(0)
	v_mfma_f32_16x16x32_bf16 v[32:35], v[40:43], v[28:31], v[32:35]
	s_and_saveexec_b64 s[2:3], s[0:1]
	s_cbranch_execz .LBB0_607
	s_nop 5
	v_mul_f32_e32 v32, v39, v32
	v_mul_f32_e32 v33, v39, v33
	v_cvt_pk_bf16_f32 v32, v32, v33
	v_mul_f32_e32 v33, v39, v34
	v_mul_f32_e32 v34, v39, v35
	v_cvt_pk_bf16_f32 v33, v33, v34
	global_store_dwordx2 v[36:37], v[32:33], off offset:64
.LBB0_607:
	s_or_b64 exec, exec, s[2:3]
	s_nop 4
	ds_read_b64_tr_b16 v[186:187], v38 offset:96
	ds_read_b64_tr_b16 v[188:189], v38 offset:4448
	ds_read_b64_tr_b16 v[190:191], v38 offset:8800
	ds_read_b64_tr_b16 v[192:193], v38 offset:13152
	ds_read_b64_tr_b16 v[194:195], v38 offset:17504
	ds_read_b64_tr_b16 v[196:197], v38 offset:21856
	ds_read_b64_tr_b16 v[198:199], v38 offset:26208
	ds_read_b64_tr_b16 v[200:201], v38 offset:30560
	ds_read_b64_tr_b16 v[202:203], v38 offset:34912
	ds_read_b64_tr_b16 v[204:205], v38 offset:39264
	ds_read_b64_tr_b16 v[206:207], v38 offset:43616
	ds_read_b64_tr_b16 v[208:209], v38 offset:47968
	s_nop 5
	s_waitcnt lgkmcnt(10)
	v_mfma_f32_16x16x32_bf16 v[32:35], v[186:189], v[24:27], 0
	s_waitcnt lgkmcnt(8)
	v_mfma_f32_16x16x32_bf16 v[32:35], v[190:193], v[20:23], v[32:35]
	s_nop 1
	s_waitcnt lgkmcnt(6)
	v_mfma_f32_16x16x32_bf16 v[32:35], v[194:197], v[16:19], v[32:35]
	s_nop 1
	s_waitcnt lgkmcnt(4)
	v_mfma_f32_16x16x32_bf16 v[32:35], v[198:201], v[12:15], v[32:35]
	s_nop 1
	s_waitcnt lgkmcnt(2)
	v_mfma_f32_16x16x32_bf16 v[32:35], v[202:205], v[8:11], v[32:35]
	ds_read_b64_tr_b16 v[44:45], v38 offset:52320
	ds_read_b64_tr_b16 v[46:47], v38 offset:56672
	s_waitcnt lgkmcnt(2)
	v_mfma_f32_16x16x32_bf16 v[32:35], v[206:209], v[4:7], v[32:35]
	ds_read_b64_tr_b16 v[40:41], v38 offset:61024
	ds_read_b64_tr_b16 v[42:43], v38 offset:65376
	s_waitcnt lgkmcnt(2)
	v_mfma_f32_16x16x32_bf16 v[32:35], v[44:47], v[0:3], v[32:35]
	s_waitcnt lgkmcnt(0)
	v_mfma_f32_16x16x32_bf16 v[32:35], v[40:43], v[28:31], v[32:35]
	s_and_saveexec_b64 s[2:3], s[0:1]
	s_cbranch_execz .LBB0_609
	s_nop 5
	v_mul_f32_e32 v32, v39, v32
	v_mul_f32_e32 v33, v39, v33
	v_cvt_pk_bf16_f32 v32, v32, v33
	v_mul_f32_e32 v33, v39, v34
	v_mul_f32_e32 v34, v39, v35
	v_cvt_pk_bf16_f32 v33, v33, v34
	global_store_dwordx2 v[36:37], v[32:33], off offset:96
.LBB0_609:
	s_or_b64 exec, exec, s[2:3]
	s_nop 4
	ds_read_b64_tr_b16 v[186:187], v38 offset:128
	ds_read_b64_tr_b16 v[188:189], v38 offset:4480
	ds_read_b64_tr_b16 v[190:191], v38 offset:8832
	ds_read_b64_tr_b16 v[192:193], v38 offset:13184
	ds_read_b64_tr_b16 v[194:195], v38 offset:17536
	ds_read_b64_tr_b16 v[196:197], v38 offset:21888
	ds_read_b64_tr_b16 v[198:199], v38 offset:26240
	ds_read_b64_tr_b16 v[200:201], v38 offset:30592
	ds_read_b64_tr_b16 v[202:203], v38 offset:34944
	ds_read_b64_tr_b16 v[204:205], v38 offset:39296
	ds_read_b64_tr_b16 v[206:207], v38 offset:43648
	ds_read_b64_tr_b16 v[208:209], v38 offset:48000
	s_nop 5
	s_waitcnt lgkmcnt(10)
	v_mfma_f32_16x16x32_bf16 v[32:35], v[186:189], v[24:27], 0
	s_waitcnt lgkmcnt(8)
	v_mfma_f32_16x16x32_bf16 v[32:35], v[190:193], v[20:23], v[32:35]
	s_nop 1
	s_waitcnt lgkmcnt(6)
	v_mfma_f32_16x16x32_bf16 v[32:35], v[194:197], v[16:19], v[32:35]
	s_nop 1
	s_waitcnt lgkmcnt(4)
	v_mfma_f32_16x16x32_bf16 v[32:35], v[198:201], v[12:15], v[32:35]
	s_nop 1
	s_waitcnt lgkmcnt(2)
	v_mfma_f32_16x16x32_bf16 v[32:35], v[202:205], v[8:11], v[32:35]
	ds_read_b64_tr_b16 v[44:45], v38 offset:52352
	ds_read_b64_tr_b16 v[46:47], v38 offset:56704
	s_waitcnt lgkmcnt(2)
	v_mfma_f32_16x16x32_bf16 v[32:35], v[206:209], v[4:7], v[32:35]
	ds_read_b64_tr_b16 v[40:41], v38 offset:61056
	ds_read_b64_tr_b16 v[42:43], v38 offset:65408
	s_waitcnt lgkmcnt(2)
	v_mfma_f32_16x16x32_bf16 v[32:35], v[44:47], v[0:3], v[32:35]
	s_waitcnt lgkmcnt(0)
	v_mfma_f32_16x16x32_bf16 v[32:35], v[40:43], v[28:31], v[32:35]
	s_and_saveexec_b64 s[2:3], s[0:1]
	s_cbranch_execz .LBB0_611
	s_nop 5
	v_mul_f32_e32 v32, v39, v32
	v_mul_f32_e32 v33, v39, v33
	v_cvt_pk_bf16_f32 v32, v32, v33
	v_mul_f32_e32 v33, v39, v34
	v_mul_f32_e32 v34, v39, v35
	v_cvt_pk_bf16_f32 v33, v33, v34
	global_store_dwordx2 v[36:37], v[32:33], off offset:128
; #define LAS __attribute__((address_space(3)))
; __device__ __forceinline__ unsigned pk2(float lo, float hi) { return pg8::cvt_pk_bf16(lo, hi); }
; __device__ __forceinline__ v2u vtr(const LAS bf16* p) { return __builtin_bit_cast(v2u, __builtin_amdgcn_ds_read_tr16_b64_v4i16((LAS v4i16_t*)p)); }
; template <bool SAMPLE>
; __device__ __forceinline__ void mem_unit(const Params& p, int l, LAS unsigned char* lds, int unit, int tid, int wave, int lane) {
;     ...
; #pragma unroll
;         for (int dt = 0; dt < 8; ++dt) { f32x4 o = (f32x4){0.f, 0.f, 0.f, 0.f};
; #pragma unroll
;             for (int cc = 0; cc < 8; ++cc) { const LAS bf16* vp = Vt + (32 * cc + 4 * kq + (q16 >> 2)) * MEM_VS + 16 * dt + 4 * (q16 & 3);
;                 const v2u lo = vtr(vp), hi = vtr(vp + 16 * MEM_VS);
;                 v4u av; av.x = lo.x; av.y = lo.y; av.z = hi.x; av.w = hi.y;
;                 o = __builtin_amdgcn_mfma_f32_16x16x32_bf16(__builtin_bit_cast(bf16x8, av), pf[cc], o, 0, 0, 0); }
;             if (st) { v2u w; w.x = pk2(o[0] * rden, o[1] * rden); w.y = pk2(o[2] * rden, o[3] * rden);
;                 *(v2u*)(MO + row * 512 + h * 128 + 16 * dt + 4 * kq) = w; } }
.LBB0_611:
	s_or_b64 exec, exec, s[2:3]
	s_nop 4
	ds_read_b64_tr_b16 v[186:187], v38 offset:160
	ds_read_b64_tr_b16 v[188:189], v38 offset:4512
	ds_read_b64_tr_b16 v[190:191], v38 offset:8864
	ds_read_b64_tr_b16 v[192:193], v38 offset:13216
	ds_read_b64_tr_b16 v[194:195], v38 offset:17568
	ds_read_b64_tr_b16 v[196:197], v38 offset:21920
	ds_read_b64_tr_b16 v[198:199], v38 offset:26272
	ds_read_b64_tr_b16 v[200:201], v38 offset:30624
	ds_read_b64_tr_b16 v[202:203], v38 offset:34976
	ds_read_b64_tr_b16 v[204:205], v38 offset:39328
	ds_read_b64_tr_b16 v[206:207], v38 offset:43680
	ds_read_b64_tr_b16 v[208:209], v38 offset:48032
	s_nop 5
	s_waitcnt lgkmcnt(10)
	v_mfma_f32_16x16x32_bf16 v[32:35], v[186:189], v[24:27], 0
	s_waitcnt lgkmcnt(8)
	v_mfma_f32_16x16x32_bf16 v[32:35], v[190:193], v[20:23], v[32:35]
	s_nop 1
	s_waitcnt lgkmcnt(6)
	v_mfma_f32_16x16x32_bf16 v[32:35], v[194:197], v[16:19], v[32:35]
	s_nop 1
	s_waitcnt lgkmcnt(4)
	v_mfma_f32_16x16x32_bf16 v[32:35], v[198:201], v[12:15], v[32:35]
	s_nop 1
	s_waitcnt lgkmcnt(2)
	v_mfma_f32_16x16x32_bf16 v[32:35], v[202:205], v[8:11], v[32:35]
	ds_read_b64_tr_b16 v[44:45], v38 offset:52384
	ds_read_b64_tr_b16 v[46:47], v38 offset:56736
	s_waitcnt lgkmcnt(2)
	v_mfma_f32_16x16x32_bf16 v[32:35], v[206:209], v[4:7], v[32:35]
	ds_read_b64_tr_b16 v[40:41], v38 offset:61088
	ds_read_b64_tr_b16 v[42:43], v38 offset:65440
	s_waitcnt lgkmcnt(2)
	v_mfma_f32_16x16x32_bf16 v[32:35], v[44:47], v[0:3], v[32:35]
	s_waitcnt lgkmcnt(0)
	v_mfma_f32_16x16x32_bf16 v[32:35], v[40:43], v[28:31], v[32:35]
	s_and_saveexec_b64 s[2:3], s[0:1]
	s_cbranch_execz .LBB0_613
	s_nop 5
	v_mul_f32_e32 v32, v39, v32
	v_mul_f32_e32 v33, v39, v33
	v_cvt_pk_bf16_f32 v32, v32, v33
	v_mul_f32_e32 v33, v39, v34
	v_mul_f32_e32 v34, v39, v35
	v_cvt_pk_bf16_f32 v33, v33, v34
	global_store_dwordx2 v[36:37], v[32:33], off offset:160
.LBB0_613:
	s_or_b64 exec, exec, s[2:3]
	s_nop 4
	ds_read_b64_tr_b16 v[186:187], v38 offset:192
	ds_read_b64_tr_b16 v[188:189], v38 offset:4544
	ds_read_b64_tr_b16 v[190:191], v38 offset:8896
	ds_read_b64_tr_b16 v[192:193], v38 offset:13248
	ds_read_b64_tr_b16 v[194:195], v38 offset:17600
	ds_read_b64_tr_b16 v[196:197], v38 offset:21952
	ds_read_b64_tr_b16 v[198:199], v38 offset:26304
	ds_read_b64_tr_b16 v[200:201], v38 offset:30656
	ds_read_b64_tr_b16 v[202:203], v38 offset:35008
	ds_read_b64_tr_b16 v[204:205], v38 offset:39360
	ds_read_b64_tr_b16 v[206:207], v38 offset:43712
	ds_read_b64_tr_b16 v[208:209], v38 offset:48064
	s_nop 5
	s_waitcnt lgkmcnt(10)
	v_mfma_f32_16x16x32_bf16 v[32:35], v[186:189], v[24:27], 0
	s_waitcnt lgkmcnt(8)
	v_mfma_f32_16x16x32_bf16 v[32:35], v[190:193], v[20:23], v[32:35]
	s_nop 1
	s_waitcnt lgkmcnt(6)
	v_mfma_f32_16x16x32_bf16 v[32:35], v[194:197], v[16:19], v[32:35]
	s_nop 1
	s_waitcnt lgkmcnt(4)
	v_mfma_f32_16x16x32_bf16 v[32:35], v[198:201], v[12:15], v[32:35]
	s_nop 1
	s_waitcnt lgkmcnt(2)
	v_mfma_f32_16x16x32_bf16 v[32:35], v[202:205], v[8:11], v[32:35]
	ds_read_b64_tr_b16 v[44:45], v38 offset:52416
	ds_read_b64_tr_b16 v[46:47], v38 offset:56768
	s_waitcnt lgkmcnt(2)
	v_mfma_f32_16x16x32_bf16 v[32:35], v[206:209], v[4:7], v[32:35]
	ds_read_b64_tr_b16 v[40:41], v38 offset:61120
	ds_read_b64_tr_b16 v[42:43], v38 offset:65472
	s_waitcnt lgkmcnt(2)
	v_mfma_f32_16x16x32_bf16 v[32:35], v[44:47], v[0:3], v[32:35]
	s_waitcnt lgkmcnt(0)
	v_mfma_f32_16x16x32_bf16 v[32:35], v[40:43], v[28:31], v[32:35]
	s_and_saveexec_b64 s[2:3], s[0:1]
	s_cbranch_execz .LBB0_615
	s_nop 5
	v_mul_f32_e32 v32, v39, v32
	v_mul_f32_e32 v33, v39, v33
	v_cvt_pk_bf16_f32 v32, v32, v33
	v_mul_f32_e32 v33, v39, v34
	v_mul_f32_e32 v34, v39, v35
	v_cvt_pk_bf16_f32 v33, v33, v34
	global_store_dwordx2 v[36:37], v[32:33], off offset:192

; template <bool SAMPLE>
; __device__ __forceinline__ void mem_unit(const Params& p, int l, LAS unsigned char* lds, int unit, int tid, int wave, int lane) {
;     ...
;     __syncthreads();
.LBB0_618:
	s_nop 0
	s_nop 0
	s_nop 0
	s_nop 0
	s_nop 0
	s_nop 0
	s_nop 0
	s_nop 0
	s_nop 0
	s_nop 0
	s_mov_b64 s[0:1], 0
	s_barrier

; __device__ __forceinline__ void unpack8(const v4u w, float (&o)[8]) { o[0] = bflo(w.x); o[1] = bfhi(w.x); o[2] = bflo(w.y); o[3] = bfhi(w.y); o[4] = bflo(w.z); o[5] = bfhi(w.z); o[6] = bflo(w.w); o[7] = bfhi(w.w); }
; __device__ __forceinline__ bf16x8 pack8(const float (&o)[8]) { v4u w; w.x = pk2(o[0], o[1]); w.y = pk2(o[2], o[3]); w.z = pk2(o[4], o[5]); w.w = pk2(o[6], o[7]); return __builtin_bit_cast(bf16x8, w); }
; template <bool SAMPLE>
; __device__ __forceinline__ void mem_unit(const Params& p, int l, LAS unsigned char* lds, int unit, int tid, int wave, int lane) {
;     ...
;         int q16 = lane & 15, kq = lane >> 4; asm volatile("" : "+v"(q16), "+v"(kq));
;         size_t row; bool st;
;         if (!SAMPLE) { row = (size_t)b * 8192 + (qt * 4 + qq) * 128 + 16 * wave + q16; st = true; } else { row = (size_t)MP + 8 * b + (q16 & 7); st = q16 < 8; }
;         bf16x8 qf[4];
;         {
;             float qv[4][8]; float ss = 0.f;
; #pragma unroll
;             for (int dc = 0; dc < 4; ++dc) { unpack8(*(const v4u*)(MQ + row * 512 + h * 128 + 32 * dc + 8 * kq), qv[dc]);
; #pragma unroll
;                 for (int e = 0; e < 8; ++e) ss += qv[dc][e] * qv[dc][e]; }
;             ss += __shfl_xor(ss, 16); ss += __shfl_xor(ss, 32);
;             const float rs = rsqrtf(ss * (1.f / 128.f) + EPS) * 0.08838834764831845f;
; #pragma unroll
;             for (int dc = 0; dc < 4; ++dc) { float qg[8]; pg8::ld8f(p.in[I_MQG] + l * 128 + 32 * dc + 8 * kq, qg);
; #pragma unroll
;                 for (int e = 0; e < 8; ++e) qv[dc][e] *= rs * qg[e];
;                 qf[dc] = pack8(qv[dc]); }
.LBB0_631:
	v_mov_b32_e32 v90, v94
	v_mov_b32_e32 v92, v95
	s_add_u32 s16, s10, s8
	s_addc_u32 s17, s18, s9
	v_ashrrev_i32_e32 v91, 31, v90
	v_lshl_add_u64 v[0:1], s[16:17], 0, v[90:91]
	v_lshlrev_b32_e32 v8, 3, v92
	v_lshlrev_b64 v[88:89], 10, v[0:1]
	v_ashrrev_i32_e32 v9, 31, v8
	v_lshl_add_u64 v[10:11], s[0:1], 0, v[88:89]
	v_lshlrev_b32_e32 v2, 4, v92
	v_mul_lo_u32 v3, v90, s30
	v_lshl_add_u64 v[24:25], v[8:9], 2, s[46:47]
	v_lshl_add_u64 v[20:21], v[8:9], 1, v[10:11]
	v_add3_u32 v91, 0, v2, v3
	global_load_dwordx4 v[0:3], v[24:25], off offset:16
	global_load_dwordx4 v[4:7], v[24:25], off
	global_load_dwordx4 v[8:11], v[20:21], off
	global_load_dwordx4 v[12:15], v[20:21], off offset:64
	global_load_dwordx4 v[16:19], v[20:21], off offset:128
	s_nop 0
	global_load_dwordx4 v[20:23], v[20:21], off offset:192
	v_lshlrev_b32_e32 v92, 2, v92
	v_ashrrev_i32_e32 v93, 31, v92
	s_add_u32 s8, s8, 0x80
	s_addc_u32 s9, s9, 0
	s_cmpk_lg_i32 s8, 0x200
	s_waitcnt vmcnt(3)
	v_and_b32_e32 v31, 0xffff0000, v8
	v_lshlrev_b32_e32 v30, 16, v8
	v_mul_f32_e32 v50, v31, v31
	v_lshlrev_b32_e32 v32, 16, v9
	v_fmac_f32_e32 v50, v30, v30
	v_and_b32_e32 v33, 0xffff0000, v9
	v_fmac_f32_e32 v50, v32, v32
	v_lshlrev_b32_e32 v34, 16, v10
	v_fmac_f32_e32 v50, v33, v33
	v_and_b32_e32 v35, 0xffff0000, v10
	v_fmac_f32_e32 v50, v34, v34
	v_lshlrev_b32_e32 v36, 16, v11
	v_fmac_f32_e32 v50, v35, v35
	v_and_b32_e32 v37, 0xffff0000, v11
	v_fmac_f32_e32 v50, v36, v36
	s_waitcnt vmcnt(2)
	v_lshlrev_b32_e32 v38, 16, v12
	v_fmac_f32_e32 v50, v37, v37
	v_and_b32_e32 v39, 0xffff0000, v12
	v_fmac_f32_e32 v50, v38, v38
	v_lshlrev_b32_e32 v40, 16, v13
	v_fmac_f32_e32 v50, v39, v39
	v_and_b32_e32 v41, 0xffff0000, v13
	v_fmac_f32_e32 v50, v40, v40
	v_lshlrev_b32_e32 v42, 16, v14
	v_fmac_f32_e32 v50, v41, v41
	v_and_b32_e32 v43, 0xffff0000, v14
	v_fmac_f32_e32 v50, v42, v42
	v_lshlrev_b32_e32 v44, 16, v15
	v_fmac_f32_e32 v50, v43, v43
	v_and_b32_e32 v45, 0xffff0000, v15
	v_fmac_f32_e32 v50, v44, v44
	s_waitcnt vmcnt(1)
	v_lshlrev_b32_e32 v46, 16, v16
	v_fmac_f32_e32 v50, v45, v45
	v_and_b32_e32 v16, 0xffff0000, v16
	v_fmac_f32_e32 v50, v46, v46
	v_lshlrev_b32_e32 v47, 16, v17
	v_fmac_f32_e32 v50, v16, v16
	v_and_b32_e32 v17, 0xffff0000, v17
	v_fmac_f32_e32 v50, v47, v47
	v_lshlrev_b32_e32 v48, 16, v18
	v_fmac_f32_e32 v50, v17, v17
	v_and_b32_e32 v18, 0xffff0000, v18
	v_fmac_f32_e32 v50, v48, v48
	v_lshlrev_b32_e32 v49, 16, v19
	v_fmac_f32_e32 v50, v18, v18
	v_and_b32_e32 v19, 0xffff0000, v19
	s_waitcnt vmcnt(0)
	v_and_b32_e32 v26, 0xffff0000, v20
	v_lshlrev_b32_e32 v27, 16, v20
	v_fmac_f32_e32 v50, v49, v49
	v_pk_mul_f32 v[8:9], v[26:27], v[26:27]
	v_fmac_f32_e32 v50, v19, v19
	v_and_b32_e32 v20, 0xffff0000, v21
	v_lshlrev_b32_e32 v21, 16, v21
	v_add_f32_e32 v9, v9, v50
	v_pk_mul_f32 v[10:11], v[20:21], v[20:21]
	v_add_f32_e32 v8, v8, v9
	v_and_b32_e32 v28, 0xffff0000, v22
	v_lshlrev_b32_e32 v29, 16, v22
	v_add_f32_e32 v8, v11, v8
	v_pk_mul_f32 v[12:13], v[28:29], v[28:29]
	v_add_f32_e32 v8, v10, v8
	v_and_b32_e32 v22, 0xffff0000, v23
	v_lshlrev_b32_e32 v23, 16, v23
	v_add_f32_e32 v8, v13, v8
	v_pk_mul_f32 v[14:15], v[22:23], v[22:23]
	v_add_f32_e32 v8, v12, v8
	v_add_f32_e32 v8, v15, v8
	v_add_f32_e32 v8, v14, v8
	ds_bpermute_b32 v9, v82, v8
	s_waitcnt lgkmcnt(0)
	v_add_f32_e32 v8, v8, v9
	ds_bpermute_b32 v9, v100, v8
	s_waitcnt lgkmcnt(0)
	v_add_f32_e32 v8, v8, v9
	v_fmamk_f32 v8, v8, 0x3c000000, v98
	v_mul_f32_e32 v9, 0x4b800000, v8
	v_cmp_gt_f32_e32 vcc, s31, v8
	s_nop 1
	v_cndmask_b32_e32 v8, v8, v9, vcc
	v_rsq_f32_e32 v8, v8
	s_nop 0
	v_mul_f32_e32 v9, 0x45800000, v8
	v_cndmask_b32_e32 v8, v8, v9, vcc
	v_mul_f32_e32 v50, 0x3db504f3, v8
	v_mul_f32_e32 v4, v4, v50
	v_mul_f32_e32 v5, v5, v50
	v_mul_f32_e32 v6, v6, v50
	v_mul_f32_e32 v7, v7, v50
	v_mul_f32_e32 v0, v0, v50
	v_mul_f32_e32 v1, v1, v50
	v_mul_f32_e32 v2, v2, v50
	v_mul_f32_e32 v3, v3, v50
	v_mul_f32_e32 v4, v4, v30
	v_mul_f32_e32 v5, v5, v31
	v_mul_f32_e32 v6, v6, v32
	v_mul_f32_e32 v7, v7, v33
	v_mul_f32_e32 v0, v0, v34
	v_mul_f32_e32 v1, v1, v35
	v_mul_f32_e32 v2, v2, v36
	v_mul_f32_e32 v3, v3, v37
	v_cvt_pk_bf16_f32 v8, v4, v5
	v_cvt_pk_bf16_f32 v9, v6, v7
	v_cvt_pk_bf16_f32 v10, v0, v1
	v_cvt_pk_bf16_f32 v11, v2, v3
	global_load_dwordx4 v[0:3], v[24:25], off offset:128
	global_load_dwordx4 v[4:7], v[24:25], off offset:144
	s_waitcnt vmcnt(1)
	v_mul_f32_e32 v0, v0, v50
	v_mul_f32_e32 v1, v1, v50
	v_mul_f32_e32 v2, v2, v50
	v_mul_f32_e32 v3, v3, v50
	s_waitcnt vmcnt(0)
	v_mul_f32_e32 v4, v4, v50
	v_mul_f32_e32 v5, v5, v50
	v_mul_f32_e32 v6, v6, v50
	v_mul_f32_e32 v7, v7, v50
	v_mul_f32_e32 v0, v0, v38
	v_mul_f32_e32 v1, v1, v39
	v_mul_f32_e32 v2, v2, v40
	v_mul_f32_e32 v3, v3, v41
	v_mul_f32_e32 v4, v4, v42
	v_mul_f32_e32 v5, v5, v43
	v_mul_f32_e32 v6, v6, v44
	v_mul_f32_e32 v7, v7, v45
	v_cvt_pk_bf16_f32 v12, v0, v1
	v_cvt_pk_bf16_f32 v13, v2, v3
	v_cvt_pk_bf16_f32 v14, v4, v5
	v_cvt_pk_bf16_f32 v15, v6, v7
	global_load_dwordx4 v[0:3], v[24:25], off offset:256
	global_load_dwordx4 v[4:7], v[24:25], off offset:272
	s_waitcnt vmcnt(1)
	v_mul_f32_e32 v0, v0, v50
	v_mul_f32_e32 v1, v1, v50
	v_mul_f32_e32 v2, v2, v50
	v_mul_f32_e32 v3, v3, v50
	s_waitcnt vmcnt(0)
	v_mul_f32_e32 v4, v4, v50
	v_mul_f32_e32 v5, v5, v50
	v_mul_f32_e32 v6, v6, v50
	v_mul_f32_e32 v7, v7, v50
	v_mul_f32_e32 v0, v0, v46
	v_mul_f32_e32 v1, v1, v16
	v_mul_f32_e32 v2, v2, v47
	v_mul_f32_e32 v3, v3, v17
	v_mul_f32_e32 v16, v4, v48
	v_mul_f32_e32 v17, v5, v18
	v_mul_f32_e32 v18, v6, v49
	v_mul_f32_e32 v7, v7, v19
	v_cvt_pk_bf16_f32 v4, v0, v1
	v_cvt_pk_bf16_f32 v5, v2, v3
	v_cvt_pk_bf16_f32 v6, v16, v17
	v_cvt_pk_bf16_f32 v7, v18, v7
	global_load_dwordx4 v[0:3], v[24:25], off offset:384
	global_load_dwordx4 v[16:19], v[24:25], off offset:400
	s_waitcnt vmcnt(1)
; #define LAS __attribute__((address_space(3)))
; template <bool SAMPLE>
; __device__ __forceinline__ void mem_unit(const Params& p, int l, LAS unsigned char* lds, int unit, int tid, int wave, int lane) {
;     ...
;         f32x4 S[8][2]; float mx = -INFINITY;
; #pragma unroll
;         for (int cc = 0; cc < 8; ++cc)
; #pragma unroll
;             for (int tt = 0; tt < 2; ++tt) { const int kb = 32 * cc + 16 * tt; f32x4 a = (f32x4){0.f, 0.f, 0.f, 0.f};
; #pragma unroll
;                 for (int dc = 0; dc < 4; ++dc) { const bf16x8 kf = *(const LAS bf16x8*)(Kl + (kb + q16) * MEM_KS + 32 * dc + 8 * kq);
;                     a = __builtin_amdgcn_mfma_f32_16x16x32_bf16(kf, qf[dc], a, 0, 0, 0); }
	v_mul_f32_e32 v0, v0, v50
	v_mul_f32_e32 v1, v1, v50
	v_mul_f32_e32 v2, v2, v50
	v_mul_f32_e32 v3, v3, v50
	s_waitcnt vmcnt(0)
	v_mul_f32_e32 v16, v16, v50
	v_mul_f32_e32 v17, v17, v50
	v_mul_f32_e32 v18, v18, v50
	v_mul_f32_e32 v19, v19, v50
	v_mul_f32_e32 v0, v0, v27
	v_mul_f32_e32 v1, v1, v26
	v_mul_f32_e32 v2, v2, v21
	v_mul_f32_e32 v3, v3, v20
	v_mul_f32_e32 v16, v16, v29
	v_mul_f32_e32 v17, v17, v28
	v_mul_f32_e32 v18, v18, v23
	v_mul_f32_e32 v19, v19, v22
	v_cvt_pk_bf16_f32 v0, v0, v1
	v_cvt_pk_bf16_f32 v1, v2, v3
	v_cvt_pk_bf16_f32 v2, v16, v17
	v_cvt_pk_bf16_f32 v3, v18, v19
	ds_read_b128 v[186:189], v91
	ds_read_b128 v[190:193], v91 offset:4352
	ds_read_b128 v[194:197], v91 offset:8704
	ds_read_b128 v[198:201], v91 offset:13056
	ds_read_b128 v[202:205], v91 offset:17408
	ds_read_b128 v[206:209], v91 offset:21760
	ds_read_b128 v[210:213], v91 offset:26112
	s_nop 0
	ds_read_b128 v[20:23], v91 offset:64
	s_nop 0
	ds_read_b128 v[28:31], v91 offset:4416
	s_nop 0
	ds_read_b128 v[36:39], v91 offset:8768
	s_nop 0
	ds_read_b128 v[44:47], v91 offset:13120
	s_nop 0
	ds_read_b128 v[52:55], v91 offset:17472
	s_nop 0
	ds_read_b128 v[60:63], v91 offset:21824
	s_nop 0
	ds_read_b128 v[68:71], v91 offset:26176
	ds_read_b128 v[72:75], v91 offset:30464
	ds_read_b128 v[76:79], v91 offset:30528
	ds_read_b128 v[102:105], v91 offset:34816
	ds_read_b128 v[106:109], v91 offset:34880
	ds_read_b128 v[110:113], v91 offset:39168
	ds_read_b128 v[114:117], v91 offset:39232
	ds_read_b128 v[118:121], v91 offset:43520
	ds_read_b128 v[122:125], v91 offset:43584
	ds_read_b128 v[126:129], v91 offset:47872
	ds_read_b128 v[130:133], v91 offset:47936
	ds_read_b128 v[134:137], v91 offset:52224
	ds_read_b128 v[138:141], v91 offset:52288
	ds_read_b128 v[142:145], v91 offset:56576
	ds_read_b128 v[146:149], v91 offset:56640
	ds_read_b128 v[150:153], v91 offset:60928
	ds_read_b128 v[154:157], v91 offset:60992
	ds_read_b128 v[158:161], v91 offset:65280
	ds_read_b128 v[162:165], v91 offset:65344
	s_waitcnt lgkmcnt(14)
	v_mfma_f32_16x16x32_bf16 v[16:19], v[186:189], v[8:11], 0
	v_mfma_f32_16x16x32_bf16 v[24:27], v[190:193], v[8:11], 0
	v_mfma_f32_16x16x32_bf16 v[32:35], v[194:197], v[8:11], 0
	v_mfma_f32_16x16x32_bf16 v[40:43], v[198:201], v[8:11], 0
	v_mfma_f32_16x16x32_bf16 v[48:51], v[202:205], v[8:11], 0
	v_mfma_f32_16x16x32_bf16 v[56:59], v[206:209], v[8:11], 0
	v_mfma_f32_16x16x32_bf16 v[64:67], v[210:213], v[8:11], 0
	v_mfma_f32_16x16x32_bf16 v[72:75], v[72:75], v[8:11], 0
	v_mfma_f32_16x16x32_bf16 v[102:105], v[102:105], v[8:11], 0
	s_waitcnt lgkmcnt(13)
	v_mfma_f32_16x16x32_bf16 v[110:113], v[110:113], v[8:11], 0
	s_waitcnt lgkmcnt(11)
	v_mfma_f32_16x16x32_bf16 v[118:121], v[118:121], v[8:11], 0
	s_waitcnt lgkmcnt(9)
	v_mfma_f32_16x16x32_bf16 v[126:129], v[126:129], v[8:11], 0
	s_waitcnt lgkmcnt(7)
	v_mfma_f32_16x16x32_bf16 v[134:137], v[134:137], v[8:11], 0
	s_waitcnt lgkmcnt(5)
	v_mfma_f32_16x16x32_bf16 v[142:145], v[142:145], v[8:11], 0
	s_waitcnt lgkmcnt(3)
	v_mfma_f32_16x16x32_bf16 v[150:153], v[150:153], v[8:11], 0
	s_waitcnt lgkmcnt(1)
	v_mfma_f32_16x16x32_bf16 v[8:11], v[158:161], v[8:11], 0
	v_mfma_f32_16x16x32_bf16 v[16:19], v[20:23], v[12:15], v[16:19]
	v_mfma_f32_16x16x32_bf16 v[20:23], v[28:31], v[12:15], v[24:27]
	v_mfma_f32_16x16x32_bf16 v[24:27], v[36:39], v[12:15], v[32:35]
	v_mfma_f32_16x16x32_bf16 v[28:31], v[44:47], v[12:15], v[40:43]
	v_mfma_f32_16x16x32_bf16 v[32:35], v[52:55], v[12:15], v[48:51]
	ds_read_b128 v[202:205], v91 offset:128
	ds_read_b128 v[206:209], v91 offset:4480
	ds_read_b128 v[210:213], v91 offset:8832
	v_mfma_f32_16x16x32_bf16 v[36:39], v[60:63], v[12:15], v[56:59]
	v_mfma_f32_16x16x32_bf16 v[40:43], v[68:71], v[12:15], v[64:67]
	v_mfma_f32_16x16x32_bf16 v[44:47], v[76:79], v[12:15], v[72:75]
	v_mfma_f32_16x16x32_bf16 v[48:51], v[106:109], v[12:15], v[102:105]
	v_mfma_f32_16x16x32_bf16 v[52:55], v[114:117], v[12:15], v[110:113]
	v_mfma_f32_16x16x32_bf16 v[56:59], v[122:125], v[12:15], v[118:121]
	v_mfma_f32_16x16x32_bf16 v[60:63], v[130:133], v[12:15], v[126:129]
	ds_read_b128 v[218:221], v91 offset:13184
	ds_read_b128 v[222:225], v91 offset:17536
	ds_read_b128 v[226:229], v91 offset:21888
	ds_read_b128 v[230:233], v91 offset:26240
	ds_read_b128 v[234:237], v91 offset:30592
	ds_read_b128 v[242:245], v91 offset:34944
	ds_read_b128 v[246:249], v91 offset:39296
	v_mfma_f32_16x16x32_bf16 v[64:67], v[138:141], v[12:15], v[134:137]
	v_mfma_f32_16x16x32_bf16 v[68:71], v[146:149], v[12:15], v[142:145]
	v_mfma_f32_16x16x32_bf16 v[102:105], v[154:157], v[12:15], v[150:153]
	s_waitcnt lgkmcnt(10)
	v_mfma_f32_16x16x32_bf16 v[8:11], v[162:165], v[12:15], v[8:11]
	s_nop 0
	ds_read_b128 v[106:109], v91 offset:192
	s_waitcnt lgkmcnt(10)
	v_mfma_f32_16x16x32_bf16 v[12:15], v[202:205], v[4:7], v[16:19]
	s_nop 2
	s_nop 0
	ds_read_b128 v[110:113], v91 offset:4544
	s_waitcnt lgkmcnt(10)
	v_mfma_f32_16x16x32_bf16 v[16:19], v[206:209], v[4:7], v[20:23]
	s_nop 2
	s_nop 0
	ds_read_b128 v[114:117], v91 offset:8896
	s_waitcnt lgkmcnt(10)
	v_mfma_f32_16x16x32_bf16 v[20:23], v[210:213], v[4:7], v[24:27]
	s_nop 2
	s_nop 0
	ds_read_b128 v[118:121], v91 offset:13248
	s_waitcnt lgkmcnt(10)
	ds_read_b128 v[186:189], v91 offset:43648
	ds_read_b128 v[190:193], v91 offset:48000
	ds_read_b128 v[194:197], v91 offset:52352
	ds_read_b128 v[198:201], v91 offset:56704
	ds_read_b128 v[202:205], v91 offset:61056
	ds_read_b128 v[206:209], v91 offset:65408
	v_mfma_f32_16x16x32_bf16 v[24:27], v[218:221], v[4:7], v[28:31]
	s_nop 2
	s_nop 0
	ds_read_b128 v[122:125], v91 offset:17600
	s_waitcnt lgkmcnt(15)
; #define LAS __attribute__((address_space(3)))
; template <bool SAMPLE>
; __device__ __forceinline__ void mem_unit(const Params& p, int l, LAS unsigned char* lds, int unit, int tid, int wave, int lane) {
;     ...
;         f32x4 S[8][2]; float mx = -INFINITY;
; #pragma unroll
;         for (int cc = 0; cc < 8; ++cc)
; #pragma unroll
;             for (int tt = 0; tt < 2; ++tt) { const int kb = 32 * cc + 16 * tt; f32x4 a = (f32x4){0.f, 0.f, 0.f, 0.f};
; #pragma unroll
;                 for (int dc = 0; dc < 4; ++dc) { const bf16x8 kf = *(const LAS bf16x8*)(Kl + (kb + q16) * MEM_KS + 32 * dc + 8 * kq);
;                     a = __builtin_amdgcn_mfma_f32_16x16x32_bf16(kf, qf[dc], a, 0, 0, 0); }
; #pragma unroll
;                 for (int e = 0; e < 4; ++e) mx = fmaxf(mx, a[e]);
;                 S[cc][tt] = a; }
;         mx = fmaxf(mx, __shfl_xor(mx, 16)); mx = fmaxf(mx, __shfl_xor(mx, 32));
;         float den = 0.f;
; #pragma unroll
;         for (int cc = 0; cc < 8; ++cc)
; #pragma unroll
;             for (int tt = 0; tt < 2; ++tt)
; #pragma unroll
;                 for (int e = 0; e < 4; ++e) { const float pe = __expf(S[cc][tt][e] - mx); S[cc][tt][e] = pe; den += pe; }
	v_mfma_f32_16x16x32_bf16 v[28:31], v[222:225], v[4:7], v[32:35]
	s_nop 2
	s_nop 0
	ds_read_b128 v[126:129], v91 offset:21952
	s_waitcnt lgkmcnt(15)
	v_mfma_f32_16x16x32_bf16 v[32:35], v[226:229], v[4:7], v[36:39]
	s_nop 2
	s_nop 0
	ds_read_b128 v[130:133], v91 offset:26304
	s_waitcnt lgkmcnt(15)
	v_mfma_f32_16x16x32_bf16 v[134:137], v[230:233], v[4:7], v[40:43]
	s_nop 0
	ds_read_b128 v[138:141], v91 offset:30656
	s_waitcnt lgkmcnt(15)
	v_mfma_f32_16x16x32_bf16 v[142:145], v[234:237], v[4:7], v[44:47]
	s_nop 0
	ds_read_b128 v[146:149], v91 offset:35008
	s_waitcnt lgkmcnt(15)
	v_mfma_f32_16x16x32_bf16 v[150:153], v[242:245], v[4:7], v[48:51]
	s_nop 0
	ds_read_b128 v[154:157], v91 offset:39360
	s_waitcnt lgkmcnt(15)
	v_mfma_f32_16x16x32_bf16 v[158:161], v[246:249], v[4:7], v[52:55]
	s_nop 0
	ds_read_b128 v[162:165], v91 offset:43712
	s_waitcnt lgkmcnt(12)
	v_mfma_f32_16x16x32_bf16 v[166:169], v[186:189], v[4:7], v[56:59]
	s_nop 0
	ds_read_b128 v[170:173], v91 offset:48064
	s_waitcnt lgkmcnt(12)
	v_mfma_f32_16x16x32_bf16 v[174:177], v[190:193], v[4:7], v[60:63]
	s_nop 0
	ds_read_b128 v[178:181], v91 offset:52416
	s_waitcnt lgkmcnt(12)
	v_mfma_f32_16x16x32_bf16 v[182:185], v[194:197], v[4:7], v[64:67]
	s_nop 0
	ds_read_b128 v[72:75], v91 offset:56768
	s_waitcnt lgkmcnt(12)
	v_mfma_f32_16x16x32_bf16 v[76:79], v[198:201], v[4:7], v[68:71]
	s_nop 0
	ds_read_b128 v[64:67], v91 offset:61120
	s_waitcnt lgkmcnt(12)
	v_mfma_f32_16x16x32_bf16 v[68:71], v[202:205], v[4:7], v[102:105]
	s_nop 0
	ds_read_b128 v[56:59], v91 offset:65472
	v_lshrrev_b32_e32 v91, 2, v90
	s_waitcnt lgkmcnt(12)
	v_mfma_f32_16x16x32_bf16 v[60:63], v[206:209], v[4:7], v[8:11]
	v_mfma_f32_16x16x32_bf16 v[52:55], v[106:109], v[0:3], v[12:15]
	v_mfma_f32_16x16x32_bf16 v[48:51], v[110:113], v[0:3], v[16:19]
	v_mfma_f32_16x16x32_bf16 v[44:47], v[114:117], v[0:3], v[20:23]
	v_mfma_f32_16x16x32_bf16 v[40:43], v[118:121], v[0:3], v[24:27]
	v_mfma_f32_16x16x32_bf16 v[36:39], v[122:125], v[0:3], v[28:31]
	v_mfma_f32_16x16x32_bf16 v[32:35], v[126:129], v[0:3], v[32:35]
	v_mfma_f32_16x16x32_bf16 v[28:31], v[130:133], v[0:3], v[134:137]
	v_mfma_f32_16x16x32_bf16 v[24:27], v[138:141], v[0:3], v[142:145]
	v_mfma_f32_16x16x32_bf16 v[20:23], v[146:149], v[0:3], v[150:153]
	v_mfma_f32_16x16x32_bf16 v[16:19], v[154:157], v[0:3], v[158:161]
	v_mfma_f32_16x16x32_bf16 v[12:15], v[162:165], v[0:3], v[166:169]
	v_mfma_f32_16x16x32_bf16 v[8:11], v[170:173], v[0:3], v[174:177]
	v_mfma_f32_16x16x32_bf16 v[4:7], v[178:181], v[0:3], v[182:185]
	v_mfma_f32_16x16x32_bf16 v[72:75], v[72:75], v[0:3], v[76:79]
	v_mfma_f32_16x16x32_bf16 v[66:69], v[64:67], v[0:3], v[68:71]
	s_nop 1
	v_lshlrev_b32_e32 v76, 3, v90
	v_add_u32_e32 v77, v91, v92
	v_and_b32_e32 v76, 24, v76
	s_waitcnt lgkmcnt(0)
	v_mfma_f32_16x16x32_bf16 v[0:3], v[56:59], v[0:3], v[60:63]
	v_max3_f32 v56, v52, s33, v53
	v_max3_f32 v56, v56, v54, v55
	v_max3_f32 v56, v56, v48, v49
	v_max3_f32 v56, v56, v50, v51
	v_max3_f32 v56, v56, v44, v45
	v_max3_f32 v56, v56, v46, v47
	v_max3_f32 v56, v56, v40, v41
	v_max3_f32 v56, v56, v42, v43
	v_max3_f32 v56, v56, v36, v37
	v_max3_f32 v56, v56, v38, v39
	v_max3_f32 v56, v56, v32, v33
	v_max3_f32 v56, v56, v34, v35
	v_max3_f32 v56, v56, v28, v29
	v_max3_f32 v56, v56, v30, v31
	v_max3_f32 v56, v56, v24, v25
	v_max3_f32 v56, v56, v26, v27
	v_max3_f32 v56, v56, v20, v21
	v_max3_f32 v56, v56, v22, v23
	v_max3_f32 v56, v56, v16, v17
	v_max3_f32 v56, v56, v18, v19
	v_max3_f32 v56, v56, v12, v13
	v_max3_f32 v56, v56, v14, v15
	v_max3_f32 v56, v56, v8, v9
	v_max3_f32 v56, v56, v10, v11
	v_max3_f32 v56, v56, v4, v5
	v_max3_f32 v56, v56, v6, v7
	v_max3_f32 v56, v56, v72, v73
	v_max3_f32 v56, v56, v74, v75
	v_max3_f32 v56, v56, v66, v67
	v_max3_f32 v56, v56, v68, v69
	v_max3_f32 v56, v56, v0, v1
	v_max3_f32 v56, v56, v2, v3
	ds_bpermute_b32 v57, v82, v56
	v_mul_lo_u32 v64, v77, s30
	v_add3_u32 v64, s90, v76, v64
	s_waitcnt lgkmcnt(0)
	v_max_f32_e32 v57, v57, v57
	v_max_f32_e32 v56, v56, v57
	ds_bpermute_b32 v57, v100, v56
	s_waitcnt lgkmcnt(0)
	v_max_f32_e32 v57, v57, v57
	v_max_f32_e32 v56, v56, v57
	v_sub_f32_e32 v52, v52, v56
	v_sub_f32_e32 v53, v53, v56
	v_mul_f32_e32 v52, 0x3fb8aa3b, v52
	v_sub_f32_e32 v54, v54, v56
	v_sub_f32_e32 v57, v72, v56
	v_sub_f32_e32 v58, v73, v56
	v_sub_f32_e32 v59, v74, v56
	v_sub_f32_e32 v60, v75, v56
	v_sub_f32_e32 v61, v66, v56
	v_sub_f32_e32 v62, v67, v56
	v_sub_f32_e32 v63, v68, v56
	v_sub_f32_e32 v65, v69, v56
	v_mul_f32_e32 v53, 0x3fb8aa3b, v53
	v_exp_f32_e32 v52, v52
	v_sub_f32_e32 v55, v55, v56
	v_sub_f32_e32 v48, v48, v56
	v_sub_f32_e32 v49, v49, v56
	v_sub_f32_e32 v50, v50, v56
	v_sub_f32_e32 v51, v51, v56
	v_sub_f32_e32 v44, v44, v56
	v_sub_f32_e32 v45, v45, v56
	v_sub_f32_e32 v46, v46, v56
	v_sub_f32_e32 v47, v47, v56
	v_sub_f32_e32 v40, v40, v56
	v_sub_f32_e32 v41, v41, v56
	v_sub_f32_e32 v42, v42, v56
	v_sub_f32_e32 v43, v43, v56
	v_sub_f32_e32 v36, v36, v56
	v_sub_f32_e32 v37, v37, v56
	v_sub_f32_e32 v38, v38, v56
	v_sub_f32_e32 v39, v39, v56
	v_sub_f32_e32 v32, v32, v56
	v_sub_f32_e32 v33, v33, v56
	v_sub_f32_e32 v34, v34, v56
	v_sub_f32_e32 v35, v35, v56
	v_sub_f32_e32 v28, v28, v56
	v_sub_f32_e32 v29, v29, v56
	v_sub_f32_e32 v30, v30, v56
	v_sub_f32_e32 v31, v31, v56
	v_sub_f32_e32 v24, v24, v56
	v_sub_f32_e32 v25, v25, v56
	v_sub_f32_e32 v26, v26, v56
	v_sub_f32_e32 v27, v27, v56
	v_sub_f32_e32 v20, v20, v56
	v_sub_f32_e32 v21, v21, v56
	v_sub_f32_e32 v22, v22, v56
	v_sub_f32_e32 v23, v23, v56
	v_sub_f32_e32 v16, v16, v56
	v_sub_f32_e32 v17, v17, v56
	v_sub_f32_e32 v18, v18, v56
	v_sub_f32_e32 v19, v19, v56
	v_sub_f32_e32 v12, v12, v56
	v_sub_f32_e32 v13, v13, v56
; #define LAS __attribute__((address_space(3)))
; __device__ __forceinline__ bf16x8 pack8(const float (&o)[8]) { v4u w; w.x = pk2(o[0], o[1]); w.y = pk2(o[2], o[3]); w.z = pk2(o[4], o[5]); w.w = pk2(o[6], o[7]); return __builtin_bit_cast(bf16x8, w); }
; __device__ __forceinline__ v2u vtr(const LAS bf16* p) { return __builtin_bit_cast(v2u, __builtin_amdgcn_ds_read_tr16_b64_v4i16((LAS v4i16_t*)p)); }
; template <bool SAMPLE>
; __device__ __forceinline__ void mem_unit(const Params& p, int l, LAS unsigned char* lds, int unit, int tid, int wave, int lane) {
;     ...
;         float den = 0.f;
; #pragma unroll
;         for (int cc = 0; cc < 8; ++cc)
; #pragma unroll
;             for (int tt = 0; tt < 2; ++tt)
; #pragma unroll
;                 for (int e = 0; e < 4; ++e) { const float pe = __expf(S[cc][tt][e] - mx); S[cc][tt][e] = pe; den += pe; }
;         den += __shfl_xor(den, 16); den += __shfl_xor(den, 32);
;         const float rden = 1.f / den;
;         bf16x8 pf[8];
; #pragma unroll
;         for (int cc = 0; cc < 8; ++cc) { float t8[8];
; #pragma unroll
;             for (int e = 0; e < 4; ++e) { t8[e] = S[cc][0][e]; t8[4 + e] = S[cc][1][e]; }
;             pf[cc] = pack8(t8); }
; #pragma unroll
;         for (int dt = 0; dt < 8; ++dt) { f32x4 o = (f32x4){0.f, 0.f, 0.f, 0.f};
; #pragma unroll
;             for (int cc = 0; cc < 8; ++cc) { const LAS bf16* vp = Vt + (32 * cc + 4 * kq + (q16 >> 2)) * MEM_VS + 16 * dt + 4 * (q16 & 3);
;                 const v2u lo = vtr(vp), hi = vtr(vp + 16 * MEM_VS);
	v_sub_f32_e32 v14, v14, v56
	v_sub_f32_e32 v15, v15, v56
	v_sub_f32_e32 v8, v8, v56
	v_sub_f32_e32 v9, v9, v56
	v_sub_f32_e32 v10, v10, v56
	v_sub_f32_e32 v11, v11, v56
	v_sub_f32_e32 v4, v4, v56
	v_sub_f32_e32 v5, v5, v56
	v_sub_f32_e32 v6, v6, v56
	v_sub_f32_e32 v7, v7, v56
	v_sub_f32_e32 v0, v0, v56
	v_sub_f32_e32 v1, v1, v56
	v_sub_f32_e32 v2, v2, v56
	v_sub_f32_e32 v3, v3, v56
	v_mul_f32_e32 v54, 0x3fb8aa3b, v54
	v_mul_f32_e32 v56, 0x3fb8aa3b, v57
	v_mul_f32_e32 v57, 0x3fb8aa3b, v58
	v_mul_f32_e32 v58, 0x3fb8aa3b, v59
	v_mul_f32_e32 v59, 0x3fb8aa3b, v60
	v_mul_f32_e32 v60, 0x3fb8aa3b, v61
	v_mul_f32_e32 v61, 0x3fb8aa3b, v62
	v_mul_f32_e32 v62, 0x3fb8aa3b, v63
	v_mul_f32_e32 v63, 0x3fb8aa3b, v65
	v_exp_f32_e32 v65, v53
	v_mul_f32_e32 v55, 0x3fb8aa3b, v55
	v_exp_f32_e32 v66, v54
	v_mul_f32_e32 v48, 0x3fb8aa3b, v48
	v_exp_f32_e32 v67, v55
	v_mul_f32_e32 v49, 0x3fb8aa3b, v49
	v_mul_f32_e32 v0, 0x3fb8aa3b, v0
	v_exp_f32_e32 v68, v48
	v_add_f32_e32 v147, 0, v52
	v_mul_f32_e32 v50, 0x3fb8aa3b, v50
	v_exp_f32_e32 v69, v49
	v_exp_f32_e32 v143, v0
	v_cvt_pk_bf16_f32 v0, v52, v65
	v_add_f32_e32 v65, v65, v147
	v_mul_f32_e32 v51, 0x3fb8aa3b, v51
	v_exp_f32_e32 v70, v50
	v_add_f32_e32 v65, v66, v65
	v_mul_f32_e32 v44, 0x3fb8aa3b, v44
	v_exp_f32_e32 v71, v51
	v_add_f32_e32 v65, v67, v65
	v_mul_f32_e32 v45, 0x3fb8aa3b, v45
	v_exp_f32_e32 v72, v44
	v_add_f32_e32 v65, v68, v65
	v_mul_f32_e32 v46, 0x3fb8aa3b, v46
	v_exp_f32_e32 v73, v45
	v_add_f32_e32 v65, v69, v65
	v_mul_f32_e32 v47, 0x3fb8aa3b, v47
	v_exp_f32_e32 v74, v46
	v_add_f32_e32 v65, v70, v65
	v_mul_f32_e32 v40, 0x3fb8aa3b, v40
	v_exp_f32_e32 v75, v47
	v_add_f32_e32 v65, v71, v65
	v_mul_f32_e32 v41, 0x3fb8aa3b, v41
	v_mul_f32_e32 v42, 0x3fb8aa3b, v42
	v_mul_f32_e32 v43, 0x3fb8aa3b, v43
	v_mul_f32_e32 v36, 0x3fb8aa3b, v36
	v_mul_f32_e32 v37, 0x3fb8aa3b, v37
	v_mul_f32_e32 v38, 0x3fb8aa3b, v38
	v_mul_f32_e32 v39, 0x3fb8aa3b, v39
	v_mul_f32_e32 v32, 0x3fb8aa3b, v32
	v_mul_f32_e32 v33, 0x3fb8aa3b, v33
	v_mul_f32_e32 v34, 0x3fb8aa3b, v34
	v_mul_f32_e32 v35, 0x3fb8aa3b, v35
	v_mul_f32_e32 v28, 0x3fb8aa3b, v28
	v_mul_f32_e32 v29, 0x3fb8aa3b, v29
	v_mul_f32_e32 v30, 0x3fb8aa3b, v30
	v_mul_f32_e32 v31, 0x3fb8aa3b, v31
	v_mul_f32_e32 v24, 0x3fb8aa3b, v24
	v_mul_f32_e32 v25, 0x3fb8aa3b, v25
	v_mul_f32_e32 v26, 0x3fb8aa3b, v26
	v_mul_f32_e32 v27, 0x3fb8aa3b, v27
	v_mul_f32_e32 v20, 0x3fb8aa3b, v20
	v_mul_f32_e32 v21, 0x3fb8aa3b, v21
	v_mul_f32_e32 v22, 0x3fb8aa3b, v22
	v_mul_f32_e32 v23, 0x3fb8aa3b, v23
	v_mul_f32_e32 v16, 0x3fb8aa3b, v16
	v_mul_f32_e32 v17, 0x3fb8aa3b, v17
	v_mul_f32_e32 v18, 0x3fb8aa3b, v18
	v_mul_f32_e32 v19, 0x3fb8aa3b, v19
	v_mul_f32_e32 v12, 0x3fb8aa3b, v12
	v_mul_f32_e32 v13, 0x3fb8aa3b, v13
	v_mul_f32_e32 v14, 0x3fb8aa3b, v14
	v_mul_f32_e32 v15, 0x3fb8aa3b, v15
	v_mul_f32_e32 v8, 0x3fb8aa3b, v8
	v_mul_f32_e32 v9, 0x3fb8aa3b, v9
	v_mul_f32_e32 v10, 0x3fb8aa3b, v10
	v_mul_f32_e32 v11, 0x3fb8aa3b, v11
	v_mul_f32_e32 v4, 0x3fb8aa3b, v4
	v_mul_f32_e32 v5, 0x3fb8aa3b, v5
	v_mul_f32_e32 v6, 0x3fb8aa3b, v6
	v_mul_f32_e32 v7, 0x3fb8aa3b, v7
	v_mul_f32_e32 v1, 0x3fb8aa3b, v1
	v_mul_f32_e32 v2, 0x3fb8aa3b, v2
	v_mul_f32_e32 v3, 0x3fb8aa3b, v3
	v_exp_f32_e32 v76, v40
	v_add_f32_e32 v65, v72, v65
	v_exp_f32_e32 v77, v41
	v_exp_f32_e32 v78, v42
	v_exp_f32_e32 v79, v43
	v_exp_f32_e32 v90, v36
	v_exp_f32_e32 v91, v37
	v_exp_f32_e32 v101, v38
	v_exp_f32_e32 v102, v39
	v_exp_f32_e32 v103, v32
	v_exp_f32_e32 v104, v33
	v_exp_f32_e32 v105, v34
	v_exp_f32_e32 v106, v35
	v_exp_f32_e32 v107, v28
	v_exp_f32_e32 v108, v29
	v_exp_f32_e32 v109, v30
	v_exp_f32_e32 v110, v31
	v_exp_f32_e32 v111, v24
	v_exp_f32_e32 v112, v25
	v_exp_f32_e32 v113, v26
	v_exp_f32_e32 v114, v27
	v_exp_f32_e32 v115, v20
	v_exp_f32_e32 v116, v21
	v_exp_f32_e32 v117, v22
	v_exp_f32_e32 v118, v23
	v_exp_f32_e32 v119, v16
	v_exp_f32_e32 v120, v17
	v_exp_f32_e32 v121, v18
	v_exp_f32_e32 v122, v19
	v_exp_f32_e32 v123, v12
	v_exp_f32_e32 v124, v13
	v_exp_f32_e32 v125, v14
	v_exp_f32_e32 v126, v15
	v_exp_f32_e32 v127, v8
	v_exp_f32_e32 v128, v9
	v_exp_f32_e32 v129, v10
	v_exp_f32_e32 v130, v11
	v_exp_f32_e32 v131, v4
	v_exp_f32_e32 v132, v5
	v_exp_f32_e32 v133, v6
	v_exp_f32_e32 v134, v7
	v_exp_f32_e32 v135, v56
	v_exp_f32_e32 v136, v57
	v_exp_f32_e32 v137, v58
	v_exp_f32_e32 v138, v59
	v_exp_f32_e32 v139, v60
	v_exp_f32_e32 v140, v61
	v_exp_f32_e32 v141, v62
	v_exp_f32_e32 v142, v63
	v_exp_f32_e32 v144, v1
	v_exp_f32_e32 v145, v2
	v_exp_f32_e32 v146, v3
	v_cvt_pk_bf16_f32 v1, v66, v67
	v_cvt_pk_bf16_f32 v2, v68, v69
	v_cvt_pk_bf16_f32 v3, v70, v71
	v_cvt_pk_bf16_f32 v4, v72, v73
	v_cvt_pk_bf16_f32 v5, v74, v75
	v_cvt_pk_bf16_f32 v6, v76, v77
	v_cvt_pk_bf16_f32 v7, v78, v79
	v_cvt_pk_bf16_f32 v8, v90, v91
	v_cvt_pk_bf16_f32 v9, v101, v102
	v_cvt_pk_bf16_f32 v10, v103, v104
	v_cvt_pk_bf16_f32 v11, v105, v106
	v_cvt_pk_bf16_f32 v12, v107, v108
	v_cvt_pk_bf16_f32 v13, v109, v110
	v_cvt_pk_bf16_f32 v14, v111, v112
	v_cvt_pk_bf16_f32 v15, v113, v114
	v_cvt_pk_bf16_f32 v16, v115, v116
	v_cvt_pk_bf16_f32 v17, v117, v118
	v_cvt_pk_bf16_f32 v18, v119, v120
	v_cvt_pk_bf16_f32 v19, v121, v122
	v_cvt_pk_bf16_f32 v24, v123, v124
	v_cvt_pk_bf16_f32 v25, v125, v126
	v_cvt_pk_bf16_f32 v26, v127, v128
	v_cvt_pk_bf16_f32 v27, v129, v130
	v_cvt_pk_bf16_f32 v28, v131, v132
	v_cvt_pk_bf16_f32 v29, v133, v134
	v_cvt_pk_bf16_f32 v30, v135, v136
	v_cvt_pk_bf16_f32 v31, v137, v138
	v_cvt_pk_bf16_f32 v20, v139, v140
	v_cvt_pk_bf16_f32 v21, v141, v142
	v_cvt_pk_bf16_f32 v22, v143, v144
	v_cvt_pk_bf16_f32 v23, v145, v146
	ds_read_b64_tr_b16 v[32:33], v64
	ds_read_b64_tr_b16 v[34:35], v64 offset:4352
	ds_read_b64_tr_b16 v[36:37], v64 offset:8704
	ds_read_b64_tr_b16 v[38:39], v64 offset:13056
	ds_read_b64_tr_b16 v[40:41], v64 offset:17408
	ds_read_b64_tr_b16 v[42:43], v64 offset:21760
	ds_read_b64_tr_b16 v[44:45], v64 offset:26112
	ds_read_b64_tr_b16 v[46:47], v64 offset:30464
	ds_read_b64_tr_b16 v[48:49], v64 offset:34816
	ds_read_b64_tr_b16 v[50:51], v64 offset:39168
	ds_read_b64_tr_b16 v[52:53], v64 offset:43520
	ds_read_b64_tr_b16 v[54:55], v64 offset:47872
	ds_read_b64_tr_b16 v[56:57], v64 offset:52224
	ds_read_b64_tr_b16 v[58:59], v64 offset:56576
	ds_read_b64_tr_b16 v[60:61], v64 offset:60928
	ds_read_b64_tr_b16 v[62:63], v64 offset:65280
	v_add_f32_e32 v65, v73, v65
	s_waitcnt lgkmcnt(14)
; #define LAS __attribute__((address_space(3)))
; __device__ __forceinline__ unsigned pk2(float lo, float hi) { return pg8::cvt_pk_bf16(lo, hi); }
; __device__ __forceinline__ bf16x8 pack8(const float (&o)[8]) { v4u w; w.x = pk2(o[0], o[1]); w.y = pk2(o[2], o[3]); w.z = pk2(o[4], o[5]); w.w = pk2(o[6], o[7]); return __builtin_bit_cast(bf16x8, w); }
; __device__ __forceinline__ v2u vtr(const LAS bf16* p) { return __builtin_bit_cast(v2u, __builtin_amdgcn_ds_read_tr16_b64_v4i16((LAS v4i16_t*)p)); }
; template <bool SAMPLE>
; __device__ __forceinline__ void mem_unit(const Params& p, int l, LAS unsigned char* lds, int unit, int tid, int wave, int lane) {
;     ...
;         den += __shfl_xor(den, 16); den += __shfl_xor(den, 32);
;         const float rden = 1.f / den;
;         bf16x8 pf[8];
; #pragma unroll
;         for (int cc = 0; cc < 8; ++cc) { float t8[8];
; #pragma unroll
;             for (int e = 0; e < 4; ++e) { t8[e] = S[cc][0][e]; t8[4 + e] = S[cc][1][e]; }
;             pf[cc] = pack8(t8); }
; #pragma unroll
;         for (int dt = 0; dt < 8; ++dt) { f32x4 o = (f32x4){0.f, 0.f, 0.f, 0.f};
; #pragma unroll
;             for (int cc = 0; cc < 8; ++cc) { const LAS bf16* vp = Vt + (32 * cc + 4 * kq + (q16 >> 2)) * MEM_VS + 16 * dt + 4 * (q16 & 3);
;                 const v2u lo = vtr(vp), hi = vtr(vp + 16 * MEM_VS);
;                 v4u av; av.x = lo.x; av.y = lo.y; av.z = hi.x; av.w = hi.y;
;                 o = __builtin_amdgcn_mfma_f32_16x16x32_bf16(__builtin_bit_cast(bf16x8, av), pf[cc], o, 0, 0, 0); }
;             if (st) { v2u w; w.x = pk2(o[0] * rden, o[1] * rden); w.y = pk2(o[2] * rden, o[3] * rden);
;                 *(v2u*)(MO + row * 512 + h * 128 + 16 * dt + 4 * kq) = w; } }
	v_mfma_f32_16x16x32_bf16 v[32:35], v[32:35], v[0:3], 0
	v_add_f32_e32 v65, v74, v65
	v_add_f32_e32 v65, v75, v65
	v_add_f32_e32 v65, v76, v65
	v_add_f32_e32 v65, v77, v65
	s_waitcnt lgkmcnt(12)
	v_mfma_f32_16x16x32_bf16 v[32:35], v[36:39], v[4:7], v[32:35]
	v_add_f32_e32 v36, v78, v65
	v_add_f32_e32 v36, v79, v36
	v_add_f32_e32 v36, v90, v36
	v_add_f32_e32 v36, v91, v36
	s_waitcnt lgkmcnt(10)
	v_mfma_f32_16x16x32_bf16 v[32:35], v[40:43], v[8:11], v[32:35]
	v_add_f32_e32 v36, v101, v36
	v_add_f32_e32 v36, v102, v36
	v_add_f32_e32 v36, v103, v36
	v_add_f32_e32 v36, v104, v36
	s_waitcnt lgkmcnt(8)
	v_mfma_f32_16x16x32_bf16 v[32:35], v[44:47], v[12:15], v[32:35]
	v_add_f32_e32 v36, v105, v36
	v_add_f32_e32 v36, v106, v36
	v_add_f32_e32 v36, v107, v36
	v_add_f32_e32 v36, v108, v36
	s_waitcnt lgkmcnt(6)
	ds_read_b64_tr_b16 v[186:187], v64 offset:52256
	ds_read_b64_tr_b16 v[188:189], v64 offset:56608
	ds_read_b64_tr_b16 v[190:191], v64 offset:60960
	ds_read_b64_tr_b16 v[192:193], v64 offset:65312
	ds_read_b64_tr_b16 v[194:195], v64 offset:64
	ds_read_b64_tr_b16 v[196:197], v64 offset:4416
	ds_read_b64_tr_b16 v[198:199], v64 offset:8768
	ds_read_b64_tr_b16 v[200:201], v64 offset:13120
	ds_read_b64_tr_b16 v[202:203], v64 offset:17472
	ds_read_b64_tr_b16 v[204:205], v64 offset:21824
	ds_read_b64_tr_b16 v[206:207], v64 offset:26176
	ds_read_b64_tr_b16 v[208:209], v64 offset:30528
	ds_read_b64_tr_b16 v[210:211], v64 offset:34880
	ds_read_b64_tr_b16 v[212:213], v64 offset:39232
	v_mfma_f32_16x16x32_bf16 v[32:35], v[48:51], v[16:19], v[32:35]
	v_add_f32_e32 v36, v109, v36
	v_add_f32_e32 v36, v110, v36
	v_add_f32_e32 v36, v111, v36
	v_add_f32_e32 v36, v112, v36
	s_waitcnt lgkmcnt(15)
	v_mfma_f32_16x16x32_bf16 v[32:35], v[52:55], v[24:27], v[32:35]
	v_add_f32_e32 v36, v113, v36
	v_add_f32_e32 v36, v114, v36
	v_add_f32_e32 v36, v115, v36
	v_add_f32_e32 v36, v116, v36
	s_waitcnt lgkmcnt(15)
	v_mfma_f32_16x16x32_bf16 v[32:35], v[56:59], v[28:31], v[32:35]
	v_add_f32_e32 v36, v117, v36
	v_add_f32_e32 v36, v118, v36
	v_add_f32_e32 v36, v119, v36
	v_add_f32_e32 v40, v120, v36
	s_waitcnt lgkmcnt(14)
	v_mfma_f32_16x16x32_bf16 v[36:39], v[60:63], v[20:23], v[32:35]
	s_nop 2
	v_add_f32_e32 v32, v121, v40
	v_add_f32_e32 v32, v122, v32
	v_add_f32_e32 v32, v123, v32
	v_add_f32_e32 v32, v124, v32
	v_add_f32_e32 v32, v125, v32
	v_add_f32_e32 v32, v126, v32
	v_add_f32_e32 v32, v127, v32
	v_add_f32_e32 v32, v128, v32
	v_add_f32_e32 v32, v129, v32
	v_add_f32_e32 v32, v130, v32
	v_add_f32_e32 v32, v131, v32
	v_add_f32_e32 v32, v132, v32
	v_add_f32_e32 v32, v133, v32
	v_add_f32_e32 v32, v134, v32
	v_add_f32_e32 v32, v135, v32
	v_add_f32_e32 v32, v136, v32
	v_add_f32_e32 v32, v137, v32
	v_add_f32_e32 v32, v138, v32
	v_add_f32_e32 v32, v139, v32
	v_add_f32_e32 v32, v140, v32
	v_add_f32_e32 v32, v141, v32
	v_add_f32_e32 v32, v142, v32
	v_add_f32_e32 v32, v143, v32
	v_add_f32_e32 v32, v144, v32
	v_add_f32_e32 v32, v145, v32
	v_add_f32_e32 v32, v146, v32
	ds_bpermute_b32 v33, v82, v32
	s_waitcnt lgkmcnt(0)
	v_add_f32_e32 v32, v32, v33
	ds_bpermute_b32 v33, v100, v32
	s_waitcnt lgkmcnt(0)
	v_add_f32_e32 v32, v32, v33
	v_div_scale_f32 v33, s[16:17], v32, v32, 1.0
	v_rcp_f32_e32 v35, v33
	v_div_scale_f32 v34, vcc, 1.0, v32, 1.0
	v_fma_f32 v40, -v33, v35, 1.0
	v_fmac_f32_e32 v35, v40, v35
	v_mul_f32_e32 v40, v34, v35
	v_fma_f32 v41, -v33, v40, v34
	v_fmac_f32_e32 v40, v41, v35
	v_fma_f32 v33, -v33, v40, v34
	v_div_fmas_f32 v33, v33, v35, v40
	v_div_fixup_f32 v34, v33, v32, 1.0
	v_mul_f32_e32 v32, v36, v34
	v_mul_f32_e32 v36, v39, v34
	v_mul_f32_e32 v33, v37, v34
	v_mul_f32_e32 v35, v38, v34
	v_cvt_pk_bf16_f32 v52, v32, v33
	v_cvt_pk_bf16_f32 v53, v35, v36
	ds_read_b64_tr_b16 v[36:37], v64 offset:32
	ds_read_b64_tr_b16 v[38:39], v64 offset:4384
	ds_read_b64_tr_b16 v[40:41], v64 offset:8736
	ds_read_b64_tr_b16 v[42:43], v64 offset:13088
	ds_read_b64_tr_b16 v[44:45], v64 offset:17440
	s_waitcnt lgkmcnt(3)
	v_mfma_f32_16x16x32_bf16 v[36:39], v[36:39], v[0:3], 0
	ds_read_b64_tr_b16 v[46:47], v64 offset:21792
	ds_read_b64_tr_b16 v[48:49], v64 offset:26144
	v_lshl_add_u64 v[32:33], s[2:3], 0, v[88:89]
	v_lshl_add_u64 v[32:33], v[92:93], 1, v[32:33]
	s_waitcnt lgkmcnt(3)
	v_mfma_f32_16x16x32_bf16 v[36:39], v[40:43], v[4:7], v[36:39]
	ds_read_b64_tr_b16 v[50:51], v64 offset:30496
	ds_read_b64_tr_b16 v[40:41], v64 offset:34848
	s_waitcnt lgkmcnt(3)
	v_mfma_f32_16x16x32_bf16 v[36:39], v[44:47], v[8:11], v[36:39]
	ds_read_b64_tr_b16 v[42:43], v64 offset:39200
	ds_read_b64_tr_b16 v[44:45], v64 offset:43552
	s_waitcnt lgkmcnt(3)
	v_mfma_f32_16x16x32_bf16 v[36:39], v[48:51], v[12:15], v[36:39]
	ds_read_b64_tr_b16 v[46:47], v64 offset:47904
	s_nop 0
	s_waitcnt lgkmcnt(2)
	v_mfma_f32_16x16x32_bf16 v[36:39], v[40:43], v[16:19], v[36:39]
	s_nop 2
	global_store_dwordx2 v[32:33], v[52:53], off
	s_waitcnt lgkmcnt(0)
	v_mfma_f32_16x16x32_bf16 v[36:39], v[44:47], v[24:27], v[36:39]
	s_nop 0
	ds_read_b64_tr_b16 v[218:219], v64 offset:43584
	ds_read_b64_tr_b16 v[220:221], v64 offset:47936
	ds_read_b64_tr_b16 v[222:223], v64 offset:52288
	ds_read_b64_tr_b16 v[224:225], v64 offset:56640
	ds_read_b64_tr_b16 v[226:227], v64 offset:60992
	ds_read_b64_tr_b16 v[228:229], v64 offset:65344
	ds_read_b64_tr_b16 v[230:231], v64 offset:96
	ds_read_b64_tr_b16 v[232:233], v64 offset:4448
	ds_read_b64_tr_b16 v[234:235], v64 offset:8800
	ds_read_b64_tr_b16 v[236:237], v64 offset:13152
	ds_read_b64_tr_b16 v[242:243], v64 offset:17504
	ds_read_b64_tr_b16 v[244:245], v64 offset:21856
	ds_read_b64_tr_b16 v[246:247], v64 offset:26208
	ds_read_b64_tr_b16 v[248:249], v64 offset:30560
	v_mfma_f32_16x16x32_bf16 v[36:39], v[186:189], v[28:31], v[36:39]
	s_nop 0
	v_mfma_f32_16x16x32_bf16 v[36:39], v[190:193], v[20:23], v[36:39]
	s_nop 7
	v_mul_f32_e32 v35, v34, v36
	v_mul_f32_e32 v36, v34, v37
	v_mul_f32_e32 v37, v34, v38
	v_mul_f32_e32 v38, v34, v39
	v_cvt_pk_bf16_f32 v52, v35, v36
	v_cvt_pk_bf16_f32 v53, v37, v38
	s_nop 5
	v_mfma_f32_16x16x32_bf16 v[36:39], v[194:197], v[0:3], 0
	s_nop 2
	v_mfma_f32_16x16x32_bf16 v[36:39], v[198:201], v[4:7], v[36:39]
	s_nop 2
	v_mfma_f32_16x16x32_bf16 v[36:39], v[202:205], v[8:11], v[36:39]
	s_nop 2
	v_mfma_f32_16x16x32_bf16 v[36:39], v[206:209], v[12:15], v[36:39]
	s_nop 2
	v_mfma_f32_16x16x32_bf16 v[36:39], v[210:213], v[16:19], v[36:39]
	s_nop 2
	global_store_dwordx2 v[32:33], v[52:53], off offset:32
	s_waitcnt lgkmcnt(12)
; #define LAS __attribute__((address_space(3)))
; __device__ __forceinline__ unsigned pk2(float lo, float hi) { return pg8::cvt_pk_bf16(lo, hi); }
; __device__ __forceinline__ v2u vtr(const LAS bf16* p) { return __builtin_bit_cast(v2u, __builtin_amdgcn_ds_read_tr16_b64_v4i16((LAS v4i16_t*)p)); }
; template <bool SAMPLE>
; __device__ __forceinline__ void mem_unit(const Params& p, int l, LAS unsigned char* lds, int unit, int tid, int wave, int lane) {
;     ...
; #pragma unroll
;         for (int dt = 0; dt < 8; ++dt) { f32x4 o = (f32x4){0.f, 0.f, 0.f, 0.f};
; #pragma unroll
;             for (int cc = 0; cc < 8; ++cc) { const LAS bf16* vp = Vt + (32 * cc + 4 * kq + (q16 >> 2)) * MEM_VS + 16 * dt + 4 * (q16 & 3);
;                 const v2u lo = vtr(vp), hi = vtr(vp + 16 * MEM_VS);
;                 v4u av; av.x = lo.x; av.y = lo.y; av.z = hi.x; av.w = hi.y;
;                 o = __builtin_amdgcn_mfma_f32_16x16x32_bf16(__builtin_bit_cast(bf16x8, av), pf[cc], o, 0, 0, 0); }
;             if (st) { v2u w; w.x = pk2(o[0] * rden, o[1] * rden); w.y = pk2(o[2] * rden, o[3] * rden);
;                 *(v2u*)(MO + row * 512 + h * 128 + 16 * dt + 4 * kq) = w; } }
	ds_read_b64_tr_b16 v[186:187], v64 offset:34912
	ds_read_b64_tr_b16 v[188:189], v64 offset:39264
	ds_read_b64_tr_b16 v[190:191], v64 offset:43616
	ds_read_b64_tr_b16 v[192:193], v64 offset:47968
	ds_read_b64_tr_b16 v[194:195], v64 offset:52320
	ds_read_b64_tr_b16 v[196:197], v64 offset:56672
	ds_read_b64_tr_b16 v[198:199], v64 offset:61024
	ds_read_b64_tr_b16 v[200:201], v64 offset:65376
	ds_read_b64_tr_b16 v[202:203], v64 offset:128
	ds_read_b64_tr_b16 v[204:205], v64 offset:4480
	ds_read_b64_tr_b16 v[206:207], v64 offset:8832
	ds_read_b64_tr_b16 v[208:209], v64 offset:13184
	ds_read_b64_tr_b16 v[210:211], v64 offset:17536
	ds_read_b64_tr_b16 v[212:213], v64 offset:21888
	v_mfma_f32_16x16x32_bf16 v[36:39], v[218:221], v[24:27], v[36:39]
	s_waitcnt lgkmcnt(15)
	v_mfma_f32_16x16x32_bf16 v[36:39], v[222:225], v[28:31], v[36:39]
	s_waitcnt lgkmcnt(15)
	v_mfma_f32_16x16x32_bf16 v[36:39], v[226:229], v[20:23], v[36:39]
	s_nop 7
	v_mul_f32_e32 v35, v34, v36
	v_mul_f32_e32 v36, v34, v37
	v_mul_f32_e32 v37, v34, v38
	v_mul_f32_e32 v38, v34, v39
	v_cvt_pk_bf16_f32 v52, v35, v36
	v_cvt_pk_bf16_f32 v53, v37, v38
	s_nop 4
	s_waitcnt lgkmcnt(15)
	v_mfma_f32_16x16x32_bf16 v[36:39], v[230:233], v[0:3], 0
	s_nop 1
	s_waitcnt lgkmcnt(15)
	v_mfma_f32_16x16x32_bf16 v[36:39], v[234:237], v[4:7], v[36:39]
	s_nop 1
	s_waitcnt lgkmcnt(15)
	v_mfma_f32_16x16x32_bf16 v[36:39], v[242:245], v[8:11], v[36:39]
	s_nop 1
	s_waitcnt lgkmcnt(14)
	v_mfma_f32_16x16x32_bf16 v[36:39], v[246:249], v[12:15], v[36:39]
	s_nop 1
	s_waitcnt lgkmcnt(12)
	ds_read_b64_tr_b16 v[218:219], v64 offset:26240
	ds_read_b64_tr_b16 v[220:221], v64 offset:30592
	ds_read_b64_tr_b16 v[222:223], v64 offset:34944
	ds_read_b64_tr_b16 v[224:225], v64 offset:39296
	ds_read_b64_tr_b16 v[226:227], v64 offset:43648
	ds_read_b64_tr_b16 v[228:229], v64 offset:48000
	ds_read_b64_tr_b16 v[230:231], v64 offset:52352
	ds_read_b64_tr_b16 v[232:233], v64 offset:56704
	ds_read_b64_tr_b16 v[234:235], v64 offset:61056
	ds_read_b64_tr_b16 v[236:237], v64 offset:65408
	ds_read_b64_tr_b16 v[242:243], v64 offset:160
	ds_read_b64_tr_b16 v[244:245], v64 offset:4512
	ds_read_b64_tr_b16 v[246:247], v64 offset:8864
	ds_read_b64_tr_b16 v[248:249], v64 offset:13216
	v_mfma_f32_16x16x32_bf16 v[36:39], v[186:189], v[16:19], v[36:39]
	s_nop 2
	global_store_dwordx2 v[32:33], v[52:53], off offset:64
	s_waitcnt lgkmcnt(15)
	v_mfma_f32_16x16x32_bf16 v[36:39], v[190:193], v[24:27], v[36:39]
	s_waitcnt lgkmcnt(15)
	v_mfma_f32_16x16x32_bf16 v[36:39], v[194:197], v[28:31], v[36:39]
	s_waitcnt lgkmcnt(15)
	v_mfma_f32_16x16x32_bf16 v[36:39], v[198:201], v[20:23], v[36:39]
	s_nop 7
	v_mul_f32_e32 v35, v34, v36
	v_mul_f32_e32 v36, v34, v37
	v_mul_f32_e32 v37, v34, v38
	v_mul_f32_e32 v38, v34, v39
	v_cvt_pk_bf16_f32 v52, v35, v36
	v_cvt_pk_bf16_f32 v53, v37, v38
	s_nop 4
	s_waitcnt lgkmcnt(15)
	v_mfma_f32_16x16x32_bf16 v[36:39], v[202:205], v[0:3], 0
	s_nop 1
	s_waitcnt lgkmcnt(15)
	v_mfma_f32_16x16x32_bf16 v[36:39], v[206:209], v[4:7], v[36:39]
	s_nop 1
	s_waitcnt lgkmcnt(14)
	v_mfma_f32_16x16x32_bf16 v[36:39], v[210:213], v[8:11], v[36:39]
	s_nop 1
	s_waitcnt lgkmcnt(12)
	ds_read_b64_tr_b16 v[186:187], v64 offset:17568
	ds_read_b64_tr_b16 v[188:189], v64 offset:21920
	ds_read_b64_tr_b16 v[190:191], v64 offset:26272
	ds_read_b64_tr_b16 v[192:193], v64 offset:30624
	ds_read_b64_tr_b16 v[194:195], v64 offset:34976
	ds_read_b64_tr_b16 v[196:197], v64 offset:39328
	ds_read_b64_tr_b16 v[198:199], v64 offset:43680
	ds_read_b64_tr_b16 v[200:201], v64 offset:48032
	ds_read_b64_tr_b16 v[202:203], v64 offset:52384
	ds_read_b64_tr_b16 v[204:205], v64 offset:56736
	ds_read_b64_tr_b16 v[206:207], v64 offset:61088
	ds_read_b64_tr_b16 v[208:209], v64 offset:65440
	ds_read_b64_tr_b16 v[210:211], v64 offset:192
	ds_read_b64_tr_b16 v[212:213], v64 offset:4544
	v_mfma_f32_16x16x32_bf16 v[36:39], v[218:221], v[12:15], v[36:39]
	s_nop 1
	s_waitcnt lgkmcnt(15)
	v_mfma_f32_16x16x32_bf16 v[36:39], v[222:225], v[16:19], v[36:39]
	s_nop 2
	global_store_dwordx2 v[32:33], v[52:53], off offset:96
	s_waitcnt lgkmcnt(15)
	v_mfma_f32_16x16x32_bf16 v[36:39], v[226:229], v[24:27], v[36:39]
	s_waitcnt lgkmcnt(15)
	v_mfma_f32_16x16x32_bf16 v[36:39], v[230:233], v[28:31], v[36:39]
	s_waitcnt lgkmcnt(15)
	v_mfma_f32_16x16x32_bf16 v[36:39], v[234:237], v[20:23], v[36:39]
	s_nop 7
	v_mul_f32_e32 v35, v34, v36
	v_mul_f32_e32 v36, v34, v37
	v_mul_f32_e32 v37, v34, v38
	v_mul_f32_e32 v38, v34, v39
	v_cvt_pk_bf16_f32 v52, v35, v36
	v_cvt_pk_bf16_f32 v53, v37, v38
	s_nop 4
	s_waitcnt lgkmcnt(15)
; #define LAS __attribute__((address_space(3)))
; __device__ __forceinline__ unsigned pk2(float lo, float hi) { return pg8::cvt_pk_bf16(lo, hi); }
; __device__ __forceinline__ v2u vtr(const LAS bf16* p) { return __builtin_bit_cast(v2u, __builtin_amdgcn_ds_read_tr16_b64_v4i16((LAS v4i16_t*)p)); }
; template <bool SAMPLE>
; __device__ __forceinline__ void mem_unit(const Params& p, int l, LAS unsigned char* lds, int unit, int tid, int wave, int lane) {
;     ...
; #pragma unroll
;         for (int dt = 0; dt < 8; ++dt) { f32x4 o = (f32x4){0.f, 0.f, 0.f, 0.f};
; #pragma unroll
;             for (int cc = 0; cc < 8; ++cc) { const LAS bf16* vp = Vt + (32 * cc + 4 * kq + (q16 >> 2)) * MEM_VS + 16 * dt + 4 * (q16 & 3);
;                 const v2u lo = vtr(vp), hi = vtr(vp + 16 * MEM_VS);
;                 v4u av; av.x = lo.x; av.y = lo.y; av.z = hi.x; av.w = hi.y;
;                 o = __builtin_amdgcn_mfma_f32_16x16x32_bf16(__builtin_bit_cast(bf16x8, av), pf[cc], o, 0, 0, 0); }
;             if (st) { v2u w; w.x = pk2(o[0] * rden, o[1] * rden); w.y = pk2(o[2] * rden, o[3] * rden);
;                 *(v2u*)(MO + row * 512 + h * 128 + 16 * dt + 4 * kq) = w; } }
	v_mfma_f32_16x16x32_bf16 v[36:39], v[242:245], v[0:3], 0
	s_nop 1
	s_waitcnt lgkmcnt(14)
	v_mfma_f32_16x16x32_bf16 v[36:39], v[246:249], v[4:7], v[36:39]
	s_nop 1
	s_waitcnt lgkmcnt(12)
	ds_read_b64_tr_b16 v[218:219], v64 offset:8896
	ds_read_b64_tr_b16 v[220:221], v64 offset:13248
	ds_read_b64_tr_b16 v[222:223], v64 offset:17600
	ds_read_b64_tr_b16 v[224:225], v64 offset:21952
	ds_read_b64_tr_b16 v[226:227], v64 offset:26304
	ds_read_b64_tr_b16 v[228:229], v64 offset:30656
	ds_read_b64_tr_b16 v[230:231], v64 offset:35008
	ds_read_b64_tr_b16 v[232:233], v64 offset:39360
	ds_read_b64_tr_b16 v[234:235], v64 offset:43712
	ds_read_b64_tr_b16 v[236:237], v64 offset:48064
	ds_read_b64_tr_b16 v[242:243], v64 offset:61120
	ds_read_b64_tr_b16 v[244:245], v64 offset:65472
	ds_read_b64_tr_b16 v[246:247], v64 offset:224
	ds_read_b64_tr_b16 v[248:249], v64 offset:4576
	v_mfma_f32_16x16x32_bf16 v[36:39], v[186:189], v[8:11], v[36:39]
	s_nop 1
	s_waitcnt lgkmcnt(15)
	v_mfma_f32_16x16x32_bf16 v[36:39], v[190:193], v[12:15], v[36:39]
	s_nop 1
	s_waitcnt lgkmcnt(15)
	v_mfma_f32_16x16x32_bf16 v[36:39], v[194:197], v[16:19], v[36:39]
	s_nop 2
	global_store_dwordx2 v[32:33], v[52:53], off offset:128
	s_waitcnt lgkmcnt(15)
	v_mfma_f32_16x16x32_bf16 v[36:39], v[198:201], v[24:27], v[36:39]
	s_waitcnt lgkmcnt(15)
	v_mfma_f32_16x16x32_bf16 v[36:39], v[202:205], v[28:31], v[36:39]
	s_waitcnt lgkmcnt(15)
	v_mfma_f32_16x16x32_bf16 v[36:39], v[206:209], v[20:23], v[36:39]
	s_nop 7
	v_mul_f32_e32 v35, v34, v36
	v_mul_f32_e32 v36, v34, v37
	v_mul_f32_e32 v37, v34, v38
	v_mul_f32_e32 v38, v34, v39
	v_cvt_pk_bf16_f32 v52, v35, v36
	v_cvt_pk_bf16_f32 v53, v37, v38
	s_nop 4
	s_waitcnt lgkmcnt(14)
	v_mfma_f32_16x16x32_bf16 v[36:39], v[210:213], v[0:3], 0
	s_nop 1
	s_waitcnt lgkmcnt(12)
	ds_read_b64_tr_b16 v[186:187], v64 offset:35040
	ds_read_b64_tr_b16 v[188:189], v64 offset:39392
	v_mfma_f32_16x16x32_bf16 v[36:39], v[218:221], v[4:7], v[36:39]
	s_nop 1
	s_waitcnt lgkmcnt(12)
	v_mfma_f32_16x16x32_bf16 v[36:39], v[222:225], v[8:11], v[36:39]
	s_nop 1
	s_waitcnt lgkmcnt(10)
	v_mfma_f32_16x16x32_bf16 v[36:39], v[226:229], v[12:15], v[36:39]
	s_nop 0
	ds_read_b64_tr_b16 v[48:49], v64 offset:52416
	s_waitcnt lgkmcnt(9)
	v_mfma_f32_16x16x32_bf16 v[36:39], v[230:233], v[16:19], v[36:39]
	ds_read_b64_tr_b16 v[50:51], v64 offset:56768
	s_nop 1
	global_store_dwordx2 v[32:33], v[52:53], off offset:160
	s_waitcnt lgkmcnt(8)
	v_mfma_f32_16x16x32_bf16 v[36:39], v[234:237], v[24:27], v[36:39]
	s_waitcnt lgkmcnt(0)
	v_mfma_f32_16x16x32_bf16 v[36:39], v[48:51], v[28:31], v[36:39]
	s_nop 0
	v_mfma_f32_16x16x32_bf16 v[36:39], v[242:245], v[20:23], v[36:39]
	s_nop 7
	v_mul_f32_e32 v35, v34, v36
	v_mul_f32_e32 v36, v34, v37
	v_mul_f32_e32 v37, v34, v38
	v_mul_f32_e32 v38, v34, v39
	v_cvt_pk_bf16_f32 v48, v35, v36
	v_cvt_pk_bf16_f32 v49, v37, v38
	s_nop 1
	ds_read_b64_tr_b16 v[40:41], v64 offset:8928
	ds_read_b64_tr_b16 v[42:43], v64 offset:13280
	ds_read_b64_tr_b16 v[44:45], v64 offset:17632
	s_nop 0
	v_mfma_f32_16x16x32_bf16 v[0:3], v[246:249], v[0:3], 0
	ds_read_b64_tr_b16 v[46:47], v64 offset:21984
	ds_read_b64_tr_b16 v[36:37], v64 offset:26336
	s_waitcnt lgkmcnt(3)
	v_mfma_f32_16x16x32_bf16 v[0:3], v[40:43], v[4:7], v[0:3]
	ds_read_b64_tr_b16 v[38:39], v64 offset:30688
	s_nop 0
	s_waitcnt lgkmcnt(2)
	v_mfma_f32_16x16x32_bf16 v[0:3], v[44:47], v[8:11], v[0:3]
	s_nop 0
	ds_read_b64_tr_b16 v[8:9], v64 offset:43744
	s_waitcnt lgkmcnt(1)
	v_mfma_f32_16x16x32_bf16 v[0:3], v[36:39], v[12:15], v[0:3]
	ds_read_b64_tr_b16 v[10:11], v64 offset:48096
	ds_read_b64_tr_b16 v[12:13], v64 offset:52448
	s_nop 0
	v_mfma_f32_16x16x32_bf16 v[0:3], v[186:189], v[16:19], v[0:3]
	ds_read_b64_tr_b16 v[14:15], v64 offset:56800
	ds_read_b64_tr_b16 v[4:5], v64 offset:61152
	ds_read_b64_tr_b16 v[6:7], v64 offset:65504
	global_store_dwordx2 v[32:33], v[48:49], off offset:192
	s_waitcnt lgkmcnt(4)
	v_mfma_f32_16x16x32_bf16 v[0:3], v[8:11], v[24:27], v[0:3]
	s_waitcnt lgkmcnt(2)
	v_mfma_f32_16x16x32_bf16 v[0:3], v[12:15], v[28:31], v[0:3]
	s_waitcnt lgkmcnt(0)
	v_mfma_f32_16x16x32_bf16 v[0:3], v[4:7], v[20:23], v[0:3]
	s_nop 7
	v_mul_f32_e32 v0, v34, v0
	v_mul_f32_e32 v1, v34, v1
	v_mul_f32_e32 v2, v34, v2
	v_mul_f32_e32 v3, v34, v3
	v_cvt_pk_bf16_f32 v0, v0, v1
	v_cvt_pk_bf16_f32 v1, v2, v3
	global_store_dwordx2 v[32:33], v[0:1], off offset:224
	s_cbranch_scc1 .LBB0_631
	s_nop 0
	s_nop 0
	s_barrier
	s_branch .LBB0_596

; #define LAS __attribute__((address_space(3)))
; template <bool SAMPLE>
; __device__ __forceinline__ void mem_unit(const Params& p, int l, LAS unsigned char* lds, int unit, int tid, int wave, int lane) {
;     ...
;         for (int hb = 0; hb < 2; ++hb) {
;             float kk[4][8], vv[4][8];
; #pragma unroll
;             for (int it = 0; it < 4; ++it) { const int s = (tid >> 4) + 32 * (4 * hb + it);
;                 const float* kp; const float* vp;
;                 if (!SAMPLE) { kp = (const float*)(p.ws + W_MKV) + ((size_t)l * 1024 + b * 256 + s) * 1024 + h * 128 + sub * 8; vp = kp + 512; }
;                 else { const size_t o = ((((size_t)l * 128 + b) * 256 + s) * 4 + h) * 128 + sub * 8; kp = p.in[I_CMK] + o; vp = p.in[I_CMV] + o; }
;                 if (SAMPLE) { pg8::ld8f_nt(kp, kk[it]); pg8::ld8f_nt(vp, vv[it]); } else { pg8::ld8f(kp, kk[it]); pg8::ld8f(vp, vv[it]); } }
; #pragma unroll
;             for (int it = 0; it < 4; ++it) { const int s = (tid >> 4) + 32 * (4 * hb + it);
;                 float (&k)[8] = kk[it]; float (&v)[8] = vv[it];
;                 if (!SAMPLE) { float ss = 0.f;
; #pragma unroll
;                     for (int e = 0; e < 8; ++e) ss += k[e] * k[e];
;                     ss += __shfl_xor(ss, 1); ss += __shfl_xor(ss, 2); ss += __shfl_xor(ss, 4); ss += __shfl_xor(ss, 8);
;                     const float rs = rsqrtf(ss * (1.f / 128.f) + EPS);
; #pragma unroll
;                     for (int e = 0; e < 8; ++e) k[e] *= rs * kg[e];
;                     if (qt == 0) { const size_t o = ((((size_t)l * 4 + b) * 256 + s) * 4 + h) * 128 + sub * 8;
;                         *(f32x4*)(p.out + O_MKP + o) = (f32x4){k[0], k[1], k[2], k[3]}; *(f32x4*)(p.out + O_MKP + o + 4) = (f32x4){k[4], k[5], k[6], k[7]};
;                         *(f32x4*)(p.out + O_MVP + o) = (f32x4){v[0], v[1], v[2], v[3]}; *(f32x4*)(p.out + O_MVP + o + 4) = (f32x4){v[4], v[5], v[6], v[7]}; }
;                 }
;                 *(LAS bf16x8*)(Kl + s * MEM_KS + sub * 8) = pack8(k);
;                 *(LAS bf16x8*)(Vt + s * MEM_VS + sub * 8) = pack8(v);
;             }
;     ...
;         if (!SAMPLE) { row = (size_t)b * 8192 + (qt * 4 + qq) * 128 + 16 * wave + q16; st = true; } else { row = (size_t)MP + 8 * b + (q16 & 7); st = q16 < 8; }
;         bf16x8 qf[4];
;         {
;             float qv[4][8]; float ss = 0.f;
; #pragma unroll
.LBB0_2730:
	v_add_u32_e32 v66, s8, v81
	v_ashrrev_i32_e32 v67, 31, v66
	v_add_u32_e32 v6, 0x60, v66
	v_lshl_add_u64 v[8:9], v[66:67], 0, s[10:11]
	v_add_u32_e32 v2, 32, v66
	v_add_u32_e32 v4, 64, v66
	v_ashrrev_i32_e32 v7, 31, v6
	v_lshlrev_b64 v[8:9], 11, v[8:9]
	v_ashrrev_i32_e32 v3, 31, v2
	v_ashrrev_i32_e32 v5, 31, v4
	v_lshl_add_u64 v[6:7], v[6:7], 0, s[10:11]
	v_or_b32_e32 v8, v8, v0
	v_lshl_add_u64 v[2:3], v[2:3], 0, s[10:11]
	v_lshl_add_u64 v[4:5], v[4:5], 0, s[10:11]
	v_lshlrev_b64 v[22:23], 11, v[6:7]
	v_lshl_add_u64 v[6:7], s[78:79], 0, v[8:9]
	v_lshl_add_u64 v[14:15], s[80:81], 0, v[8:9]
	v_lshlrev_b64 v[18:19], 11, v[2:3]
	v_lshlrev_b64 v[20:21], 11, v[4:5]
	global_load_dwordx4 v[2:5], v[6:7], off nt
	s_nop 0
	global_load_dwordx4 v[6:9], v[6:7], off offset:16 nt
	s_nop 0
	global_load_dwordx4 v[10:13], v[14:15], off offset:16 nt
	s_nop 0
	global_load_dwordx4 v[14:17], v[14:15], off nt
	v_or_b32_e32 v18, v18, v0
	v_or_b32_e32 v20, v20, v0
	v_or_b32_e32 v22, v22, v0
	v_lshl_add_u64 v[24:25], s[78:79], 0, v[18:19]
	v_lshl_add_u64 v[30:31], s[80:81], 0, v[18:19]
	v_lshl_add_u64 v[38:39], s[78:79], 0, v[20:21]
	v_lshl_add_u64 v[46:47], s[80:81], 0, v[20:21]
	v_lshl_add_u64 v[54:55], s[78:79], 0, v[22:23]
	v_lshl_add_u64 v[62:63], s[80:81], 0, v[22:23]
	global_load_dwordx4 v[18:21], v[24:25], off nt
	s_nop 0
	global_load_dwordx4 v[22:25], v[24:25], off offset:16 nt
	s_nop 0
	global_load_dwordx4 v[26:29], v[30:31], off nt
	s_nop 0
	global_load_dwordx4 v[30:33], v[30:31], off offset:16 nt
	s_nop 0
	global_load_dwordx4 v[34:37], v[38:39], off nt
	s_nop 0
	global_load_dwordx4 v[38:41], v[38:39], off offset:16 nt
	s_nop 0
	global_load_dwordx4 v[42:45], v[46:47], off nt
	s_nop 0
	global_load_dwordx4 v[46:49], v[46:47], off offset:16 nt
	s_nop 0
	global_load_dwordx4 v[50:53], v[54:55], off nt
	s_nop 0
	global_load_dwordx4 v[54:57], v[54:55], off offset:16 nt
	s_nop 0
	global_load_dwordx4 v[58:61], v[62:63], off nt
	s_nop 0
	global_load_dwordx4 v[62:65], v[62:63], off offset:16 nt
	v_cndmask_b32_e64 v1, 0, 1, s[0:1]
	v_cmp_ne_u32_e32 vcc, 1, v1
	v_mul_lo_u32 v1, v66, s22
	v_add_u32_e32 v66, v96, v1
	v_add_u32_e32 v1, v97, v1
	s_movk_i32 s8, 0x80
	s_mov_b64 s[0:1], 0
	s_and_b64 vcc, exec, vcc
	s_waitcnt vmcnt(15)
	v_cvt_pk_bf16_f32 v2, v2, v3
	v_cvt_pk_bf16_f32 v3, v4, v5
	s_waitcnt vmcnt(14)
	v_cvt_pk_bf16_f32 v4, v6, v7
	v_cvt_pk_bf16_f32 v5, v8, v9
	ds_write_b128 v66, v[2:5]
	s_waitcnt vmcnt(12)
	v_cvt_pk_bf16_f32 v2, v14, v15
	v_cvt_pk_bf16_f32 v3, v16, v17
	v_cvt_pk_bf16_f32 v4, v10, v11
	v_cvt_pk_bf16_f32 v5, v12, v13
	ds_write_b128 v1, v[2:5]
	s_waitcnt vmcnt(11)
	v_cvt_pk_bf16_f32 v2, v18, v19
	v_cvt_pk_bf16_f32 v3, v20, v21
	s_waitcnt vmcnt(10)
	v_cvt_pk_bf16_f32 v4, v22, v23
	v_cvt_pk_bf16_f32 v5, v24, v25
	ds_write_b128 v66, v[2:5] offset:8704
	s_waitcnt vmcnt(9)
	v_cvt_pk_bf16_f32 v2, v26, v27
	v_cvt_pk_bf16_f32 v3, v28, v29
	s_waitcnt vmcnt(8)
	v_cvt_pk_bf16_f32 v4, v30, v31
	v_cvt_pk_bf16_f32 v5, v32, v33
	ds_write_b128 v1, v[2:5] offset:8704
	s_waitcnt vmcnt(7)
	v_cvt_pk_bf16_f32 v2, v34, v35
	v_cvt_pk_bf16_f32 v3, v36, v37
	s_waitcnt vmcnt(6)
	v_cvt_pk_bf16_f32 v4, v38, v39
	v_cvt_pk_bf16_f32 v5, v40, v41
	ds_write_b128 v66, v[2:5] offset:17408
	s_waitcnt vmcnt(5)
	v_cvt_pk_bf16_f32 v2, v42, v43
	v_cvt_pk_bf16_f32 v3, v44, v45
	s_waitcnt vmcnt(4)
	v_cvt_pk_bf16_f32 v4, v46, v47
	v_cvt_pk_bf16_f32 v5, v48, v49
	ds_write_b128 v1, v[2:5] offset:17408
	s_waitcnt vmcnt(3)
	v_cvt_pk_bf16_f32 v2, v50, v51
	v_cvt_pk_bf16_f32 v3, v52, v53
	s_waitcnt vmcnt(2)
	v_cvt_pk_bf16_f32 v4, v54, v55
	v_cvt_pk_bf16_f32 v5, v56, v57
	ds_write_b128 v66, v[2:5] offset:26112
	s_waitcnt vmcnt(1)
	v_cvt_pk_bf16_f32 v2, v58, v59
	v_cvt_pk_bf16_f32 v3, v60, v61
	s_waitcnt vmcnt(0)
	v_cvt_pk_bf16_f32 v4, v62, v63
	v_cvt_pk_bf16_f32 v5, v64, v65
	ds_write_b128 v1, v[2:5] offset:26112
	s_cbranch_vccz .LBB0_2730
	s_andn2_b64 vcc, exec, s[6:7]
	s_waitcnt lgkmcnt(0)
	s_barrier
	s_cbranch_vccnz .LBB0_2749
	s_lshl_b32 s0, s2, 3
	s_add_i32 s1, s0, 0x8000
	s_lshl_b32 s0, s3, 1
	v_mov_b32_e32 v37, v95
	v_mov_b32_e32 v36, v94
	s_add_u32 s2, s64, s0
	s_addc_u32 s3, s65, 0
	v_and_or_b32 v0, v36, 7, s1
	v_lshlrev_b32_e32 v82, 10, v0
	v_lshlrev_b32_e32 v16, 3, v37
	v_lshl_add_u64 v[0:1], s[2:3], 0, v[82:83]
	v_ashrrev_i32_e32 v17, 31, v16
	v_lshl_add_u64 v[12:13], v[16:17], 1, v[0:1]
	global_load_dwordx4 v[0:3], v[12:13], off
	global_load_dwordx4 v[4:7], v[12:13], off offset:64
	global_load_dwordx4 v[8:11], v[12:13], off offset:128
	s_nop 0
	global_load_dwordx4 v[12:15], v[12:13], off offset:192
	v_and_b32_e32 v19, 64, v99
	v_xor_b32_e32 v18, 16, v99
	v_add_u32_e32 v34, 64, v19
	v_cmp_lt_i32_e32 vcc, v18, v34
	v_lshl_add_u64 v[24:25], v[16:17], 2, s[46:47]
	s_waitcnt vmcnt(3)
	v_and_b32_e32 v40, 0xffff0000, v0
	v_cndmask_b32_e32 v18, v99, v18, vcc
	v_lshlrev_b32_e32 v38, 2, v18
	global_load_dwordx4 v[16:19], v[24:25], off offset:528
	global_load_dwordx4 v[20:23], v[24:25], off offset:512
	v_lshlrev_b32_e32 v35, 16, v0
	s_waitcnt vmcnt(3)
; __device__ __forceinline__ void unpack8(const v4u w, float (&o)[8]) { o[0] = bflo(w.x); o[1] = bfhi(w.x); o[2] = bflo(w.y); o[3] = bfhi(w.y); o[4] = bflo(w.z); o[5] = bfhi(w.z); o[6] = bflo(w.w); o[7] = bfhi(w.w); }
; __device__ __forceinline__ bf16x8 pack8(const float (&o)[8]) { v4u w; w.x = pk2(o[0], o[1]); w.y = pk2(o[2], o[3]); w.z = pk2(o[4], o[5]); w.w = pk2(o[6], o[7]); return __builtin_bit_cast(bf16x8, w); }
; template <bool SAMPLE>
; __device__ __forceinline__ void mem_unit(const Params& p, int l, LAS unsigned char* lds, int unit, int tid, int wave, int lane) {
;     ...
;             float qv[4][8]; float ss = 0.f;
; #pragma unroll
;             for (int dc = 0; dc < 4; ++dc) { unpack8(*(const v4u*)(MQ + row * 512 + h * 128 + 32 * dc + 8 * kq), qv[dc]);
; #pragma unroll
;                 for (int e = 0; e < 8; ++e) ss += qv[dc][e] * qv[dc][e]; }
;             ss += __shfl_xor(ss, 16); ss += __shfl_xor(ss, 32);
;             const float rs = rsqrtf(ss * (1.f / 128.f) + EPS) * 0.08838834764831845f;
; #pragma unroll
;             for (int dc = 0; dc < 4; ++dc) { float qg[8]; pg8::ld8f(p.in[I_MQG] + l * 128 + 32 * dc + 8 * kq, qg);
; #pragma unroll
;                 for (int e = 0; e < 8; ++e) qv[dc][e] *= rs * qg[e];
;                 qf[dc] = pack8(qv[dc]); }
	v_lshlrev_b32_e32 v55, 16, v8
	v_and_b32_e32 v56, 0xffff0000, v8
	v_mul_f32_e32 v8, v40, v40
	v_lshlrev_b32_e32 v41, 16, v1
	v_fmac_f32_e32 v8, v35, v35
	v_and_b32_e32 v42, 0xffff0000, v1
	v_fmac_f32_e32 v8, v41, v41
	v_lshlrev_b32_e32 v43, 16, v2
	v_fmac_f32_e32 v8, v42, v42
	v_and_b32_e32 v44, 0xffff0000, v2
	v_fmac_f32_e32 v8, v43, v43
	v_lshlrev_b32_e32 v45, 16, v3
	v_fmac_f32_e32 v8, v44, v44
	v_and_b32_e32 v46, 0xffff0000, v3
	v_fmac_f32_e32 v8, v45, v45
	v_lshlrev_b32_e32 v47, 16, v4
	v_fmac_f32_e32 v8, v46, v46
	v_and_b32_e32 v48, 0xffff0000, v4
	v_fmac_f32_e32 v8, v47, v47
	v_lshlrev_b32_e32 v49, 16, v5
	v_fmac_f32_e32 v8, v48, v48
	v_and_b32_e32 v50, 0xffff0000, v5
	v_fmac_f32_e32 v8, v49, v49
	v_lshlrev_b32_e32 v51, 16, v6
	v_fmac_f32_e32 v8, v50, v50
	v_and_b32_e32 v52, 0xffff0000, v6
	v_fmac_f32_e32 v8, v51, v51
	v_lshlrev_b32_e32 v53, 16, v7
	v_fmac_f32_e32 v8, v52, v52
	v_and_b32_e32 v54, 0xffff0000, v7
	v_fmac_f32_e32 v8, v53, v53
	v_fmac_f32_e32 v8, v54, v54
	v_fmac_f32_e32 v8, v55, v55
	v_lshlrev_b32_e32 v57, 16, v9
	v_fmac_f32_e32 v8, v56, v56
	v_and_b32_e32 v58, 0xffff0000, v9
	v_fmac_f32_e32 v8, v57, v57
	v_lshlrev_b32_e32 v59, 16, v10
	v_fmac_f32_e32 v8, v58, v58
	v_and_b32_e32 v60, 0xffff0000, v10
	v_fmac_f32_e32 v8, v59, v59
	v_lshlrev_b32_e32 v61, 16, v11
	v_fmac_f32_e32 v8, v60, v60
	v_and_b32_e32 v62, 0xffff0000, v11
	s_waitcnt vmcnt(2)
	v_and_b32_e32 v26, 0xffff0000, v12
	v_lshlrev_b32_e32 v27, 16, v12
	v_fmac_f32_e32 v8, v61, v61
	v_pk_mul_f32 v[0:1], v[26:27], v[26:27]
	v_fmac_f32_e32 v8, v62, v62
	v_and_b32_e32 v28, 0xffff0000, v13
	v_lshlrev_b32_e32 v29, 16, v13
	v_add_f32_e32 v1, v1, v8
	v_pk_mul_f32 v[2:3], v[28:29], v[28:29]
	v_add_f32_e32 v0, v0, v1
	v_and_b32_e32 v30, 0xffff0000, v14
	v_lshlrev_b32_e32 v31, 16, v14
	v_add_f32_e32 v0, v3, v0
	v_pk_mul_f32 v[4:5], v[30:31], v[30:31]
	v_add_f32_e32 v0, v2, v0
	v_and_b32_e32 v32, 0xffff0000, v15
	v_lshlrev_b32_e32 v33, 16, v15
	v_add_f32_e32 v0, v5, v0
	v_pk_mul_f32 v[6:7], v[32:33], v[32:33]
	v_add_f32_e32 v0, v4, v0
	v_add_f32_e32 v0, v7, v0
	v_add_f32_e32 v0, v6, v0
	ds_bpermute_b32 v1, v38, v0
	v_xor_b32_e32 v2, 32, v99
	v_cmp_lt_i32_e32 vcc, v2, v34
	s_waitcnt lgkmcnt(0)
	v_add_f32_e32 v0, v0, v1
	v_cndmask_b32_e32 v2, v99, v2, vcc
	v_lshlrev_b32_e32 v39, 2, v2
	ds_bpermute_b32 v1, v39, v0
	s_waitcnt lgkmcnt(0)
	v_add_f32_e32 v0, v0, v1
	v_fmamk_f32 v0, v0, 0x3c000000, v98
	v_mul_f32_e32 v1, 0x4b800000, v0
	v_cmp_gt_f32_e32 vcc, s23, v0
	s_nop 1
	v_cndmask_b32_e32 v0, v0, v1, vcc
	v_rsq_f32_e32 v0, v0
	s_nop 0
	v_mul_f32_e32 v1, 0x45800000, v0
	v_cndmask_b32_e32 v0, v0, v1, vcc
	v_mul_f32_e32 v34, 0x3db504f3, v0
	s_waitcnt vmcnt(0)
	v_mul_f32_e32 v0, v20, v34
	v_mul_f32_e32 v1, v21, v34
	v_mul_f32_e32 v2, v22, v34
	v_mul_f32_e32 v3, v23, v34
	v_mul_f32_e32 v4, v16, v34
	v_mul_f32_e32 v5, v17, v34
	v_mul_f32_e32 v6, v18, v34
	v_mul_f32_e32 v7, v19, v34
	v_mul_f32_e32 v0, v0, v35
	v_mul_f32_e32 v1, v1, v40
	v_mul_f32_e32 v2, v2, v41
	v_mul_f32_e32 v3, v3, v42
	v_mul_f32_e32 v4, v4, v43
	v_mul_f32_e32 v5, v5, v44
	v_mul_f32_e32 v6, v6, v45
	v_mul_f32_e32 v7, v7, v46
	v_cvt_pk_bf16_f32 v0, v0, v1
	v_cvt_pk_bf16_f32 v1, v2, v3
	v_cvt_pk_bf16_f32 v2, v4, v5
	v_cvt_pk_bf16_f32 v3, v6, v7
	global_load_dwordx4 v[4:7], v[24:25], off offset:640
	global_load_dwordx4 v[8:11], v[24:25], off offset:656
	v_lshlrev_b32_e32 v20, 4, v37
	v_mul_lo_u32 v21, v36, s22
	v_add3_u32 v92, 0, v20, v21
	s_waitcnt vmcnt(1)
	v_mul_f32_e32 v4, v4, v34
	v_mul_f32_e32 v5, v5, v34
	v_mul_f32_e32 v6, v6, v34
	v_mul_f32_e32 v7, v7, v34
	s_waitcnt vmcnt(0)
	v_mul_f32_e32 v8, v8, v34
	v_mul_f32_e32 v9, v9, v34
	v_mul_f32_e32 v10, v10, v34
	v_mul_f32_e32 v11, v11, v34
	v_mul_f32_e32 v4, v4, v47
	v_mul_f32_e32 v5, v5, v48
	v_mul_f32_e32 v6, v6, v49
	v_mul_f32_e32 v7, v7, v50
	v_mul_f32_e32 v12, v8, v51
	v_mul_f32_e32 v13, v9, v52
	v_mul_f32_e32 v14, v10, v53
	v_mul_f32_e32 v11, v11, v54
	v_cvt_pk_bf16_f32 v8, v4, v5
	v_cvt_pk_bf16_f32 v9, v6, v7
	v_cvt_pk_bf16_f32 v10, v12, v13
	v_cvt_pk_bf16_f32 v11, v14, v11
	global_load_dwordx4 v[4:7], v[24:25], off offset:768
	global_load_dwordx4 v[12:15], v[24:25], off offset:784
	s_waitcnt vmcnt(1)
	v_mul_f32_e32 v4, v4, v34
	v_mul_f32_e32 v5, v5, v34
	v_mul_f32_e32 v6, v6, v34
	v_mul_f32_e32 v7, v7, v34
	s_waitcnt vmcnt(0)
	v_mul_f32_e32 v12, v12, v34
	v_mul_f32_e32 v13, v13, v34
	v_mul_f32_e32 v14, v14, v34
	v_mul_f32_e32 v15, v15, v34
	v_mul_f32_e32 v4, v4, v55
	v_mul_f32_e32 v5, v5, v56
	v_mul_f32_e32 v6, v6, v57
	v_mul_f32_e32 v7, v7, v58
	v_mul_f32_e32 v12, v12, v59
	v_mul_f32_e32 v13, v13, v60
	v_mul_f32_e32 v14, v14, v61
	v_mul_f32_e32 v15, v15, v62
	v_cvt_pk_bf16_f32 v4, v4, v5
	v_cvt_pk_bf16_f32 v5, v6, v7
	v_cvt_pk_bf16_f32 v6, v12, v13
	v_cvt_pk_bf16_f32 v7, v14, v15
	global_load_dwordx4 v[12:15], v[24:25], off offset:896
	global_load_dwordx4 v[16:19], v[24:25], off offset:912
	s_waitcnt vmcnt(1)
	v_mul_f32_e32 v12, v12, v34
	v_mul_f32_e32 v13, v13, v34
	v_mul_f32_e32 v14, v14, v34
	v_mul_f32_e32 v15, v15, v34
	s_waitcnt vmcnt(0)
; #define LAS __attribute__((address_space(3)))
; template <bool SAMPLE>
; __device__ __forceinline__ void mem_unit(const Params& p, int l, LAS unsigned char* lds, int unit, int tid, int wave, int lane) {
;     ...
;         f32x4 S[8][2]; float mx = -INFINITY;
; #pragma unroll
;         for (int cc = 0; cc < 8; ++cc)
; #pragma unroll
;             for (int tt = 0; tt < 2; ++tt) { const int kb = 32 * cc + 16 * tt; f32x4 a = (f32x4){0.f, 0.f, 0.f, 0.f};
; #pragma unroll
;                 for (int dc = 0; dc < 4; ++dc) { const bf16x8 kf = *(const LAS bf16x8*)(Kl + (kb + q16) * MEM_KS + 32 * dc + 8 * kq);
;                     a = __builtin_amdgcn_mfma_f32_16x16x32_bf16(kf, qf[dc], a, 0, 0, 0); }
	v_mul_f32_e32 v16, v16, v34
	v_mul_f32_e32 v17, v17, v34
	v_mul_f32_e32 v18, v18, v34
	v_mul_f32_e32 v19, v19, v34
	v_mul_f32_e32 v12, v12, v27
	v_mul_f32_e32 v13, v13, v26
	v_mul_f32_e32 v14, v14, v29
	v_mul_f32_e32 v15, v15, v28
	v_mul_f32_e32 v16, v16, v31
	v_mul_f32_e32 v17, v17, v30
	v_mul_f32_e32 v18, v18, v33
	v_mul_f32_e32 v19, v19, v32
	v_cvt_pk_bf16_f32 v32, v12, v13
	v_cvt_pk_bf16_f32 v33, v14, v15
	v_cvt_pk_bf16_f32 v34, v16, v17
	v_cvt_pk_bf16_f32 v35, v18, v19
	ds_read_b128 v[186:189], v92
	ds_read_b128 v[190:193], v92 offset:4352
	ds_read_b128 v[194:197], v92 offset:8704
	ds_read_b128 v[198:201], v92 offset:13056
	ds_read_b128 v[202:205], v92 offset:17408
	ds_read_b128 v[206:209], v92 offset:21760
	ds_read_b128 v[210:213], v92 offset:26112
	s_nop 0
	ds_read_b128 v[16:19], v92 offset:64
	s_nop 0
	ds_read_b128 v[24:27], v92 offset:4416
	s_nop 0
	ds_read_b128 v[40:43], v92 offset:8768
	s_nop 0
	ds_read_b128 v[48:51], v92 offset:13120
	s_nop 0
	ds_read_b128 v[56:59], v92 offset:17472
	s_nop 0
	ds_read_b128 v[64:67], v92 offset:21824
	s_nop 0
	ds_read_b128 v[72:75], v92 offset:26176
	ds_read_b128 v[76:79], v92 offset:30464
	ds_read_b128 v[88:91], v92 offset:30528
	ds_read_b128 v[100:103], v92 offset:34816
	ds_read_b128 v[104:107], v92 offset:34880
	ds_read_b128 v[108:111], v92 offset:39168
	ds_read_b128 v[112:115], v92 offset:39232
	ds_read_b128 v[116:119], v92 offset:43520
	ds_read_b128 v[120:123], v92 offset:43584
	ds_read_b128 v[124:127], v92 offset:47872
	ds_read_b128 v[128:131], v92 offset:47936
	ds_read_b128 v[132:135], v92 offset:52224
	ds_read_b128 v[136:139], v92 offset:52288
	ds_read_b128 v[140:143], v92 offset:56576
	ds_read_b128 v[144:147], v92 offset:56640
	ds_read_b128 v[148:151], v92 offset:60928
	ds_read_b128 v[152:155], v92 offset:60992
	ds_read_b128 v[156:159], v92 offset:65280
	ds_read_b128 v[160:163], v92 offset:65344
	s_waitcnt lgkmcnt(14)
	v_mfma_f32_16x16x32_bf16 v[12:15], v[186:189], v[0:3], 0
	v_mfma_f32_16x16x32_bf16 v[20:23], v[190:193], v[0:3], 0
	v_mfma_f32_16x16x32_bf16 v[28:31], v[194:197], v[0:3], 0
	v_mfma_f32_16x16x32_bf16 v[44:47], v[198:201], v[0:3], 0
	v_mfma_f32_16x16x32_bf16 v[52:55], v[202:205], v[0:3], 0
	v_mfma_f32_16x16x32_bf16 v[60:63], v[206:209], v[0:3], 0
	v_mfma_f32_16x16x32_bf16 v[68:71], v[210:213], v[0:3], 0
	v_mfma_f32_16x16x32_bf16 v[76:79], v[76:79], v[0:3], 0
	v_mfma_f32_16x16x32_bf16 v[100:103], v[100:103], v[0:3], 0
	s_waitcnt lgkmcnt(13)
	v_mfma_f32_16x16x32_bf16 v[108:111], v[108:111], v[0:3], 0
	s_waitcnt lgkmcnt(11)
	v_mfma_f32_16x16x32_bf16 v[116:119], v[116:119], v[0:3], 0
	s_waitcnt lgkmcnt(9)
	v_mfma_f32_16x16x32_bf16 v[124:127], v[124:127], v[0:3], 0
	s_waitcnt lgkmcnt(7)
	v_mfma_f32_16x16x32_bf16 v[132:135], v[132:135], v[0:3], 0
	s_waitcnt lgkmcnt(5)
	v_mfma_f32_16x16x32_bf16 v[140:143], v[140:143], v[0:3], 0
	s_waitcnt lgkmcnt(3)
	v_mfma_f32_16x16x32_bf16 v[148:151], v[148:151], v[0:3], 0
	s_waitcnt lgkmcnt(1)
	v_mfma_f32_16x16x32_bf16 v[0:3], v[156:159], v[0:3], 0
	v_mfma_f32_16x16x32_bf16 v[12:15], v[16:19], v[8:11], v[12:15]
	v_mfma_f32_16x16x32_bf16 v[16:19], v[24:27], v[8:11], v[20:23]
	v_mfma_f32_16x16x32_bf16 v[20:23], v[40:43], v[8:11], v[28:31]
	v_mfma_f32_16x16x32_bf16 v[24:27], v[48:51], v[8:11], v[44:47]
	v_mfma_f32_16x16x32_bf16 v[28:31], v[56:59], v[8:11], v[52:55]
	ds_read_b128 v[198:201], v92 offset:128
	ds_read_b128 v[202:205], v92 offset:4480
	ds_read_b128 v[206:209], v92 offset:8832
	ds_read_b128 v[210:213], v92 offset:13184
	v_mfma_f32_16x16x32_bf16 v[40:43], v[64:67], v[8:11], v[60:63]
	v_mfma_f32_16x16x32_bf16 v[44:47], v[72:75], v[8:11], v[68:71]
	v_mfma_f32_16x16x32_bf16 v[48:51], v[88:91], v[8:11], v[76:79]
	v_mfma_f32_16x16x32_bf16 v[52:55], v[104:107], v[8:11], v[100:103]
	v_mfma_f32_16x16x32_bf16 v[56:59], v[112:115], v[8:11], v[108:111]
	v_mfma_f32_16x16x32_bf16 v[60:63], v[120:123], v[8:11], v[116:119]
	v_mfma_f32_16x16x32_bf16 v[64:67], v[128:131], v[8:11], v[124:127]
	ds_read_b128 v[218:221], v92 offset:17536
	ds_read_b128 v[222:225], v92 offset:21888
	ds_read_b128 v[226:229], v92 offset:26240
	ds_read_b128 v[230:233], v92 offset:30592
	ds_read_b128 v[234:237], v92 offset:34944
	ds_read_b128 v[242:245], v92 offset:39296
	ds_read_b128 v[246:249], v92 offset:43648
	v_mfma_f32_16x16x32_bf16 v[68:71], v[136:139], v[8:11], v[132:135]
	v_mfma_f32_16x16x32_bf16 v[72:75], v[144:147], v[8:11], v[140:143]
	v_mfma_f32_16x16x32_bf16 v[76:79], v[152:155], v[8:11], v[148:151]
	s_waitcnt lgkmcnt(11)
	v_mfma_f32_16x16x32_bf16 v[0:3], v[160:163], v[8:11], v[0:3]
	s_nop 0
	ds_read_b128 v[88:91], v92 offset:192
	s_waitcnt lgkmcnt(11)
	v_mfma_f32_16x16x32_bf16 v[8:11], v[198:201], v[4:7], v[12:15]
	s_nop 2
	s_nop 0
	ds_read_b128 v[100:103], v92 offset:4544
	s_waitcnt lgkmcnt(11)
	v_mfma_f32_16x16x32_bf16 v[12:15], v[202:205], v[4:7], v[16:19]
	s_nop 2
	s_nop 0
	ds_read_b128 v[104:107], v92 offset:8896
	s_waitcnt lgkmcnt(11)
	v_mfma_f32_16x16x32_bf16 v[16:19], v[206:209], v[4:7], v[20:23]
	s_nop 2
	s_nop 0
	ds_read_b128 v[108:111], v92 offset:13248
	s_waitcnt lgkmcnt(11)
	v_mfma_f32_16x16x32_bf16 v[20:23], v[210:213], v[4:7], v[24:27]
	s_nop 2
	s_nop 0
	ds_read_b128 v[112:115], v92 offset:17600
	s_waitcnt lgkmcnt(11)
	ds_read_b128 v[186:189], v92 offset:48000
	ds_read_b128 v[190:193], v92 offset:52352
	ds_read_b128 v[194:197], v92 offset:56704
	ds_read_b128 v[198:201], v92 offset:61056
	ds_read_b128 v[202:205], v92 offset:65408
	v_mfma_f32_16x16x32_bf16 v[24:27], v[218:221], v[4:7], v[28:31]
	s_nop 2
	s_nop 0
	ds_read_b128 v[116:119], v92 offset:21952
	s_waitcnt lgkmcnt(15)
; #define LAS __attribute__((address_space(3)))
; template <bool SAMPLE>
; __device__ __forceinline__ void mem_unit(const Params& p, int l, LAS unsigned char* lds, int unit, int tid, int wave, int lane) {
;     ...
;         f32x4 S[8][2]; float mx = -INFINITY;
; #pragma unroll
;         for (int cc = 0; cc < 8; ++cc)
; #pragma unroll
;             for (int tt = 0; tt < 2; ++tt) { const int kb = 32 * cc + 16 * tt; f32x4 a = (f32x4){0.f, 0.f, 0.f, 0.f};
; #pragma unroll
;                 for (int dc = 0; dc < 4; ++dc) { const bf16x8 kf = *(const LAS bf16x8*)(Kl + (kb + q16) * MEM_KS + 32 * dc + 8 * kq);
;                     a = __builtin_amdgcn_mfma_f32_16x16x32_bf16(kf, qf[dc], a, 0, 0, 0); }
; #pragma unroll
;                 for (int e = 0; e < 4; ++e) mx = fmaxf(mx, a[e]);
;                 S[cc][tt] = a; }
;         mx = fmaxf(mx, __shfl_xor(mx, 16)); mx = fmaxf(mx, __shfl_xor(mx, 32));
;         float den = 0.f;
; #pragma unroll
;         for (int cc = 0; cc < 8; ++cc)
; #pragma unroll
;             for (int tt = 0; tt < 2; ++tt)
; #pragma unroll
;                 for (int e = 0; e < 4; ++e) { const float pe = __expf(S[cc][tt][e] - mx); S[cc][tt][e] = pe; den += pe; }
	v_mfma_f32_16x16x32_bf16 v[28:31], v[222:225], v[4:7], v[40:43]
	s_nop 2
	s_nop 0
	ds_read_b128 v[120:123], v92 offset:26304
	s_waitcnt lgkmcnt(15)
	v_mfma_f32_16x16x32_bf16 v[40:43], v[226:229], v[4:7], v[44:47]
	s_nop 2
	s_nop 0
	ds_read_b128 v[124:127], v92 offset:30656
	s_waitcnt lgkmcnt(15)
	v_mfma_f32_16x16x32_bf16 v[44:47], v[230:233], v[4:7], v[48:51]
	s_nop 2
	s_nop 0
	ds_read_b128 v[128:131], v92 offset:35008
	s_waitcnt lgkmcnt(15)
	v_mfma_f32_16x16x32_bf16 v[48:51], v[234:237], v[4:7], v[52:55]
	s_nop 2
	s_nop 0
	ds_read_b128 v[132:135], v92 offset:39360
	s_waitcnt lgkmcnt(15)
	v_mfma_f32_16x16x32_bf16 v[52:55], v[242:245], v[4:7], v[56:59]
	s_nop 2
	s_nop 0
	ds_read_b128 v[136:139], v92 offset:43712
	s_waitcnt lgkmcnt(15)
	v_mfma_f32_16x16x32_bf16 v[56:59], v[246:249], v[4:7], v[60:63]
	s_nop 2
	s_nop 0
	ds_read_b128 v[140:143], v92 offset:48064
	s_waitcnt lgkmcnt(11)
	v_mfma_f32_16x16x32_bf16 v[60:63], v[186:189], v[4:7], v[64:67]
	s_nop 2
	s_nop 0
	ds_read_b128 v[144:147], v92 offset:52416
	s_waitcnt lgkmcnt(11)
	v_mfma_f32_16x16x32_bf16 v[64:67], v[190:193], v[4:7], v[68:71]
	s_nop 2
	s_nop 0
	ds_read_b128 v[148:151], v92 offset:56768
	s_waitcnt lgkmcnt(11)
	v_mfma_f32_16x16x32_bf16 v[68:71], v[194:197], v[4:7], v[72:75]
	s_nop 2
	s_nop 0
	ds_read_b128 v[152:155], v92 offset:61120
	s_waitcnt lgkmcnt(11)
	v_mfma_f32_16x16x32_bf16 v[72:75], v[198:201], v[4:7], v[76:79]
	s_nop 2
	s_nop 0
	ds_read_b128 v[156:159], v92 offset:65472
	s_waitcnt lgkmcnt(11)
	v_mfma_f32_16x16x32_bf16 v[0:3], v[202:205], v[4:7], v[0:3]
	v_mfma_f32_16x16x32_bf16 v[76:79], v[88:91], v[32:35], v[8:11]
	v_mfma_f32_16x16x32_bf16 v[88:91], v[100:103], v[32:35], v[12:15]
	v_mfma_f32_16x16x32_bf16 v[100:103], v[104:107], v[32:35], v[16:19]
	v_mfma_f32_16x16x32_bf16 v[104:107], v[108:111], v[32:35], v[20:23]
	v_mfma_f32_16x16x32_bf16 v[108:111], v[112:115], v[32:35], v[24:27]
	v_mfma_f32_16x16x32_bf16 v[112:115], v[116:119], v[32:35], v[28:31]
	v_mfma_f32_16x16x32_bf16 v[40:43], v[120:123], v[32:35], v[40:43]
	v_mfma_f32_16x16x32_bf16 v[44:47], v[124:127], v[32:35], v[44:47]
	v_mfma_f32_16x16x32_bf16 v[28:31], v[128:131], v[32:35], v[48:51]
	v_mfma_f32_16x16x32_bf16 v[24:27], v[132:135], v[32:35], v[52:55]
	v_mfma_f32_16x16x32_bf16 v[20:23], v[136:139], v[32:35], v[56:59]
	v_mfma_f32_16x16x32_bf16 v[16:19], v[140:143], v[32:35], v[60:63]
	v_mfma_f32_16x16x32_bf16 v[12:15], v[144:147], v[32:35], v[64:67]
	v_mfma_f32_16x16x32_bf16 v[8:11], v[148:151], v[32:35], v[68:71]
	v_mfma_f32_16x16x32_bf16 v[4:7], v[152:155], v[32:35], v[72:75]
	s_waitcnt lgkmcnt(0)
	v_mfma_f32_16x16x32_bf16 v[0:3], v[156:159], v[32:35], v[0:3]
	v_max3_f32 v32, v76, s24, v77
	v_max3_f32 v32, v32, v78, v79
	v_max3_f32 v32, v32, v88, v89
	v_max3_f32 v32, v32, v90, v91
	v_max3_f32 v32, v32, v100, v101
	v_max3_f32 v32, v32, v102, v103
	v_max3_f32 v32, v32, v104, v105
	v_max3_f32 v32, v32, v106, v107
	v_max3_f32 v32, v32, v108, v109
	v_max3_f32 v32, v32, v110, v111
	v_max3_f32 v32, v32, v112, v113
	v_max3_f32 v32, v32, v114, v115
	v_max3_f32 v32, v32, v40, v41
	v_max3_f32 v32, v32, v42, v43
	v_max3_f32 v32, v32, v44, v45
	v_max3_f32 v32, v32, v46, v47
	v_max3_f32 v32, v32, v28, v29
	v_max3_f32 v32, v32, v30, v31
	v_max3_f32 v32, v32, v24, v25
	v_max3_f32 v32, v32, v26, v27
	v_max3_f32 v32, v32, v20, v21
	v_max3_f32 v32, v32, v22, v23
	v_max3_f32 v32, v32, v16, v17
	v_max3_f32 v32, v32, v18, v19
	v_max3_f32 v32, v32, v12, v13
	v_max3_f32 v32, v32, v14, v15
	v_max3_f32 v32, v32, v8, v9
	v_max3_f32 v32, v32, v10, v11
	v_max3_f32 v32, v32, v4, v5
	v_max3_f32 v32, v32, v6, v7
	v_max3_f32 v32, v32, v0, v1
	v_max3_f32 v32, v32, v2, v3
	ds_bpermute_b32 v33, v38, v32
	s_waitcnt lgkmcnt(0)
	v_max_f32_e32 v33, v33, v33
	v_max_f32_e32 v32, v32, v33
	ds_bpermute_b32 v33, v39, v32
	s_waitcnt lgkmcnt(0)
	v_max_f32_e32 v33, v33, v33
	v_max_f32_e32 v32, v32, v33
	v_sub_f32_e32 v33, v76, v32
	v_sub_f32_e32 v34, v77, v32
	v_mul_f32_e32 v33, 0x3fb8aa3b, v33
	v_sub_f32_e32 v35, v78, v32
	v_mul_f32_e32 v34, 0x3fb8aa3b, v34
	v_exp_f32_e32 v33, v33
	v_sub_f32_e32 v48, v79, v32
	v_mul_f32_e32 v35, 0x3fb8aa3b, v35
	v_exp_f32_e32 v34, v34
	v_sub_f32_e32 v49, v88, v32
	v_mul_f32_e32 v48, 0x3fb8aa3b, v48
	v_exp_f32_e32 v35, v35
	v_sub_f32_e32 v50, v89, v32
	v_mul_f32_e32 v49, 0x3fb8aa3b, v49
	v_exp_f32_e32 v48, v48
	v_sub_f32_e32 v51, v90, v32
	v_mul_f32_e32 v50, 0x3fb8aa3b, v50
	v_exp_f32_e32 v49, v49
	v_add_f32_e32 v69, 0, v33
	v_sub_f32_e32 v52, v91, v32
	v_mul_f32_e32 v51, 0x3fb8aa3b, v51
	v_exp_f32_e32 v50, v50
	v_add_f32_e32 v69, v34, v69
	v_sub_f32_e32 v53, v100, v32
	v_mul_f32_e32 v52, 0x3fb8aa3b, v52
	v_exp_f32_e32 v51, v51
	v_add_f32_e32 v69, v35, v69
	v_sub_f32_e32 v54, v101, v32
	v_mul_f32_e32 v53, 0x3fb8aa3b, v53
	v_exp_f32_e32 v52, v52
	v_add_f32_e32 v69, v48, v69
	v_sub_f32_e32 v55, v102, v32
	v_mul_f32_e32 v54, 0x3fb8aa3b, v54
	v_exp_f32_e32 v53, v53
	v_add_f32_e32 v69, v49, v69
	v_sub_f32_e32 v56, v103, v32
	v_mul_f32_e32 v55, 0x3fb8aa3b, v55
	v_exp_f32_e32 v54, v54
	v_add_f32_e32 v69, v50, v69
	v_sub_f32_e32 v57, v104, v32
	v_mul_f32_e32 v56, 0x3fb8aa3b, v56
	v_exp_f32_e32 v55, v55
	v_add_f32_e32 v69, v51, v69
	v_sub_f32_e32 v58, v105, v32
	v_mul_f32_e32 v57, 0x3fb8aa3b, v57
	v_exp_f32_e32 v56, v56
	v_add_f32_e32 v69, v52, v69
	v_sub_f32_e32 v59, v106, v32
	v_mul_f32_e32 v58, 0x3fb8aa3b, v58
	v_exp_f32_e32 v57, v57
	v_add_f32_e32 v69, v53, v69
	v_sub_f32_e32 v60, v107, v32
	v_mul_f32_e32 v59, 0x3fb8aa3b, v59
	v_exp_f32_e32 v58, v58
	v_add_f32_e32 v69, v54, v69
	v_sub_f32_e32 v61, v108, v32
	v_mul_f32_e32 v60, 0x3fb8aa3b, v60
	v_exp_f32_e32 v59, v59
	v_add_f32_e32 v69, v55, v69
	v_sub_f32_e32 v62, v109, v32
; __device__ __forceinline__ bf16x8 pack8(const float (&o)[8]) { v4u w; w.x = pk2(o[0], o[1]); w.y = pk2(o[2], o[3]); w.z = pk2(o[4], o[5]); w.w = pk2(o[6], o[7]); return __builtin_bit_cast(bf16x8, w); }
; template <bool SAMPLE>
; __device__ __forceinline__ void mem_unit(const Params& p, int l, LAS unsigned char* lds, int unit, int tid, int wave, int lane) {
;     ...
;         float den = 0.f;
; #pragma unroll
;         for (int cc = 0; cc < 8; ++cc)
; #pragma unroll
;             for (int tt = 0; tt < 2; ++tt)
; #pragma unroll
;                 for (int e = 0; e < 4; ++e) { const float pe = __expf(S[cc][tt][e] - mx); S[cc][tt][e] = pe; den += pe; }
;         den += __shfl_xor(den, 16); den += __shfl_xor(den, 32);
;         const float rden = 1.f / den;
;         bf16x8 pf[8];
; #pragma unroll
;         for (int cc = 0; cc < 8; ++cc) { float t8[8];
; #pragma unroll
;             for (int e = 0; e < 4; ++e) { t8[e] = S[cc][0][e]; t8[4 + e] = S[cc][1][e]; }
;             pf[cc] = pack8(t8); }
	v_mul_f32_e32 v61, 0x3fb8aa3b, v61
	v_exp_f32_e32 v60, v60
	v_add_f32_e32 v69, v56, v69
	v_sub_f32_e32 v63, v110, v32
	v_mul_f32_e32 v62, 0x3fb8aa3b, v62
	v_exp_f32_e32 v61, v61
	v_add_f32_e32 v69, v57, v69
	v_sub_f32_e32 v64, v111, v32
	v_mul_f32_e32 v63, 0x3fb8aa3b, v63
	v_exp_f32_e32 v62, v62
	v_add_f32_e32 v69, v58, v69
	v_sub_f32_e32 v65, v112, v32
	v_mul_f32_e32 v64, 0x3fb8aa3b, v64
	v_exp_f32_e32 v63, v63
	v_add_f32_e32 v69, v59, v69
	v_sub_f32_e32 v66, v113, v32
	v_mul_f32_e32 v65, 0x3fb8aa3b, v65
	v_exp_f32_e32 v64, v64
	v_add_f32_e32 v69, v60, v69
	v_sub_f32_e32 v67, v114, v32
	v_mul_f32_e32 v66, 0x3fb8aa3b, v66
	v_exp_f32_e32 v65, v65
	v_add_f32_e32 v69, v61, v69
	v_sub_f32_e32 v68, v115, v32
	v_mul_f32_e32 v67, 0x3fb8aa3b, v67
	v_exp_f32_e32 v66, v66
	v_add_f32_e32 v69, v62, v69
	v_sub_f32_e32 v40, v40, v32
	v_mul_f32_e32 v68, 0x3fb8aa3b, v68
	v_exp_f32_e32 v67, v67
	v_add_f32_e32 v69, v63, v69
	v_sub_f32_e32 v41, v41, v32
	v_mul_f32_e32 v40, 0x3fb8aa3b, v40
	v_exp_f32_e32 v68, v68
	v_add_f32_e32 v69, v64, v69
	v_sub_f32_e32 v42, v42, v32
	v_mul_f32_e32 v41, 0x3fb8aa3b, v41
	v_exp_f32_e32 v40, v40
	v_add_f32_e32 v69, v65, v69
	v_sub_f32_e32 v43, v43, v32
	v_mul_f32_e32 v42, 0x3fb8aa3b, v42
	v_exp_f32_e32 v41, v41
	v_add_f32_e32 v69, v66, v69
	v_sub_f32_e32 v44, v44, v32
	v_mul_f32_e32 v43, 0x3fb8aa3b, v43
	v_exp_f32_e32 v42, v42
	v_add_f32_e32 v69, v67, v69
	v_sub_f32_e32 v45, v45, v32
	v_mul_f32_e32 v44, 0x3fb8aa3b, v44
	v_exp_f32_e32 v43, v43
	v_add_f32_e32 v69, v68, v69
	v_sub_f32_e32 v46, v46, v32
	v_mul_f32_e32 v45, 0x3fb8aa3b, v45
	v_exp_f32_e32 v44, v44
	v_add_f32_e32 v69, v40, v69
	v_sub_f32_e32 v47, v47, v32
	v_mul_f32_e32 v46, 0x3fb8aa3b, v46
	v_exp_f32_e32 v45, v45
	v_add_f32_e32 v69, v41, v69
	v_sub_f32_e32 v28, v28, v32
	v_mul_f32_e32 v47, 0x3fb8aa3b, v47
	v_exp_f32_e32 v46, v46
	v_add_f32_e32 v69, v42, v69
	v_sub_f32_e32 v29, v29, v32
	v_mul_f32_e32 v28, 0x3fb8aa3b, v28
	v_exp_f32_e32 v47, v47
	v_add_f32_e32 v69, v43, v69
	v_exp_f32_e32 v28, v28
	v_add_f32_e32 v69, v44, v69
	v_mul_f32_e32 v29, 0x3fb8aa3b, v29
	v_sub_f32_e32 v30, v30, v32
	v_sub_f32_e32 v24, v24, v32
	v_add_f32_e32 v69, v45, v69
	v_exp_f32_e32 v29, v29
	v_mul_f32_e32 v30, 0x3fb8aa3b, v30
	v_sub_f32_e32 v31, v31, v32
	v_mul_f32_e32 v24, 0x3fb8aa3b, v24
	v_add_f32_e32 v69, v46, v69
	v_exp_f32_e32 v30, v30
	v_mul_f32_e32 v31, 0x3fb8aa3b, v31
	v_exp_f32_e32 v70, v24
	v_sub_f32_e32 v24, v25, v32
	v_add_f32_e32 v69, v47, v69
	v_exp_f32_e32 v31, v31
	v_mul_f32_e32 v24, 0x3fb8aa3b, v24
	v_add_f32_e32 v69, v28, v69
	v_exp_f32_e32 v71, v24
	v_sub_f32_e32 v24, v26, v32
	v_add_f32_e32 v69, v29, v69
	v_mul_f32_e32 v24, 0x3fb8aa3b, v24
	v_add_f32_e32 v69, v30, v69
	v_exp_f32_e32 v72, v24
	v_sub_f32_e32 v24, v27, v32
	v_sub_f32_e32 v20, v20, v32
	v_add_f32_e32 v69, v31, v69
	v_mul_f32_e32 v24, 0x3fb8aa3b, v24
	v_mul_f32_e32 v20, 0x3fb8aa3b, v20
	v_exp_f32_e32 v73, v24
	v_add_f32_e32 v24, v70, v69
	v_exp_f32_e32 v69, v20
	v_sub_f32_e32 v20, v21, v32
	v_mul_f32_e32 v20, 0x3fb8aa3b, v20
	v_exp_f32_e32 v74, v20
	v_sub_f32_e32 v20, v22, v32
	v_sub_f32_e32 v16, v16, v32
	v_mul_f32_e32 v20, 0x3fb8aa3b, v20
	v_mul_f32_e32 v16, 0x3fb8aa3b, v16
	v_add_f32_e32 v24, v71, v24
	v_exp_f32_e32 v75, v20
	v_sub_f32_e32 v20, v23, v32
	v_exp_f32_e32 v77, v16
	v_sub_f32_e32 v16, v17, v32
	v_add_f32_e32 v24, v72, v24
	v_mul_f32_e32 v20, 0x3fb8aa3b, v20
	v_mul_f32_e32 v16, 0x3fb8aa3b, v16
	v_add_f32_e32 v24, v73, v24
	v_exp_f32_e32 v76, v20
	v_exp_f32_e32 v78, v16
	v_sub_f32_e32 v16, v18, v32
	v_sub_f32_e32 v12, v12, v32
	v_add_f32_e32 v20, v69, v24
	v_mul_f32_e32 v16, 0x3fb8aa3b, v16
	v_mul_f32_e32 v12, 0x3fb8aa3b, v12
	v_add_f32_e32 v20, v74, v20
	v_exp_f32_e32 v79, v16
	v_sub_f32_e32 v16, v19, v32
	v_exp_f32_e32 v89, v12
	v_sub_f32_e32 v12, v13, v32
	v_add_f32_e32 v20, v75, v20
	v_mul_f32_e32 v16, 0x3fb8aa3b, v16
	v_mul_f32_e32 v12, 0x3fb8aa3b, v12
	v_add_f32_e32 v20, v76, v20
	v_exp_f32_e32 v88, v16
	v_exp_f32_e32 v90, v12
	v_sub_f32_e32 v12, v14, v32
	v_sub_f32_e32 v8, v8, v32
	v_add_f32_e32 v16, v77, v20
	v_mul_f32_e32 v12, 0x3fb8aa3b, v12
	v_mul_f32_e32 v8, 0x3fb8aa3b, v8
	v_add_f32_e32 v16, v78, v16
	v_exp_f32_e32 v91, v12
	v_sub_f32_e32 v12, v15, v32
	v_exp_f32_e32 v93, v8
	v_sub_f32_e32 v8, v9, v32
	v_add_f32_e32 v16, v79, v16
	v_mul_f32_e32 v12, 0x3fb8aa3b, v12
	v_mul_f32_e32 v8, 0x3fb8aa3b, v8
	v_add_f32_e32 v16, v88, v16
	v_exp_f32_e32 v92, v12
	v_exp_f32_e32 v100, v8
	v_sub_f32_e32 v8, v10, v32
	v_sub_f32_e32 v4, v4, v32
	v_add_f32_e32 v12, v89, v16
	v_mul_f32_e32 v8, 0x3fb8aa3b, v8
	v_mul_f32_e32 v4, 0x3fb8aa3b, v4
	v_add_f32_e32 v12, v90, v12
	v_exp_f32_e32 v101, v8
	v_sub_f32_e32 v8, v11, v32
	v_exp_f32_e32 v103, v4
	v_sub_f32_e32 v4, v5, v32
	v_add_f32_e32 v12, v91, v12
	v_mul_f32_e32 v8, 0x3fb8aa3b, v8
	v_mul_f32_e32 v4, 0x3fb8aa3b, v4
	v_add_f32_e32 v12, v92, v12
	v_exp_f32_e32 v102, v8
	v_exp_f32_e32 v104, v4
	v_sub_f32_e32 v4, v6, v32
	v_sub_f32_e32 v0, v0, v32
	v_add_f32_e32 v8, v93, v12
	v_mul_f32_e32 v4, 0x3fb8aa3b, v4
	v_mul_f32_e32 v0, 0x3fb8aa3b, v0
	v_add_f32_e32 v8, v100, v8
	v_exp_f32_e32 v105, v4
	v_sub_f32_e32 v4, v7, v32
	v_exp_f32_e32 v107, v0
	v_sub_f32_e32 v0, v1, v32
	v_add_f32_e32 v8, v101, v8
	v_mul_f32_e32 v4, 0x3fb8aa3b, v4
	v_mul_f32_e32 v0, 0x3fb8aa3b, v0
	v_add_f32_e32 v8, v102, v8
	v_exp_f32_e32 v106, v4
	v_exp_f32_e32 v108, v0
	v_sub_f32_e32 v0, v2, v32
	v_add_f32_e32 v4, v103, v8
	v_mul_f32_e32 v0, 0x3fb8aa3b, v0
	v_add_f32_e32 v4, v104, v4
	v_exp_f32_e32 v109, v0
	v_sub_f32_e32 v0, v3, v32
	v_add_f32_e32 v4, v105, v4
	v_mul_f32_e32 v0, 0x3fb8aa3b, v0
	v_add_f32_e32 v4, v106, v4
	v_exp_f32_e32 v32, v0
	v_add_f32_e32 v0, v107, v4
	v_add_f32_e32 v0, v108, v0
	v_add_f32_e32 v0, v109, v0
	v_add_f32_e32 v0, v32, v0
	ds_bpermute_b32 v1, v38, v0
	v_cvt_pk_bf16_f32 v24, v33, v34
	v_cvt_pk_bf16_f32 v25, v35, v48
	v_cvt_pk_bf16_f32 v26, v49, v50
	v_cvt_pk_bf16_f32 v27, v51, v52
	s_waitcnt lgkmcnt(0)
; #define LAS __attribute__((address_space(3)))
; __device__ __forceinline__ unsigned pk2(float lo, float hi) { return pg8::cvt_pk_bf16(lo, hi); }
; __device__ __forceinline__ bf16x8 pack8(const float (&o)[8]) { v4u w; w.x = pk2(o[0], o[1]); w.y = pk2(o[2], o[3]); w.z = pk2(o[4], o[5]); w.w = pk2(o[6], o[7]); return __builtin_bit_cast(bf16x8, w); }
; __device__ __forceinline__ v2u vtr(const LAS bf16* p) { return __builtin_bit_cast(v2u, __builtin_amdgcn_ds_read_tr16_b64_v4i16((LAS v4i16_t*)p)); }
; template <bool SAMPLE>
; __device__ __forceinline__ void mem_unit(const Params& p, int l, LAS unsigned char* lds, int unit, int tid, int wave, int lane) {
;     ...
;         den += __shfl_xor(den, 16); den += __shfl_xor(den, 32);
;         const float rden = 1.f / den;
;         bf16x8 pf[8];
; #pragma unroll
;         for (int cc = 0; cc < 8; ++cc) { float t8[8];
; #pragma unroll
;             for (int e = 0; e < 4; ++e) { t8[e] = S[cc][0][e]; t8[4 + e] = S[cc][1][e]; }
;             pf[cc] = pack8(t8); }
; #pragma unroll
;         for (int dt = 0; dt < 8; ++dt) { f32x4 o = (f32x4){0.f, 0.f, 0.f, 0.f};
; #pragma unroll
;             for (int cc = 0; cc < 8; ++cc) { const LAS bf16* vp = Vt + (32 * cc + 4 * kq + (q16 >> 2)) * MEM_VS + 16 * dt + 4 * (q16 & 3);
;                 const v2u lo = vtr(vp), hi = vtr(vp + 16 * MEM_VS);
;                 v4u av; av.x = lo.x; av.y = lo.y; av.z = hi.x; av.w = hi.y;
;                 o = __builtin_amdgcn_mfma_f32_16x16x32_bf16(__builtin_bit_cast(bf16x8, av), pf[cc], o, 0, 0, 0); }
;             if (st) { v2u w; w.x = pk2(o[0] * rden, o[1] * rden); w.y = pk2(o[2] * rden, o[3] * rden);
;                 *(v2u*)(MO + row * 512 + h * 128 + 16 * dt + 4 * kq) = w; } }
	v_add_f32_e32 v0, v0, v1
	ds_bpermute_b32 v1, v39, v0
	v_cvt_pk_bf16_f32 v20, v53, v54
	v_cvt_pk_bf16_f32 v21, v55, v56
	v_cvt_pk_bf16_f32 v22, v57, v58
	v_cvt_pk_bf16_f32 v23, v59, v60
	s_waitcnt lgkmcnt(0)
	v_add_f32_e32 v39, v0, v1
	v_cvt_pk_bf16_f32 v16, v61, v62
	v_cvt_pk_bf16_f32 v17, v63, v64
	v_cvt_pk_bf16_f32 v18, v65, v66
	v_cvt_pk_bf16_f32 v19, v67, v68
	v_cvt_pk_bf16_f32 v12, v40, v41
	v_cvt_pk_bf16_f32 v13, v42, v43
	v_cvt_pk_bf16_f32 v14, v44, v45
	v_cvt_pk_bf16_f32 v15, v46, v47
	v_cvt_pk_bf16_f32 v8, v28, v29
	v_cvt_pk_bf16_f32 v9, v30, v31
	v_cvt_pk_bf16_f32 v10, v70, v71
	v_cvt_pk_bf16_f32 v11, v72, v73
	v_cvt_pk_bf16_f32 v4, v69, v74
	v_cvt_pk_bf16_f32 v5, v75, v76
	v_cvt_pk_bf16_f32 v6, v77, v78
	v_cvt_pk_bf16_f32 v7, v79, v88
	v_cvt_pk_bf16_f32 v0, v89, v90
	v_cvt_pk_bf16_f32 v1, v91, v92
	v_cvt_pk_bf16_f32 v2, v93, v100
	v_cvt_pk_bf16_f32 v3, v101, v102
	v_cvt_pk_bf16_f32 v28, v103, v104
	v_cvt_pk_bf16_f32 v29, v105, v106
	v_cvt_pk_bf16_f32 v30, v107, v108
	v_cvt_pk_bf16_f32 v31, v109, v32
	v_lshlrev_b32_e32 v52, 2, v37
	v_lshrrev_b32_e32 v32, 2, v36
	v_add_u32_e32 v32, v32, v52
	v_lshlrev_b32_e32 v33, 3, v36
	v_and_b32_e32 v33, 24, v33
	v_mul_lo_u32 v32, v32, s22
	v_add3_u32 v38, s90, v33, v32
	ds_read_b64_tr_b16 v[32:33], v38
	ds_read_b64_tr_b16 v[34:35], v38 offset:4352
	ds_read_b64_tr_b16 v[40:41], v38 offset:8704
	ds_read_b64_tr_b16 v[42:43], v38 offset:13056
	s_waitcnt lgkmcnt(2)
	v_mfma_f32_16x16x32_bf16 v[32:35], v[32:35], v[24:27], 0
	ds_read_b64_tr_b16 v[44:45], v38 offset:17408
	ds_read_b64_tr_b16 v[46:47], v38 offset:21760
	ds_read_b64_tr_b16 v[48:49], v38 offset:26112
	ds_read_b64_tr_b16 v[50:51], v38 offset:30464
	v_div_scale_f32 v53, s[2:3], v39, v39, 1.0
	s_waitcnt lgkmcnt(4)
	v_mfma_f32_16x16x32_bf16 v[32:35], v[40:43], v[20:23], v[32:35]
	ds_read_b64_tr_b16 v[40:41], v38 offset:34816
	ds_read_b64_tr_b16 v[42:43], v38 offset:39168
	v_rcp_f32_e32 v37, v53
	s_add_u32 s2, s70, s0
	s_waitcnt lgkmcnt(4)
	v_mfma_f32_16x16x32_bf16 v[32:35], v[44:47], v[16:19], v[32:35]
	ds_read_b64_tr_b16 v[44:45], v38 offset:43520
	ds_read_b64_tr_b16 v[46:47], v38 offset:47872
	v_cmp_gt_i32_e64 s[0:1], 8, v36
	v_fma_f32 v36, -v53, v37, 1.0
	s_waitcnt lgkmcnt(4)
	v_mfma_f32_16x16x32_bf16 v[32:35], v[48:51], v[12:15], v[32:35]
	ds_read_b64_tr_b16 v[48:49], v38 offset:52224
	ds_read_b64_tr_b16 v[50:51], v38 offset:56576
	v_fmac_f32_e32 v37, v36, v37
	v_div_scale_f32 v36, vcc, 1.0, v39, 1.0
	s_waitcnt lgkmcnt(4)
	v_mfma_f32_16x16x32_bf16 v[32:35], v[40:43], v[8:11], v[32:35]
	ds_read_b64_tr_b16 v[40:41], v38 offset:60928
	ds_read_b64_tr_b16 v[42:43], v38 offset:65280
	v_mul_f32_e32 v54, v36, v37
	v_fma_f32 v55, -v53, v54, v36
	s_waitcnt lgkmcnt(4)
	v_mfma_f32_16x16x32_bf16 v[32:35], v[44:47], v[4:7], v[32:35]
	v_fmac_f32_e32 v54, v55, v37
	v_fma_f32 v36, -v53, v54, v36
	s_addc_u32 s3, s71, 0
	s_waitcnt lgkmcnt(2)
	v_mfma_f32_16x16x32_bf16 v[32:35], v[48:51], v[0:3], v[32:35]
	v_div_fmas_f32 v36, v36, v37, v54
	v_div_fixup_f32 v39, v36, v39, 1.0
	v_lshl_add_u64 v[36:37], s[2:3], 0, v[82:83]
	s_waitcnt lgkmcnt(0)
	v_mfma_f32_16x16x32_bf16 v[32:35], v[40:43], v[28:31], v[32:35]
	v_ashrrev_i32_e32 v53, 31, v52
	v_lshl_add_u64 v[36:37], v[52:53], 1, v[36:37]
	s_and_saveexec_b64 s[2:3], s[0:1]
	s_cbranch_execz .LBB0_2734
	s_nop 3
	v_mul_f32_e32 v32, v32, v39
	v_mul_f32_e32 v33, v33, v39
	v_cvt_pk_bf16_f32 v32, v32, v33
	v_mul_f32_e32 v33, v34, v39
	v_mul_f32_e32 v34, v35, v39
	v_cvt_pk_bf16_f32 v33, v33, v34
	global_store_dwordx2 v[36:37], v[32:33], off

; __device__ __forceinline__ void unpack8(const v4u w, float (&o)[8]) { o[0] = bflo(w.x); o[1] = bfhi(w.x); o[2] = bflo(w.y); o[3] = bfhi(w.y); o[4] = bflo(w.z); o[5] = bfhi(w.z); o[6] = bflo(w.w); o[7] = bfhi(w.w); }
; __device__ __forceinline__ bf16x8 pack8(const float (&o)[8]) { v4u w; w.x = pk2(o[0], o[1]); w.y = pk2(o[2], o[3]); w.z = pk2(o[4], o[5]); w.w = pk2(o[6], o[7]); return __builtin_bit_cast(bf16x8, w); }
; template <bool SAMPLE>
; __device__ __forceinline__ void mem_unit(const Params& p, int l, LAS unsigned char* lds, int unit, int tid, int wave, int lane) {
;     ...
;         int q16 = lane & 15, kq = lane >> 4; asm volatile("" : "+v"(q16), "+v"(kq));
;         size_t row; bool st;
;         if (!SAMPLE) { row = (size_t)b * 8192 + (qt * 4 + qq) * 128 + 16 * wave + q16; st = true; } else { row = (size_t)MP + 8 * b + (q16 & 7); st = q16 < 8; }
;         bf16x8 qf[4];
;         {
;             float qv[4][8]; float ss = 0.f;
; #pragma unroll
;             for (int dc = 0; dc < 4; ++dc) { unpack8(*(const v4u*)(MQ + row * 512 + h * 128 + 32 * dc + 8 * kq), qv[dc]);
; #pragma unroll
;                 for (int e = 0; e < 8; ++e) ss += qv[dc][e] * qv[dc][e]; }
;             ss += __shfl_xor(ss, 16); ss += __shfl_xor(ss, 32);
;             const float rs = rsqrtf(ss * (1.f / 128.f) + EPS) * 0.08838834764831845f;
; #pragma unroll
;             for (int dc = 0; dc < 4; ++dc) { float qg[8]; pg8::ld8f(p.in[I_MQG] + l * 128 + 32 * dc + 8 * kq, qg);
; #pragma unroll
;                 for (int e = 0; e < 8; ++e) qv[dc][e] *= rs * qg[e];
;                 qf[dc] = pack8(qv[dc]); }
.LBB0_2762:
	v_mov_b32_e32 v92, v95
	v_mov_b32_e32 v90, v94
	s_add_u32 s16, s10, s8
	s_addc_u32 s17, s18, s9
	v_ashrrev_i32_e32 v91, 31, v90
	v_lshl_add_u64 v[0:1], s[16:17], 0, v[90:91]
	v_lshlrev_b32_e32 v8, 3, v92
	v_lshlrev_b64 v[88:89], 10, v[0:1]
	v_ashrrev_i32_e32 v9, 31, v8
	v_lshl_add_u64 v[10:11], s[0:1], 0, v[88:89]
	v_lshlrev_b32_e32 v2, 4, v92
	v_mul_lo_u32 v3, v90, s22
	v_lshl_add_u64 v[24:25], v[8:9], 2, s[46:47]
	v_lshl_add_u64 v[20:21], v[8:9], 1, v[10:11]
	v_add3_u32 v91, 0, v2, v3
	global_load_dwordx4 v[0:3], v[24:25], off offset:528
	global_load_dwordx4 v[4:7], v[24:25], off offset:512
	global_load_dwordx4 v[8:11], v[20:21], off
	global_load_dwordx4 v[12:15], v[20:21], off offset:64
	global_load_dwordx4 v[16:19], v[20:21], off offset:128
	s_nop 0
	global_load_dwordx4 v[20:23], v[20:21], off offset:192
	v_lshlrev_b32_e32 v92, 2, v92
	v_ashrrev_i32_e32 v93, 31, v92
	s_add_u32 s8, s8, 0x80
	s_addc_u32 s9, s9, 0
	s_cmpk_lg_i32 s8, 0x200
	s_waitcnt vmcnt(3)
	v_and_b32_e32 v31, 0xffff0000, v8
	v_lshlrev_b32_e32 v30, 16, v8
	v_mul_f32_e32 v50, v31, v31
	v_lshlrev_b32_e32 v32, 16, v9
	v_fmac_f32_e32 v50, v30, v30
	v_and_b32_e32 v33, 0xffff0000, v9
	v_fmac_f32_e32 v50, v32, v32
	v_lshlrev_b32_e32 v34, 16, v10
	v_fmac_f32_e32 v50, v33, v33
	v_and_b32_e32 v35, 0xffff0000, v10
	v_fmac_f32_e32 v50, v34, v34
	v_lshlrev_b32_e32 v36, 16, v11
	v_fmac_f32_e32 v50, v35, v35
	v_and_b32_e32 v37, 0xffff0000, v11
	v_fmac_f32_e32 v50, v36, v36
	s_waitcnt vmcnt(2)
	v_lshlrev_b32_e32 v38, 16, v12
	v_fmac_f32_e32 v50, v37, v37
	v_and_b32_e32 v39, 0xffff0000, v12
	v_fmac_f32_e32 v50, v38, v38
	v_lshlrev_b32_e32 v40, 16, v13
	v_fmac_f32_e32 v50, v39, v39
	v_and_b32_e32 v41, 0xffff0000, v13
	v_fmac_f32_e32 v50, v40, v40
	v_lshlrev_b32_e32 v42, 16, v14
	v_fmac_f32_e32 v50, v41, v41
	v_and_b32_e32 v43, 0xffff0000, v14
	v_fmac_f32_e32 v50, v42, v42
	v_lshlrev_b32_e32 v44, 16, v15
	v_fmac_f32_e32 v50, v43, v43
	v_and_b32_e32 v45, 0xffff0000, v15
	v_fmac_f32_e32 v50, v44, v44
	s_waitcnt vmcnt(1)
	v_lshlrev_b32_e32 v46, 16, v16
	v_fmac_f32_e32 v50, v45, v45
	v_and_b32_e32 v16, 0xffff0000, v16
	v_fmac_f32_e32 v50, v46, v46
	v_lshlrev_b32_e32 v47, 16, v17
	v_fmac_f32_e32 v50, v16, v16
	v_and_b32_e32 v17, 0xffff0000, v17
	v_fmac_f32_e32 v50, v47, v47
	v_lshlrev_b32_e32 v48, 16, v18
	v_fmac_f32_e32 v50, v17, v17
	v_and_b32_e32 v18, 0xffff0000, v18
	v_fmac_f32_e32 v50, v48, v48
	v_lshlrev_b32_e32 v49, 16, v19
	v_fmac_f32_e32 v50, v18, v18
	v_and_b32_e32 v19, 0xffff0000, v19
	s_waitcnt vmcnt(0)
	v_and_b32_e32 v26, 0xffff0000, v20
	v_lshlrev_b32_e32 v27, 16, v20
	v_fmac_f32_e32 v50, v49, v49
	v_pk_mul_f32 v[8:9], v[26:27], v[26:27]
	v_fmac_f32_e32 v50, v19, v19
	v_and_b32_e32 v20, 0xffff0000, v21
	v_lshlrev_b32_e32 v21, 16, v21
	v_add_f32_e32 v9, v9, v50
	v_pk_mul_f32 v[10:11], v[20:21], v[20:21]
	v_add_f32_e32 v8, v8, v9
	v_and_b32_e32 v28, 0xffff0000, v22
	v_lshlrev_b32_e32 v29, 16, v22
	v_add_f32_e32 v8, v11, v8
	v_pk_mul_f32 v[12:13], v[28:29], v[28:29]
	v_add_f32_e32 v8, v10, v8
	v_and_b32_e32 v22, 0xffff0000, v23
	v_lshlrev_b32_e32 v23, 16, v23
	v_add_f32_e32 v8, v13, v8
	v_pk_mul_f32 v[14:15], v[22:23], v[22:23]
	v_add_f32_e32 v8, v12, v8
	v_add_f32_e32 v8, v15, v8
	v_add_f32_e32 v8, v14, v8
	ds_bpermute_b32 v9, v82, v8
	s_waitcnt lgkmcnt(0)
	v_add_f32_e32 v8, v8, v9
	ds_bpermute_b32 v9, v100, v8
	s_waitcnt lgkmcnt(0)
	v_add_f32_e32 v8, v8, v9
	v_fmamk_f32 v8, v8, 0x3c000000, v98
	v_mul_f32_e32 v9, 0x4b800000, v8
	v_cmp_gt_f32_e32 vcc, s23, v8
	s_nop 1
	v_cndmask_b32_e32 v8, v8, v9, vcc
	v_rsq_f32_e32 v8, v8
	s_nop 0
	v_mul_f32_e32 v9, 0x45800000, v8
	v_cndmask_b32_e32 v8, v8, v9, vcc
	v_mul_f32_e32 v50, 0x3db504f3, v8
	v_mul_f32_e32 v4, v4, v50
	v_mul_f32_e32 v5, v5, v50
	v_mul_f32_e32 v6, v6, v50
	v_mul_f32_e32 v7, v7, v50
	v_mul_f32_e32 v0, v0, v50
	v_mul_f32_e32 v1, v1, v50
	v_mul_f32_e32 v2, v2, v50
	v_mul_f32_e32 v3, v3, v50
	v_mul_f32_e32 v4, v4, v30
	v_mul_f32_e32 v5, v5, v31
	v_mul_f32_e32 v6, v6, v32
	v_mul_f32_e32 v7, v7, v33
	v_mul_f32_e32 v0, v0, v34
	v_mul_f32_e32 v1, v1, v35
	v_mul_f32_e32 v2, v2, v36
	v_mul_f32_e32 v3, v3, v37
	v_cvt_pk_bf16_f32 v8, v4, v5
	v_cvt_pk_bf16_f32 v9, v6, v7
	v_cvt_pk_bf16_f32 v10, v0, v1
	v_cvt_pk_bf16_f32 v11, v2, v3
	global_load_dwordx4 v[0:3], v[24:25], off offset:640
	global_load_dwordx4 v[4:7], v[24:25], off offset:656
	s_waitcnt vmcnt(1)
	v_mul_f32_e32 v0, v0, v50
	v_mul_f32_e32 v1, v1, v50
	v_mul_f32_e32 v2, v2, v50
	v_mul_f32_e32 v3, v3, v50
	s_waitcnt vmcnt(0)
	v_mul_f32_e32 v4, v4, v50
	v_mul_f32_e32 v5, v5, v50
	v_mul_f32_e32 v6, v6, v50
	v_mul_f32_e32 v7, v7, v50
	v_mul_f32_e32 v0, v0, v38
	v_mul_f32_e32 v1, v1, v39
	v_mul_f32_e32 v2, v2, v40
	v_mul_f32_e32 v3, v3, v41
	v_mul_f32_e32 v4, v4, v42
	v_mul_f32_e32 v5, v5, v43
	v_mul_f32_e32 v6, v6, v44
	v_mul_f32_e32 v7, v7, v45
	v_cvt_pk_bf16_f32 v12, v0, v1
	v_cvt_pk_bf16_f32 v13, v2, v3
	v_cvt_pk_bf16_f32 v14, v4, v5
	v_cvt_pk_bf16_f32 v15, v6, v7
	global_load_dwordx4 v[0:3], v[24:25], off offset:768
	global_load_dwordx4 v[4:7], v[24:25], off offset:784
	s_waitcnt vmcnt(1)
	v_mul_f32_e32 v0, v0, v50
	v_mul_f32_e32 v1, v1, v50
	v_mul_f32_e32 v2, v2, v50
	v_mul_f32_e32 v3, v3, v50
	s_waitcnt vmcnt(0)
	v_mul_f32_e32 v4, v4, v50
	v_mul_f32_e32 v5, v5, v50
	v_mul_f32_e32 v6, v6, v50
	v_mul_f32_e32 v7, v7, v50
	v_mul_f32_e32 v0, v0, v46
	v_mul_f32_e32 v1, v1, v16
	v_mul_f32_e32 v2, v2, v47
	v_mul_f32_e32 v3, v3, v17
	v_mul_f32_e32 v16, v4, v48
	v_mul_f32_e32 v17, v5, v18
	v_mul_f32_e32 v18, v6, v49
	v_mul_f32_e32 v7, v7, v19
	v_cvt_pk_bf16_f32 v4, v0, v1
	v_cvt_pk_bf16_f32 v5, v2, v3
	v_cvt_pk_bf16_f32 v6, v16, v17
	v_cvt_pk_bf16_f32 v7, v18, v7
	global_load_dwordx4 v[0:3], v[24:25], off offset:896
	global_load_dwordx4 v[16:19], v[24:25], off offset:912
	s_waitcnt vmcnt(1)
; #define LAS __attribute__((address_space(3)))
; template <bool SAMPLE>
; __device__ __forceinline__ void mem_unit(const Params& p, int l, LAS unsigned char* lds, int unit, int tid, int wave, int lane) {
;     ...
;         f32x4 S[8][2]; float mx = -INFINITY;
; #pragma unroll
;         for (int cc = 0; cc < 8; ++cc)
; #pragma unroll
;             for (int tt = 0; tt < 2; ++tt) { const int kb = 32 * cc + 16 * tt; f32x4 a = (f32x4){0.f, 0.f, 0.f, 0.f};
; #pragma unroll
;                 for (int dc = 0; dc < 4; ++dc) { const bf16x8 kf = *(const LAS bf16x8*)(Kl + (kb + q16) * MEM_KS + 32 * dc + 8 * kq);
;                     a = __builtin_amdgcn_mfma_f32_16x16x32_bf16(kf, qf[dc], a, 0, 0, 0); }
	v_mul_f32_e32 v0, v0, v50
	v_mul_f32_e32 v1, v1, v50
	v_mul_f32_e32 v2, v2, v50
	v_mul_f32_e32 v3, v3, v50
	s_waitcnt vmcnt(0)
	v_mul_f32_e32 v16, v16, v50
	v_mul_f32_e32 v17, v17, v50
	v_mul_f32_e32 v18, v18, v50
	v_mul_f32_e32 v19, v19, v50
	v_mul_f32_e32 v0, v0, v27
	v_mul_f32_e32 v1, v1, v26
	v_mul_f32_e32 v2, v2, v21
	v_mul_f32_e32 v3, v3, v20
	v_mul_f32_e32 v16, v16, v29
	v_mul_f32_e32 v17, v17, v28
	v_mul_f32_e32 v18, v18, v23
	v_mul_f32_e32 v19, v19, v22
	v_cvt_pk_bf16_f32 v0, v0, v1
	v_cvt_pk_bf16_f32 v1, v2, v3
	v_cvt_pk_bf16_f32 v2, v16, v17
	v_cvt_pk_bf16_f32 v3, v18, v19
	ds_read_b128 v[186:189], v91
	ds_read_b128 v[190:193], v91 offset:4352
	ds_read_b128 v[194:197], v91 offset:8704
	ds_read_b128 v[198:201], v91 offset:13056
	ds_read_b128 v[202:205], v91 offset:17408
	ds_read_b128 v[206:209], v91 offset:21760
	ds_read_b128 v[210:213], v91 offset:26112
	s_nop 0
	ds_read_b128 v[20:23], v91 offset:64
	s_nop 0
	ds_read_b128 v[28:31], v91 offset:4416
	s_nop 0
	ds_read_b128 v[36:39], v91 offset:8768
	s_nop 0
	ds_read_b128 v[44:47], v91 offset:13120
	s_nop 0
	ds_read_b128 v[52:55], v91 offset:17472
	s_nop 0
	ds_read_b128 v[60:63], v91 offset:21824
	s_nop 0
	ds_read_b128 v[68:71], v91 offset:26176
	ds_read_b128 v[72:75], v91 offset:30464
	ds_read_b128 v[76:79], v91 offset:30528
	ds_read_b128 v[102:105], v91 offset:34816
	ds_read_b128 v[106:109], v91 offset:34880
	ds_read_b128 v[110:113], v91 offset:39168
	ds_read_b128 v[114:117], v91 offset:39232
	ds_read_b128 v[118:121], v91 offset:43520
	ds_read_b128 v[122:125], v91 offset:43584
	ds_read_b128 v[126:129], v91 offset:47872
	ds_read_b128 v[130:133], v91 offset:47936
	ds_read_b128 v[134:137], v91 offset:52224
	ds_read_b128 v[138:141], v91 offset:52288
	ds_read_b128 v[142:145], v91 offset:56576
	ds_read_b128 v[146:149], v91 offset:56640
	ds_read_b128 v[150:153], v91 offset:60928
	ds_read_b128 v[154:157], v91 offset:60992
	ds_read_b128 v[158:161], v91 offset:65280
	ds_read_b128 v[162:165], v91 offset:65344
	s_waitcnt lgkmcnt(14)
	v_mfma_f32_16x16x32_bf16 v[16:19], v[186:189], v[8:11], 0
	v_mfma_f32_16x16x32_bf16 v[24:27], v[190:193], v[8:11], 0
	v_mfma_f32_16x16x32_bf16 v[32:35], v[194:197], v[8:11], 0
	v_mfma_f32_16x16x32_bf16 v[40:43], v[198:201], v[8:11], 0
	v_mfma_f32_16x16x32_bf16 v[48:51], v[202:205], v[8:11], 0
	v_mfma_f32_16x16x32_bf16 v[56:59], v[206:209], v[8:11], 0
	v_mfma_f32_16x16x32_bf16 v[64:67], v[210:213], v[8:11], 0
	v_mfma_f32_16x16x32_bf16 v[72:75], v[72:75], v[8:11], 0
	v_mfma_f32_16x16x32_bf16 v[102:105], v[102:105], v[8:11], 0
	s_waitcnt lgkmcnt(13)
	v_mfma_f32_16x16x32_bf16 v[110:113], v[110:113], v[8:11], 0
	s_waitcnt lgkmcnt(11)
	v_mfma_f32_16x16x32_bf16 v[118:121], v[118:121], v[8:11], 0
	s_waitcnt lgkmcnt(9)
	v_mfma_f32_16x16x32_bf16 v[126:129], v[126:129], v[8:11], 0
	s_waitcnt lgkmcnt(7)
	v_mfma_f32_16x16x32_bf16 v[134:137], v[134:137], v[8:11], 0
	s_waitcnt lgkmcnt(5)
	v_mfma_f32_16x16x32_bf16 v[142:145], v[142:145], v[8:11], 0
	s_waitcnt lgkmcnt(3)
	v_mfma_f32_16x16x32_bf16 v[150:153], v[150:153], v[8:11], 0
	s_waitcnt lgkmcnt(1)
	v_mfma_f32_16x16x32_bf16 v[8:11], v[158:161], v[8:11], 0
	v_mfma_f32_16x16x32_bf16 v[16:19], v[20:23], v[12:15], v[16:19]
	v_mfma_f32_16x16x32_bf16 v[20:23], v[28:31], v[12:15], v[24:27]
	v_mfma_f32_16x16x32_bf16 v[24:27], v[36:39], v[12:15], v[32:35]
	v_mfma_f32_16x16x32_bf16 v[28:31], v[44:47], v[12:15], v[40:43]
	v_mfma_f32_16x16x32_bf16 v[32:35], v[52:55], v[12:15], v[48:51]
	ds_read_b128 v[202:205], v91 offset:128
	ds_read_b128 v[206:209], v91 offset:4480
	ds_read_b128 v[210:213], v91 offset:8832
	v_mfma_f32_16x16x32_bf16 v[36:39], v[60:63], v[12:15], v[56:59]
	v_mfma_f32_16x16x32_bf16 v[40:43], v[68:71], v[12:15], v[64:67]
	v_mfma_f32_16x16x32_bf16 v[44:47], v[76:79], v[12:15], v[72:75]
	v_mfma_f32_16x16x32_bf16 v[48:51], v[106:109], v[12:15], v[102:105]
	v_mfma_f32_16x16x32_bf16 v[52:55], v[114:117], v[12:15], v[110:113]
	v_mfma_f32_16x16x32_bf16 v[56:59], v[122:125], v[12:15], v[118:121]
	v_mfma_f32_16x16x32_bf16 v[60:63], v[130:133], v[12:15], v[126:129]
	ds_read_b128 v[218:221], v91 offset:13184
	ds_read_b128 v[222:225], v91 offset:17536
	ds_read_b128 v[226:229], v91 offset:21888
	ds_read_b128 v[230:233], v91 offset:26240
	ds_read_b128 v[234:237], v91 offset:30592
	ds_read_b128 v[242:245], v91 offset:34944
	ds_read_b128 v[246:249], v91 offset:39296
	v_mfma_f32_16x16x32_bf16 v[64:67], v[138:141], v[12:15], v[134:137]
	v_mfma_f32_16x16x32_bf16 v[68:71], v[146:149], v[12:15], v[142:145]
	v_mfma_f32_16x16x32_bf16 v[102:105], v[154:157], v[12:15], v[150:153]
	s_waitcnt lgkmcnt(10)
	v_mfma_f32_16x16x32_bf16 v[8:11], v[162:165], v[12:15], v[8:11]
	s_nop 0
	ds_read_b128 v[106:109], v91 offset:192
	s_waitcnt lgkmcnt(10)
	v_mfma_f32_16x16x32_bf16 v[12:15], v[202:205], v[4:7], v[16:19]
	s_nop 2
	s_nop 0
	ds_read_b128 v[110:113], v91 offset:4544
	s_waitcnt lgkmcnt(10)
	v_mfma_f32_16x16x32_bf16 v[16:19], v[206:209], v[4:7], v[20:23]
	s_nop 2
	s_nop 0
	ds_read_b128 v[114:117], v91 offset:8896
	s_waitcnt lgkmcnt(10)
	v_mfma_f32_16x16x32_bf16 v[20:23], v[210:213], v[4:7], v[24:27]
	s_nop 2
	s_nop 0
	ds_read_b128 v[118:121], v91 offset:13248
	s_waitcnt lgkmcnt(10)
	ds_read_b128 v[186:189], v91 offset:43648
	ds_read_b128 v[190:193], v91 offset:48000
	ds_read_b128 v[194:197], v91 offset:52352
	ds_read_b128 v[198:201], v91 offset:56704
	ds_read_b128 v[202:205], v91 offset:61056
	ds_read_b128 v[206:209], v91 offset:65408
	v_mfma_f32_16x16x32_bf16 v[24:27], v[218:221], v[4:7], v[28:31]
	s_nop 2
	s_nop 0
	ds_read_b128 v[122:125], v91 offset:17600
	s_waitcnt lgkmcnt(15)
; #define LAS __attribute__((address_space(3)))
; template <bool SAMPLE>
; __device__ __forceinline__ void mem_unit(const Params& p, int l, LAS unsigned char* lds, int unit, int tid, int wave, int lane) {
;     ...
;         f32x4 S[8][2]; float mx = -INFINITY;
; #pragma unroll
;         for (int cc = 0; cc < 8; ++cc)
; #pragma unroll
;             for (int tt = 0; tt < 2; ++tt) { const int kb = 32 * cc + 16 * tt; f32x4 a = (f32x4){0.f, 0.f, 0.f, 0.f};
; #pragma unroll
;                 for (int dc = 0; dc < 4; ++dc) { const bf16x8 kf = *(const LAS bf16x8*)(Kl + (kb + q16) * MEM_KS + 32 * dc + 8 * kq);
;                     a = __builtin_amdgcn_mfma_f32_16x16x32_bf16(kf, qf[dc], a, 0, 0, 0); }
; #pragma unroll
;                 for (int e = 0; e < 4; ++e) mx = fmaxf(mx, a[e]);
;                 S[cc][tt] = a; }
;         mx = fmaxf(mx, __shfl_xor(mx, 16)); mx = fmaxf(mx, __shfl_xor(mx, 32));
;         float den = 0.f;
; #pragma unroll
;         for (int cc = 0; cc < 8; ++cc)
; #pragma unroll
;             for (int tt = 0; tt < 2; ++tt)
; #pragma unroll
;                 for (int e = 0; e < 4; ++e) { const float pe = __expf(S[cc][tt][e] - mx); S[cc][tt][e] = pe; den += pe; }
	v_mfma_f32_16x16x32_bf16 v[28:31], v[222:225], v[4:7], v[32:35]
	s_nop 2
	s_nop 0
	ds_read_b128 v[126:129], v91 offset:21952
	s_waitcnt lgkmcnt(15)
	v_mfma_f32_16x16x32_bf16 v[32:35], v[226:229], v[4:7], v[36:39]
	s_nop 2
	s_nop 0
	ds_read_b128 v[130:133], v91 offset:26304
	s_waitcnt lgkmcnt(15)
	v_mfma_f32_16x16x32_bf16 v[134:137], v[230:233], v[4:7], v[40:43]
	s_nop 0
	ds_read_b128 v[138:141], v91 offset:30656
	s_waitcnt lgkmcnt(15)
	v_mfma_f32_16x16x32_bf16 v[142:145], v[234:237], v[4:7], v[44:47]
	s_nop 0
	ds_read_b128 v[146:149], v91 offset:35008
	s_waitcnt lgkmcnt(15)
	v_mfma_f32_16x16x32_bf16 v[150:153], v[242:245], v[4:7], v[48:51]
	s_nop 0
	ds_read_b128 v[154:157], v91 offset:39360
	s_waitcnt lgkmcnt(15)
	v_mfma_f32_16x16x32_bf16 v[158:161], v[246:249], v[4:7], v[52:55]
	s_nop 0
	ds_read_b128 v[162:165], v91 offset:43712
	s_waitcnt lgkmcnt(12)
	v_mfma_f32_16x16x32_bf16 v[166:169], v[186:189], v[4:7], v[56:59]
	s_nop 0
	ds_read_b128 v[170:173], v91 offset:48064
	s_waitcnt lgkmcnt(12)
	v_mfma_f32_16x16x32_bf16 v[174:177], v[190:193], v[4:7], v[60:63]
	s_nop 0
	ds_read_b128 v[178:181], v91 offset:52416
	s_waitcnt lgkmcnt(12)
	v_mfma_f32_16x16x32_bf16 v[182:185], v[194:197], v[4:7], v[64:67]
	s_nop 0
	ds_read_b128 v[72:75], v91 offset:56768
	s_waitcnt lgkmcnt(12)
	v_mfma_f32_16x16x32_bf16 v[76:79], v[198:201], v[4:7], v[68:71]
	s_nop 0
	ds_read_b128 v[64:67], v91 offset:61120
	s_waitcnt lgkmcnt(12)
	v_mfma_f32_16x16x32_bf16 v[68:71], v[202:205], v[4:7], v[102:105]
	s_nop 0
	ds_read_b128 v[56:59], v91 offset:65472
	v_lshrrev_b32_e32 v91, 2, v90
	s_waitcnt lgkmcnt(12)
	v_mfma_f32_16x16x32_bf16 v[60:63], v[206:209], v[4:7], v[8:11]
	v_mfma_f32_16x16x32_bf16 v[52:55], v[106:109], v[0:3], v[12:15]
	v_mfma_f32_16x16x32_bf16 v[48:51], v[110:113], v[0:3], v[16:19]
	v_mfma_f32_16x16x32_bf16 v[44:47], v[114:117], v[0:3], v[20:23]
	v_mfma_f32_16x16x32_bf16 v[40:43], v[118:121], v[0:3], v[24:27]
	v_mfma_f32_16x16x32_bf16 v[36:39], v[122:125], v[0:3], v[28:31]
	v_mfma_f32_16x16x32_bf16 v[32:35], v[126:129], v[0:3], v[32:35]
	v_mfma_f32_16x16x32_bf16 v[28:31], v[130:133], v[0:3], v[134:137]
	v_mfma_f32_16x16x32_bf16 v[24:27], v[138:141], v[0:3], v[142:145]
	v_mfma_f32_16x16x32_bf16 v[20:23], v[146:149], v[0:3], v[150:153]
	v_mfma_f32_16x16x32_bf16 v[16:19], v[154:157], v[0:3], v[158:161]
	v_mfma_f32_16x16x32_bf16 v[12:15], v[162:165], v[0:3], v[166:169]
	v_mfma_f32_16x16x32_bf16 v[8:11], v[170:173], v[0:3], v[174:177]
	v_mfma_f32_16x16x32_bf16 v[4:7], v[178:181], v[0:3], v[182:185]
	v_mfma_f32_16x16x32_bf16 v[72:75], v[72:75], v[0:3], v[76:79]
	v_mfma_f32_16x16x32_bf16 v[66:69], v[64:67], v[0:3], v[68:71]
	s_nop 1
	v_lshlrev_b32_e32 v76, 3, v90
	v_add_u32_e32 v77, v91, v92
	v_and_b32_e32 v76, 24, v76
	s_waitcnt lgkmcnt(0)
	v_mfma_f32_16x16x32_bf16 v[0:3], v[56:59], v[0:3], v[60:63]
	v_max3_f32 v56, v52, s24, v53
	v_max3_f32 v56, v56, v54, v55
	v_max3_f32 v56, v56, v48, v49
	v_max3_f32 v56, v56, v50, v51
	v_max3_f32 v56, v56, v44, v45
	v_max3_f32 v56, v56, v46, v47
	v_max3_f32 v56, v56, v40, v41
	v_max3_f32 v56, v56, v42, v43
	v_max3_f32 v56, v56, v36, v37
	v_max3_f32 v56, v56, v38, v39
	v_max3_f32 v56, v56, v32, v33
	v_max3_f32 v56, v56, v34, v35
	v_max3_f32 v56, v56, v28, v29
	v_max3_f32 v56, v56, v30, v31
	v_max3_f32 v56, v56, v24, v25
	v_max3_f32 v56, v56, v26, v27
	v_max3_f32 v56, v56, v20, v21
	v_max3_f32 v56, v56, v22, v23
	v_max3_f32 v56, v56, v16, v17
	v_max3_f32 v56, v56, v18, v19
	v_max3_f32 v56, v56, v12, v13
	v_max3_f32 v56, v56, v14, v15
	v_max3_f32 v56, v56, v8, v9
	v_max3_f32 v56, v56, v10, v11
	v_max3_f32 v56, v56, v4, v5
	v_max3_f32 v56, v56, v6, v7
	v_max3_f32 v56, v56, v72, v73
	v_max3_f32 v56, v56, v74, v75
	v_max3_f32 v56, v56, v66, v67
	v_max3_f32 v56, v56, v68, v69
	v_max3_f32 v56, v56, v0, v1
	v_max3_f32 v56, v56, v2, v3
	ds_bpermute_b32 v57, v82, v56
	v_mul_lo_u32 v64, v77, s22
	v_add3_u32 v64, s90, v76, v64
	s_waitcnt lgkmcnt(0)
	v_max_f32_e32 v57, v57, v57
	v_max_f32_e32 v56, v56, v57
	ds_bpermute_b32 v57, v100, v56
	s_waitcnt lgkmcnt(0)
	v_max_f32_e32 v57, v57, v57
	v_max_f32_e32 v56, v56, v57
	v_sub_f32_e32 v52, v52, v56
	v_sub_f32_e32 v53, v53, v56
	v_mul_f32_e32 v52, 0x3fb8aa3b, v52
	v_sub_f32_e32 v54, v54, v56
	v_sub_f32_e32 v57, v72, v56
	v_sub_f32_e32 v58, v73, v56
	v_sub_f32_e32 v59, v74, v56
	v_sub_f32_e32 v60, v75, v56
	v_sub_f32_e32 v61, v66, v56
	v_sub_f32_e32 v62, v67, v56
	v_sub_f32_e32 v63, v68, v56
	v_sub_f32_e32 v65, v69, v56
	v_mul_f32_e32 v53, 0x3fb8aa3b, v53
	v_exp_f32_e32 v52, v52
	v_sub_f32_e32 v55, v55, v56
	v_sub_f32_e32 v48, v48, v56
	v_sub_f32_e32 v49, v49, v56
	v_sub_f32_e32 v50, v50, v56
	v_sub_f32_e32 v51, v51, v56
	v_sub_f32_e32 v44, v44, v56
	v_sub_f32_e32 v45, v45, v56
	v_sub_f32_e32 v46, v46, v56
	v_sub_f32_e32 v47, v47, v56
	v_sub_f32_e32 v40, v40, v56
	v_sub_f32_e32 v41, v41, v56
	v_sub_f32_e32 v42, v42, v56
	v_sub_f32_e32 v43, v43, v56
	v_sub_f32_e32 v36, v36, v56
	v_sub_f32_e32 v37, v37, v56
	v_sub_f32_e32 v38, v38, v56
	v_sub_f32_e32 v39, v39, v56
	v_sub_f32_e32 v32, v32, v56
	v_sub_f32_e32 v33, v33, v56
	v_sub_f32_e32 v34, v34, v56
	v_sub_f32_e32 v35, v35, v56
	v_sub_f32_e32 v28, v28, v56
	v_sub_f32_e32 v29, v29, v56
	v_sub_f32_e32 v30, v30, v56
	v_sub_f32_e32 v31, v31, v56
	v_sub_f32_e32 v24, v24, v56
	v_sub_f32_e32 v25, v25, v56
	v_sub_f32_e32 v26, v26, v56
	v_sub_f32_e32 v27, v27, v56
	v_sub_f32_e32 v20, v20, v56
	v_sub_f32_e32 v21, v21, v56
	v_sub_f32_e32 v22, v22, v56
	v_sub_f32_e32 v23, v23, v56
	v_sub_f32_e32 v16, v16, v56
	v_sub_f32_e32 v17, v17, v56
	v_sub_f32_e32 v18, v18, v56
	v_sub_f32_e32 v19, v19, v56
	v_sub_f32_e32 v12, v12, v56
	v_sub_f32_e32 v13, v13, v56
; #define LAS __attribute__((address_space(3)))
; __device__ __forceinline__ bf16x8 pack8(const float (&o)[8]) { v4u w; w.x = pk2(o[0], o[1]); w.y = pk2(o[2], o[3]); w.z = pk2(o[4], o[5]); w.w = pk2(o[6], o[7]); return __builtin_bit_cast(bf16x8, w); }
; __device__ __forceinline__ v2u vtr(const LAS bf16* p) { return __builtin_bit_cast(v2u, __builtin_amdgcn_ds_read_tr16_b64_v4i16((LAS v4i16_t*)p)); }
; template <bool SAMPLE>
; __device__ __forceinline__ void mem_unit(const Params& p, int l, LAS unsigned char* lds, int unit, int tid, int wave, int lane) {
;     ...
;         float den = 0.f;
; #pragma unroll
;         for (int cc = 0; cc < 8; ++cc)
; #pragma unroll
;             for (int tt = 0; tt < 2; ++tt)
; #pragma unroll
;                 for (int e = 0; e < 4; ++e) { const float pe = __expf(S[cc][tt][e] - mx); S[cc][tt][e] = pe; den += pe; }
;         den += __shfl_xor(den, 16); den += __shfl_xor(den, 32);
;         const float rden = 1.f / den;
;         bf16x8 pf[8];
; #pragma unroll
;         for (int cc = 0; cc < 8; ++cc) { float t8[8];
; #pragma unroll
;             for (int e = 0; e < 4; ++e) { t8[e] = S[cc][0][e]; t8[4 + e] = S[cc][1][e]; }
;             pf[cc] = pack8(t8); }
; #pragma unroll
;         for (int dt = 0; dt < 8; ++dt) { f32x4 o = (f32x4){0.f, 0.f, 0.f, 0.f};
; #pragma unroll
;             for (int cc = 0; cc < 8; ++cc) { const LAS bf16* vp = Vt + (32 * cc + 4 * kq + (q16 >> 2)) * MEM_VS + 16 * dt + 4 * (q16 & 3);
;                 const v2u lo = vtr(vp), hi = vtr(vp + 16 * MEM_VS);
	v_sub_f32_e32 v14, v14, v56
	v_sub_f32_e32 v15, v15, v56
	v_sub_f32_e32 v8, v8, v56
	v_sub_f32_e32 v9, v9, v56
	v_sub_f32_e32 v10, v10, v56
	v_sub_f32_e32 v11, v11, v56
	v_sub_f32_e32 v4, v4, v56
	v_sub_f32_e32 v5, v5, v56
	v_sub_f32_e32 v6, v6, v56
	v_sub_f32_e32 v7, v7, v56
	v_sub_f32_e32 v0, v0, v56
	v_sub_f32_e32 v1, v1, v56
	v_sub_f32_e32 v2, v2, v56
	v_sub_f32_e32 v3, v3, v56
	v_mul_f32_e32 v54, 0x3fb8aa3b, v54
	v_mul_f32_e32 v56, 0x3fb8aa3b, v57
	v_mul_f32_e32 v57, 0x3fb8aa3b, v58
	v_mul_f32_e32 v58, 0x3fb8aa3b, v59
	v_mul_f32_e32 v59, 0x3fb8aa3b, v60
	v_mul_f32_e32 v60, 0x3fb8aa3b, v61
	v_mul_f32_e32 v61, 0x3fb8aa3b, v62
	v_mul_f32_e32 v62, 0x3fb8aa3b, v63
	v_mul_f32_e32 v63, 0x3fb8aa3b, v65
	v_exp_f32_e32 v65, v53
	v_mul_f32_e32 v55, 0x3fb8aa3b, v55
	v_exp_f32_e32 v66, v54
	v_mul_f32_e32 v48, 0x3fb8aa3b, v48
	v_exp_f32_e32 v67, v55
	v_mul_f32_e32 v49, 0x3fb8aa3b, v49
	v_mul_f32_e32 v0, 0x3fb8aa3b, v0
	v_exp_f32_e32 v68, v48
	v_add_f32_e32 v147, 0, v52
	v_mul_f32_e32 v50, 0x3fb8aa3b, v50
	v_exp_f32_e32 v69, v49
	v_exp_f32_e32 v143, v0
	v_cvt_pk_bf16_f32 v0, v52, v65
	v_add_f32_e32 v65, v65, v147
	v_mul_f32_e32 v51, 0x3fb8aa3b, v51
	v_exp_f32_e32 v70, v50
	v_add_f32_e32 v65, v66, v65
	v_mul_f32_e32 v44, 0x3fb8aa3b, v44
	v_exp_f32_e32 v71, v51
	v_add_f32_e32 v65, v67, v65
	v_mul_f32_e32 v45, 0x3fb8aa3b, v45
	v_exp_f32_e32 v72, v44
	v_add_f32_e32 v65, v68, v65
	v_mul_f32_e32 v46, 0x3fb8aa3b, v46
	v_exp_f32_e32 v73, v45
	v_add_f32_e32 v65, v69, v65
	v_mul_f32_e32 v47, 0x3fb8aa3b, v47
	v_exp_f32_e32 v74, v46
	v_add_f32_e32 v65, v70, v65
	v_mul_f32_e32 v40, 0x3fb8aa3b, v40
	v_exp_f32_e32 v75, v47
	v_add_f32_e32 v65, v71, v65
	v_mul_f32_e32 v41, 0x3fb8aa3b, v41
	v_mul_f32_e32 v42, 0x3fb8aa3b, v42
	v_mul_f32_e32 v43, 0x3fb8aa3b, v43
	v_mul_f32_e32 v36, 0x3fb8aa3b, v36
	v_mul_f32_e32 v37, 0x3fb8aa3b, v37
	v_mul_f32_e32 v38, 0x3fb8aa3b, v38
	v_mul_f32_e32 v39, 0x3fb8aa3b, v39
	v_mul_f32_e32 v32, 0x3fb8aa3b, v32
	v_mul_f32_e32 v33, 0x3fb8aa3b, v33
	v_mul_f32_e32 v34, 0x3fb8aa3b, v34
	v_mul_f32_e32 v35, 0x3fb8aa3b, v35
	v_mul_f32_e32 v28, 0x3fb8aa3b, v28
	v_mul_f32_e32 v29, 0x3fb8aa3b, v29
	v_mul_f32_e32 v30, 0x3fb8aa3b, v30
	v_mul_f32_e32 v31, 0x3fb8aa3b, v31
	v_mul_f32_e32 v24, 0x3fb8aa3b, v24
	v_mul_f32_e32 v25, 0x3fb8aa3b, v25
	v_mul_f32_e32 v26, 0x3fb8aa3b, v26
	v_mul_f32_e32 v27, 0x3fb8aa3b, v27
	v_mul_f32_e32 v20, 0x3fb8aa3b, v20
	v_mul_f32_e32 v21, 0x3fb8aa3b, v21
	v_mul_f32_e32 v22, 0x3fb8aa3b, v22
	v_mul_f32_e32 v23, 0x3fb8aa3b, v23
	v_mul_f32_e32 v16, 0x3fb8aa3b, v16
	v_mul_f32_e32 v17, 0x3fb8aa3b, v17
	v_mul_f32_e32 v18, 0x3fb8aa3b, v18
	v_mul_f32_e32 v19, 0x3fb8aa3b, v19
	v_mul_f32_e32 v12, 0x3fb8aa3b, v12
	v_mul_f32_e32 v13, 0x3fb8aa3b, v13
	v_mul_f32_e32 v14, 0x3fb8aa3b, v14
	v_mul_f32_e32 v15, 0x3fb8aa3b, v15
	v_mul_f32_e32 v8, 0x3fb8aa3b, v8
	v_mul_f32_e32 v9, 0x3fb8aa3b, v9
	v_mul_f32_e32 v10, 0x3fb8aa3b, v10
	v_mul_f32_e32 v11, 0x3fb8aa3b, v11
	v_mul_f32_e32 v4, 0x3fb8aa3b, v4
	v_mul_f32_e32 v5, 0x3fb8aa3b, v5
	v_mul_f32_e32 v6, 0x3fb8aa3b, v6
	v_mul_f32_e32 v7, 0x3fb8aa3b, v7
	v_mul_f32_e32 v1, 0x3fb8aa3b, v1
	v_mul_f32_e32 v2, 0x3fb8aa3b, v2
	v_mul_f32_e32 v3, 0x3fb8aa3b, v3
	v_exp_f32_e32 v76, v40
	v_add_f32_e32 v65, v72, v65
	v_exp_f32_e32 v77, v41
	v_exp_f32_e32 v78, v42
	v_exp_f32_e32 v79, v43
	v_exp_f32_e32 v90, v36
	v_exp_f32_e32 v91, v37
	v_exp_f32_e32 v101, v38
	v_exp_f32_e32 v102, v39
	v_exp_f32_e32 v103, v32
	v_exp_f32_e32 v104, v33
	v_exp_f32_e32 v105, v34
	v_exp_f32_e32 v106, v35
	v_exp_f32_e32 v107, v28
	v_exp_f32_e32 v108, v29
	v_exp_f32_e32 v109, v30
	v_exp_f32_e32 v110, v31
	v_exp_f32_e32 v111, v24
	v_exp_f32_e32 v112, v25
	v_exp_f32_e32 v113, v26
	v_exp_f32_e32 v114, v27
	v_exp_f32_e32 v115, v20
	v_exp_f32_e32 v116, v21
	v_exp_f32_e32 v117, v22
	v_exp_f32_e32 v118, v23
	v_exp_f32_e32 v119, v16
	v_exp_f32_e32 v120, v17
	v_exp_f32_e32 v121, v18
	v_exp_f32_e32 v122, v19
	v_exp_f32_e32 v123, v12
	v_exp_f32_e32 v124, v13
	v_exp_f32_e32 v125, v14
	v_exp_f32_e32 v126, v15
	v_exp_f32_e32 v127, v8
	v_exp_f32_e32 v128, v9
	v_exp_f32_e32 v129, v10
	v_exp_f32_e32 v130, v11
	v_exp_f32_e32 v131, v4
	v_exp_f32_e32 v132, v5
	v_exp_f32_e32 v133, v6
	v_exp_f32_e32 v134, v7
	v_exp_f32_e32 v135, v56
	v_exp_f32_e32 v136, v57
	v_exp_f32_e32 v137, v58
	v_exp_f32_e32 v138, v59
	v_exp_f32_e32 v139, v60
	v_exp_f32_e32 v140, v61
	v_exp_f32_e32 v141, v62
	v_exp_f32_e32 v142, v63
	v_exp_f32_e32 v144, v1
	v_exp_f32_e32 v145, v2
	v_exp_f32_e32 v146, v3
	v_cvt_pk_bf16_f32 v1, v66, v67
	v_cvt_pk_bf16_f32 v2, v68, v69
	v_cvt_pk_bf16_f32 v3, v70, v71
	v_cvt_pk_bf16_f32 v4, v72, v73
	v_cvt_pk_bf16_f32 v5, v74, v75
	v_cvt_pk_bf16_f32 v6, v76, v77
	v_cvt_pk_bf16_f32 v7, v78, v79
	v_cvt_pk_bf16_f32 v8, v90, v91
	v_cvt_pk_bf16_f32 v9, v101, v102
	v_cvt_pk_bf16_f32 v10, v103, v104
	v_cvt_pk_bf16_f32 v11, v105, v106
	v_cvt_pk_bf16_f32 v12, v107, v108
	v_cvt_pk_bf16_f32 v13, v109, v110
	v_cvt_pk_bf16_f32 v14, v111, v112
	v_cvt_pk_bf16_f32 v15, v113, v114
	v_cvt_pk_bf16_f32 v16, v115, v116
	v_cvt_pk_bf16_f32 v17, v117, v118
	v_cvt_pk_bf16_f32 v18, v119, v120
	v_cvt_pk_bf16_f32 v19, v121, v122
	v_cvt_pk_bf16_f32 v24, v123, v124
	v_cvt_pk_bf16_f32 v25, v125, v126
	v_cvt_pk_bf16_f32 v26, v127, v128
	v_cvt_pk_bf16_f32 v27, v129, v130
	v_cvt_pk_bf16_f32 v28, v131, v132
	v_cvt_pk_bf16_f32 v29, v133, v134
	v_cvt_pk_bf16_f32 v30, v135, v136
	v_cvt_pk_bf16_f32 v31, v137, v138
	v_cvt_pk_bf16_f32 v20, v139, v140
	v_cvt_pk_bf16_f32 v21, v141, v142
	v_cvt_pk_bf16_f32 v22, v143, v144
	v_cvt_pk_bf16_f32 v23, v145, v146
	ds_read_b64_tr_b16 v[32:33], v64
	ds_read_b64_tr_b16 v[34:35], v64 offset:4352
	ds_read_b64_tr_b16 v[36:37], v64 offset:8704
	ds_read_b64_tr_b16 v[38:39], v64 offset:13056
	ds_read_b64_tr_b16 v[40:41], v64 offset:17408
	ds_read_b64_tr_b16 v[42:43], v64 offset:21760
	ds_read_b64_tr_b16 v[44:45], v64 offset:26112
	ds_read_b64_tr_b16 v[46:47], v64 offset:30464
	ds_read_b64_tr_b16 v[48:49], v64 offset:34816
	ds_read_b64_tr_b16 v[50:51], v64 offset:39168
	ds_read_b64_tr_b16 v[52:53], v64 offset:43520
	ds_read_b64_tr_b16 v[54:55], v64 offset:47872
	ds_read_b64_tr_b16 v[56:57], v64 offset:52224
	ds_read_b64_tr_b16 v[58:59], v64 offset:56576
	ds_read_b64_tr_b16 v[60:61], v64 offset:60928
	ds_read_b64_tr_b16 v[62:63], v64 offset:65280
	v_add_f32_e32 v65, v73, v65
	s_waitcnt lgkmcnt(14)
; #define LAS __attribute__((address_space(3)))
; __device__ __forceinline__ unsigned pk2(float lo, float hi) { return pg8::cvt_pk_bf16(lo, hi); }
; __device__ __forceinline__ bf16x8 pack8(const float (&o)[8]) { v4u w; w.x = pk2(o[0], o[1]); w.y = pk2(o[2], o[3]); w.z = pk2(o[4], o[5]); w.w = pk2(o[6], o[7]); return __builtin_bit_cast(bf16x8, w); }
; __device__ __forceinline__ v2u vtr(const LAS bf16* p) { return __builtin_bit_cast(v2u, __builtin_amdgcn_ds_read_tr16_b64_v4i16((LAS v4i16_t*)p)); }
; template <bool SAMPLE>
; __device__ __forceinline__ void mem_unit(const Params& p, int l, LAS unsigned char* lds, int unit, int tid, int wave, int lane) {
;     ...
;         den += __shfl_xor(den, 16); den += __shfl_xor(den, 32);
;         const float rden = 1.f / den;
;         bf16x8 pf[8];
; #pragma unroll
;         for (int cc = 0; cc < 8; ++cc) { float t8[8];
; #pragma unroll
;             for (int e = 0; e < 4; ++e) { t8[e] = S[cc][0][e]; t8[4 + e] = S[cc][1][e]; }
;             pf[cc] = pack8(t8); }
; #pragma unroll
;         for (int dt = 0; dt < 8; ++dt) { f32x4 o = (f32x4){0.f, 0.f, 0.f, 0.f};
; #pragma unroll
;             for (int cc = 0; cc < 8; ++cc) { const LAS bf16* vp = Vt + (32 * cc + 4 * kq + (q16 >> 2)) * MEM_VS + 16 * dt + 4 * (q16 & 3);
;                 const v2u lo = vtr(vp), hi = vtr(vp + 16 * MEM_VS);
;                 v4u av; av.x = lo.x; av.y = lo.y; av.z = hi.x; av.w = hi.y;
;                 o = __builtin_amdgcn_mfma_f32_16x16x32_bf16(__builtin_bit_cast(bf16x8, av), pf[cc], o, 0, 0, 0); }
;             if (st) { v2u w; w.x = pk2(o[0] * rden, o[1] * rden); w.y = pk2(o[2] * rden, o[3] * rden);
;                 *(v2u*)(MO + row * 512 + h * 128 + 16 * dt + 4 * kq) = w; } }
	v_mfma_f32_16x16x32_bf16 v[32:35], v[32:35], v[0:3], 0
	v_add_f32_e32 v65, v74, v65
	v_add_f32_e32 v65, v75, v65
	v_add_f32_e32 v65, v76, v65
	v_add_f32_e32 v65, v77, v65
	s_waitcnt lgkmcnt(12)
	v_mfma_f32_16x16x32_bf16 v[32:35], v[36:39], v[4:7], v[32:35]
	v_add_f32_e32 v36, v78, v65
	v_add_f32_e32 v36, v79, v36
	v_add_f32_e32 v36, v90, v36
	v_add_f32_e32 v36, v91, v36
	s_waitcnt lgkmcnt(10)
	v_mfma_f32_16x16x32_bf16 v[32:35], v[40:43], v[8:11], v[32:35]
	v_add_f32_e32 v36, v101, v36
	v_add_f32_e32 v36, v102, v36
	v_add_f32_e32 v36, v103, v36
	v_add_f32_e32 v36, v104, v36
	s_waitcnt lgkmcnt(8)
	v_mfma_f32_16x16x32_bf16 v[32:35], v[44:47], v[12:15], v[32:35]
	v_add_f32_e32 v36, v105, v36
	v_add_f32_e32 v36, v106, v36
	v_add_f32_e32 v36, v107, v36
	v_add_f32_e32 v36, v108, v36
	s_waitcnt lgkmcnt(6)
	ds_read_b64_tr_b16 v[186:187], v64 offset:52256
	ds_read_b64_tr_b16 v[188:189], v64 offset:56608
	ds_read_b64_tr_b16 v[190:191], v64 offset:60960
	ds_read_b64_tr_b16 v[192:193], v64 offset:65312
	ds_read_b64_tr_b16 v[194:195], v64 offset:64
	ds_read_b64_tr_b16 v[196:197], v64 offset:4416
	ds_read_b64_tr_b16 v[198:199], v64 offset:8768
	ds_read_b64_tr_b16 v[200:201], v64 offset:13120
	ds_read_b64_tr_b16 v[202:203], v64 offset:17472
	ds_read_b64_tr_b16 v[204:205], v64 offset:21824
	ds_read_b64_tr_b16 v[206:207], v64 offset:26176
	ds_read_b64_tr_b16 v[208:209], v64 offset:30528
	ds_read_b64_tr_b16 v[210:211], v64 offset:34880
	ds_read_b64_tr_b16 v[212:213], v64 offset:39232
	v_mfma_f32_16x16x32_bf16 v[32:35], v[48:51], v[16:19], v[32:35]
	v_add_f32_e32 v36, v109, v36
	v_add_f32_e32 v36, v110, v36
	v_add_f32_e32 v36, v111, v36
	v_add_f32_e32 v36, v112, v36
	s_waitcnt lgkmcnt(15)
	v_mfma_f32_16x16x32_bf16 v[32:35], v[52:55], v[24:27], v[32:35]
	v_add_f32_e32 v36, v113, v36
	v_add_f32_e32 v36, v114, v36
	v_add_f32_e32 v36, v115, v36
	v_add_f32_e32 v36, v116, v36
	s_waitcnt lgkmcnt(15)
	v_mfma_f32_16x16x32_bf16 v[32:35], v[56:59], v[28:31], v[32:35]
	v_add_f32_e32 v36, v117, v36
	v_add_f32_e32 v36, v118, v36
	v_add_f32_e32 v36, v119, v36
	v_add_f32_e32 v40, v120, v36
	s_waitcnt lgkmcnt(14)
	v_mfma_f32_16x16x32_bf16 v[36:39], v[60:63], v[20:23], v[32:35]
	s_nop 2
	v_add_f32_e32 v32, v121, v40
	v_add_f32_e32 v32, v122, v32
	v_add_f32_e32 v32, v123, v32
	v_add_f32_e32 v32, v124, v32
	v_add_f32_e32 v32, v125, v32
	v_add_f32_e32 v32, v126, v32
	v_add_f32_e32 v32, v127, v32
	v_add_f32_e32 v32, v128, v32
	v_add_f32_e32 v32, v129, v32
	v_add_f32_e32 v32, v130, v32
	v_add_f32_e32 v32, v131, v32
	v_add_f32_e32 v32, v132, v32
	v_add_f32_e32 v32, v133, v32
	v_add_f32_e32 v32, v134, v32
	v_add_f32_e32 v32, v135, v32
	v_add_f32_e32 v32, v136, v32
	v_add_f32_e32 v32, v137, v32
	v_add_f32_e32 v32, v138, v32
	v_add_f32_e32 v32, v139, v32
	v_add_f32_e32 v32, v140, v32
	v_add_f32_e32 v32, v141, v32
	v_add_f32_e32 v32, v142, v32
	v_add_f32_e32 v32, v143, v32
	v_add_f32_e32 v32, v144, v32
	v_add_f32_e32 v32, v145, v32
	v_add_f32_e32 v32, v146, v32
	ds_bpermute_b32 v33, v82, v32
	s_waitcnt lgkmcnt(0)
	v_add_f32_e32 v32, v32, v33
	ds_bpermute_b32 v33, v100, v32
	s_waitcnt lgkmcnt(0)
	v_add_f32_e32 v32, v32, v33
	v_div_scale_f32 v33, s[16:17], v32, v32, 1.0
	v_rcp_f32_e32 v35, v33
	v_div_scale_f32 v34, vcc, 1.0, v32, 1.0
	v_fma_f32 v40, -v33, v35, 1.0
	v_fmac_f32_e32 v35, v40, v35
	v_mul_f32_e32 v40, v34, v35
	v_fma_f32 v41, -v33, v40, v34
	v_fmac_f32_e32 v40, v41, v35
	v_fma_f32 v33, -v33, v40, v34
	v_div_fmas_f32 v33, v33, v35, v40
	v_div_fixup_f32 v34, v33, v32, 1.0
	v_mul_f32_e32 v32, v36, v34
	v_mul_f32_e32 v36, v39, v34
	v_mul_f32_e32 v33, v37, v34
	v_mul_f32_e32 v35, v38, v34
	v_cvt_pk_bf16_f32 v52, v32, v33
	v_cvt_pk_bf16_f32 v53, v35, v36
	ds_read_b64_tr_b16 v[36:37], v64 offset:32
	ds_read_b64_tr_b16 v[38:39], v64 offset:4384
	ds_read_b64_tr_b16 v[40:41], v64 offset:8736
	ds_read_b64_tr_b16 v[42:43], v64 offset:13088
	ds_read_b64_tr_b16 v[44:45], v64 offset:17440
	s_waitcnt lgkmcnt(3)
	v_mfma_f32_16x16x32_bf16 v[36:39], v[36:39], v[0:3], 0
	ds_read_b64_tr_b16 v[46:47], v64 offset:21792
	ds_read_b64_tr_b16 v[48:49], v64 offset:26144
	v_lshl_add_u64 v[32:33], s[2:3], 0, v[88:89]
	v_lshl_add_u64 v[32:33], v[92:93], 1, v[32:33]
	s_waitcnt lgkmcnt(3)
	v_mfma_f32_16x16x32_bf16 v[36:39], v[40:43], v[4:7], v[36:39]
	ds_read_b64_tr_b16 v[50:51], v64 offset:30496
	ds_read_b64_tr_b16 v[40:41], v64 offset:34848
	s_waitcnt lgkmcnt(3)
	v_mfma_f32_16x16x32_bf16 v[36:39], v[44:47], v[8:11], v[36:39]
	ds_read_b64_tr_b16 v[42:43], v64 offset:39200
	ds_read_b64_tr_b16 v[44:45], v64 offset:43552
	s_waitcnt lgkmcnt(3)
	v_mfma_f32_16x16x32_bf16 v[36:39], v[48:51], v[12:15], v[36:39]
	ds_read_b64_tr_b16 v[46:47], v64 offset:47904
	s_nop 0
	s_waitcnt lgkmcnt(2)
	v_mfma_f32_16x16x32_bf16 v[36:39], v[40:43], v[16:19], v[36:39]
	s_nop 2
	global_store_dwordx2 v[32:33], v[52:53], off
	s_waitcnt lgkmcnt(0)
	v_mfma_f32_16x16x32_bf16 v[36:39], v[44:47], v[24:27], v[36:39]
	s_nop 0
	ds_read_b64_tr_b16 v[218:219], v64 offset:43584
	ds_read_b64_tr_b16 v[220:221], v64 offset:47936
	ds_read_b64_tr_b16 v[222:223], v64 offset:52288
	ds_read_b64_tr_b16 v[224:225], v64 offset:56640
	ds_read_b64_tr_b16 v[226:227], v64 offset:60992
	ds_read_b64_tr_b16 v[228:229], v64 offset:65344
	ds_read_b64_tr_b16 v[230:231], v64 offset:96
	ds_read_b64_tr_b16 v[232:233], v64 offset:4448
	ds_read_b64_tr_b16 v[234:235], v64 offset:8800
	ds_read_b64_tr_b16 v[236:237], v64 offset:13152
	ds_read_b64_tr_b16 v[242:243], v64 offset:17504
	ds_read_b64_tr_b16 v[244:245], v64 offset:21856
	ds_read_b64_tr_b16 v[246:247], v64 offset:26208
	ds_read_b64_tr_b16 v[248:249], v64 offset:30560
	v_mfma_f32_16x16x32_bf16 v[36:39], v[186:189], v[28:31], v[36:39]
	s_nop 0
	v_mfma_f32_16x16x32_bf16 v[36:39], v[190:193], v[20:23], v[36:39]
	s_nop 7
	v_mul_f32_e32 v35, v34, v36
	v_mul_f32_e32 v36, v34, v37
	v_mul_f32_e32 v37, v34, v38
	v_mul_f32_e32 v38, v34, v39
	v_cvt_pk_bf16_f32 v52, v35, v36
	v_cvt_pk_bf16_f32 v53, v37, v38
	s_nop 5
	v_mfma_f32_16x16x32_bf16 v[36:39], v[194:197], v[0:3], 0
	s_nop 2
	v_mfma_f32_16x16x32_bf16 v[36:39], v[198:201], v[4:7], v[36:39]
	s_nop 2
	v_mfma_f32_16x16x32_bf16 v[36:39], v[202:205], v[8:11], v[36:39]
	s_nop 2
	v_mfma_f32_16x16x32_bf16 v[36:39], v[206:209], v[12:15], v[36:39]
	s_nop 2
	v_mfma_f32_16x16x32_bf16 v[36:39], v[210:213], v[16:19], v[36:39]
	s_nop 2
	global_store_dwordx2 v[32:33], v[52:53], off offset:32
	s_waitcnt lgkmcnt(12)
; #define LAS __attribute__((address_space(3)))
; __device__ __forceinline__ unsigned pk2(float lo, float hi) { return pg8::cvt_pk_bf16(lo, hi); }
; __device__ __forceinline__ v2u vtr(const LAS bf16* p) { return __builtin_bit_cast(v2u, __builtin_amdgcn_ds_read_tr16_b64_v4i16((LAS v4i16_t*)p)); }
; template <bool SAMPLE>
; __device__ __forceinline__ void mem_unit(const Params& p, int l, LAS unsigned char* lds, int unit, int tid, int wave, int lane) {
;     ...
; #pragma unroll
;         for (int dt = 0; dt < 8; ++dt) { f32x4 o = (f32x4){0.f, 0.f, 0.f, 0.f};
; #pragma unroll
;             for (int cc = 0; cc < 8; ++cc) { const LAS bf16* vp = Vt + (32 * cc + 4 * kq + (q16 >> 2)) * MEM_VS + 16 * dt + 4 * (q16 & 3);
;                 const v2u lo = vtr(vp), hi = vtr(vp + 16 * MEM_VS);
;                 v4u av; av.x = lo.x; av.y = lo.y; av.z = hi.x; av.w = hi.y;
;                 o = __builtin_amdgcn_mfma_f32_16x16x32_bf16(__builtin_bit_cast(bf16x8, av), pf[cc], o, 0, 0, 0); }
;             if (st) { v2u w; w.x = pk2(o[0] * rden, o[1] * rden); w.y = pk2(o[2] * rden, o[3] * rden);
;                 *(v2u*)(MO + row * 512 + h * 128 + 16 * dt + 4 * kq) = w; } }
	ds_read_b64_tr_b16 v[186:187], v64 offset:34912
	ds_read_b64_tr_b16 v[188:189], v64 offset:39264
	ds_read_b64_tr_b16 v[190:191], v64 offset:43616
	ds_read_b64_tr_b16 v[192:193], v64 offset:47968
	ds_read_b64_tr_b16 v[194:195], v64 offset:52320
	ds_read_b64_tr_b16 v[196:197], v64 offset:56672
	ds_read_b64_tr_b16 v[198:199], v64 offset:61024
	ds_read_b64_tr_b16 v[200:201], v64 offset:65376
	ds_read_b64_tr_b16 v[202:203], v64 offset:128
	ds_read_b64_tr_b16 v[204:205], v64 offset:4480
	ds_read_b64_tr_b16 v[206:207], v64 offset:8832
	ds_read_b64_tr_b16 v[208:209], v64 offset:13184
	ds_read_b64_tr_b16 v[210:211], v64 offset:17536
	ds_read_b64_tr_b16 v[212:213], v64 offset:21888
	v_mfma_f32_16x16x32_bf16 v[36:39], v[218:221], v[24:27], v[36:39]
	s_waitcnt lgkmcnt(15)
	v_mfma_f32_16x16x32_bf16 v[36:39], v[222:225], v[28:31], v[36:39]
	s_waitcnt lgkmcnt(15)
	v_mfma_f32_16x16x32_bf16 v[36:39], v[226:229], v[20:23], v[36:39]
	s_nop 7
	v_mul_f32_e32 v35, v34, v36
	v_mul_f32_e32 v36, v34, v37
	v_mul_f32_e32 v37, v34, v38
	v_mul_f32_e32 v38, v34, v39
	v_cvt_pk_bf16_f32 v52, v35, v36
	v_cvt_pk_bf16_f32 v53, v37, v38
	s_nop 4
	s_waitcnt lgkmcnt(15)
	v_mfma_f32_16x16x32_bf16 v[36:39], v[230:233], v[0:3], 0
	s_nop 1
	s_waitcnt lgkmcnt(15)
	v_mfma_f32_16x16x32_bf16 v[36:39], v[234:237], v[4:7], v[36:39]
	s_nop 1
	s_waitcnt lgkmcnt(15)
	v_mfma_f32_16x16x32_bf16 v[36:39], v[242:245], v[8:11], v[36:39]
	s_nop 1
	s_waitcnt lgkmcnt(14)
	v_mfma_f32_16x16x32_bf16 v[36:39], v[246:249], v[12:15], v[36:39]
	s_nop 1
	s_waitcnt lgkmcnt(12)
	ds_read_b64_tr_b16 v[218:219], v64 offset:26240
	ds_read_b64_tr_b16 v[220:221], v64 offset:30592
	ds_read_b64_tr_b16 v[222:223], v64 offset:34944
	ds_read_b64_tr_b16 v[224:225], v64 offset:39296
	ds_read_b64_tr_b16 v[226:227], v64 offset:43648
	ds_read_b64_tr_b16 v[228:229], v64 offset:48000
	ds_read_b64_tr_b16 v[230:231], v64 offset:52352
	ds_read_b64_tr_b16 v[232:233], v64 offset:56704
	ds_read_b64_tr_b16 v[234:235], v64 offset:61056
	ds_read_b64_tr_b16 v[236:237], v64 offset:65408
	ds_read_b64_tr_b16 v[242:243], v64 offset:160
	ds_read_b64_tr_b16 v[244:245], v64 offset:4512
	ds_read_b64_tr_b16 v[246:247], v64 offset:8864
	ds_read_b64_tr_b16 v[248:249], v64 offset:13216
	v_mfma_f32_16x16x32_bf16 v[36:39], v[186:189], v[16:19], v[36:39]
	s_nop 2
	global_store_dwordx2 v[32:33], v[52:53], off offset:64
	s_waitcnt lgkmcnt(15)
	v_mfma_f32_16x16x32_bf16 v[36:39], v[190:193], v[24:27], v[36:39]
	s_waitcnt lgkmcnt(15)
	v_mfma_f32_16x16x32_bf16 v[36:39], v[194:197], v[28:31], v[36:39]
	s_waitcnt lgkmcnt(15)
	v_mfma_f32_16x16x32_bf16 v[36:39], v[198:201], v[20:23], v[36:39]
	s_nop 7
	v_mul_f32_e32 v35, v34, v36
	v_mul_f32_e32 v36, v34, v37
	v_mul_f32_e32 v37, v34, v38
	v_mul_f32_e32 v38, v34, v39
	v_cvt_pk_bf16_f32 v52, v35, v36
	v_cvt_pk_bf16_f32 v53, v37, v38
	s_nop 4
	s_waitcnt lgkmcnt(15)
	v_mfma_f32_16x16x32_bf16 v[36:39], v[202:205], v[0:3], 0
	s_nop 1
	s_waitcnt lgkmcnt(15)
	v_mfma_f32_16x16x32_bf16 v[36:39], v[206:209], v[4:7], v[36:39]
	s_nop 1
	s_waitcnt lgkmcnt(14)
	v_mfma_f32_16x16x32_bf16 v[36:39], v[210:213], v[8:11], v[36:39]
	s_nop 1
	s_waitcnt lgkmcnt(12)
	ds_read_b64_tr_b16 v[186:187], v64 offset:17568
	ds_read_b64_tr_b16 v[188:189], v64 offset:21920
	ds_read_b64_tr_b16 v[190:191], v64 offset:26272
	ds_read_b64_tr_b16 v[192:193], v64 offset:30624
	ds_read_b64_tr_b16 v[194:195], v64 offset:34976
	ds_read_b64_tr_b16 v[196:197], v64 offset:39328
	ds_read_b64_tr_b16 v[198:199], v64 offset:43680
	ds_read_b64_tr_b16 v[200:201], v64 offset:48032
	ds_read_b64_tr_b16 v[202:203], v64 offset:52384
	ds_read_b64_tr_b16 v[204:205], v64 offset:56736
	ds_read_b64_tr_b16 v[206:207], v64 offset:61088
	ds_read_b64_tr_b16 v[208:209], v64 offset:65440
	ds_read_b64_tr_b16 v[210:211], v64 offset:192
	ds_read_b64_tr_b16 v[212:213], v64 offset:4544
	v_mfma_f32_16x16x32_bf16 v[36:39], v[218:221], v[12:15], v[36:39]
	s_nop 1
	s_waitcnt lgkmcnt(15)
	v_mfma_f32_16x16x32_bf16 v[36:39], v[222:225], v[16:19], v[36:39]
	s_nop 2
	global_store_dwordx2 v[32:33], v[52:53], off offset:96
	s_waitcnt lgkmcnt(15)
	v_mfma_f32_16x16x32_bf16 v[36:39], v[226:229], v[24:27], v[36:39]
	s_waitcnt lgkmcnt(15)
	v_mfma_f32_16x16x32_bf16 v[36:39], v[230:233], v[28:31], v[36:39]
	s_waitcnt lgkmcnt(15)
	v_mfma_f32_16x16x32_bf16 v[36:39], v[234:237], v[20:23], v[36:39]
	s_nop 7
	v_mul_f32_e32 v35, v34, v36
	v_mul_f32_e32 v36, v34, v37
	v_mul_f32_e32 v37, v34, v38
	v_mul_f32_e32 v38, v34, v39
	v_cvt_pk_bf16_f32 v52, v35, v36
	v_cvt_pk_bf16_f32 v53, v37, v38
	s_nop 4
	s_waitcnt lgkmcnt(15)
; #define LAS __attribute__((address_space(3)))
; __device__ __forceinline__ unsigned pk2(float lo, float hi) { return pg8::cvt_pk_bf16(lo, hi); }
; __device__ __forceinline__ v2u vtr(const LAS bf16* p) { return __builtin_bit_cast(v2u, __builtin_amdgcn_ds_read_tr16_b64_v4i16((LAS v4i16_t*)p)); }
; template <bool SAMPLE>
; __device__ __forceinline__ void mem_unit(const Params& p, int l, LAS unsigned char* lds, int unit, int tid, int wave, int lane) {
;     ...
; #pragma unroll
;         for (int dt = 0; dt < 8; ++dt) { f32x4 o = (f32x4){0.f, 0.f, 0.f, 0.f};
; #pragma unroll
;             for (int cc = 0; cc < 8; ++cc) { const LAS bf16* vp = Vt + (32 * cc + 4 * kq + (q16 >> 2)) * MEM_VS + 16 * dt + 4 * (q16 & 3);
;                 const v2u lo = vtr(vp), hi = vtr(vp + 16 * MEM_VS);
;                 v4u av; av.x = lo.x; av.y = lo.y; av.z = hi.x; av.w = hi.y;
;                 o = __builtin_amdgcn_mfma_f32_16x16x32_bf16(__builtin_bit_cast(bf16x8, av), pf[cc], o, 0, 0, 0); }
;             if (st) { v2u w; w.x = pk2(o[0] * rden, o[1] * rden); w.y = pk2(o[2] * rden, o[3] * rden);
;                 *(v2u*)(MO + row * 512 + h * 128 + 16 * dt + 4 * kq) = w; } }
	v_mfma_f32_16x16x32_bf16 v[36:39], v[242:245], v[0:3], 0
	s_nop 1
	s_waitcnt lgkmcnt(14)
	v_mfma_f32_16x16x32_bf16 v[36:39], v[246:249], v[4:7], v[36:39]
	s_nop 1
	s_waitcnt lgkmcnt(12)
	ds_read_b64_tr_b16 v[218:219], v64 offset:8896
	ds_read_b64_tr_b16 v[220:221], v64 offset:13248
	ds_read_b64_tr_b16 v[222:223], v64 offset:17600
	ds_read_b64_tr_b16 v[224:225], v64 offset:21952
	ds_read_b64_tr_b16 v[226:227], v64 offset:26304
	ds_read_b64_tr_b16 v[228:229], v64 offset:30656
	ds_read_b64_tr_b16 v[230:231], v64 offset:35008
	ds_read_b64_tr_b16 v[232:233], v64 offset:39360
	ds_read_b64_tr_b16 v[234:235], v64 offset:43712
	ds_read_b64_tr_b16 v[236:237], v64 offset:48064
	ds_read_b64_tr_b16 v[242:243], v64 offset:61120
	ds_read_b64_tr_b16 v[244:245], v64 offset:65472
	ds_read_b64_tr_b16 v[246:247], v64 offset:224
	ds_read_b64_tr_b16 v[248:249], v64 offset:4576
	v_mfma_f32_16x16x32_bf16 v[36:39], v[186:189], v[8:11], v[36:39]
	s_nop 1
	s_waitcnt lgkmcnt(15)
	v_mfma_f32_16x16x32_bf16 v[36:39], v[190:193], v[12:15], v[36:39]
	s_nop 1
	s_waitcnt lgkmcnt(15)
	v_mfma_f32_16x16x32_bf16 v[36:39], v[194:197], v[16:19], v[36:39]
	s_nop 2
	global_store_dwordx2 v[32:33], v[52:53], off offset:128
	s_waitcnt lgkmcnt(15)
	v_mfma_f32_16x16x32_bf16 v[36:39], v[198:201], v[24:27], v[36:39]
	s_waitcnt lgkmcnt(15)
	v_mfma_f32_16x16x32_bf16 v[36:39], v[202:205], v[28:31], v[36:39]
	s_waitcnt lgkmcnt(15)
	v_mfma_f32_16x16x32_bf16 v[36:39], v[206:209], v[20:23], v[36:39]
	s_nop 7
	v_mul_f32_e32 v35, v34, v36
	v_mul_f32_e32 v36, v34, v37
	v_mul_f32_e32 v37, v34, v38
	v_mul_f32_e32 v38, v34, v39
	v_cvt_pk_bf16_f32 v52, v35, v36
	v_cvt_pk_bf16_f32 v53, v37, v38
	s_nop 4
	s_waitcnt lgkmcnt(14)
	v_mfma_f32_16x16x32_bf16 v[36:39], v[210:213], v[0:3], 0
	s_nop 1
	s_waitcnt lgkmcnt(12)
	ds_read_b64_tr_b16 v[186:187], v64 offset:35040
	ds_read_b64_tr_b16 v[188:189], v64 offset:39392
	v_mfma_f32_16x16x32_bf16 v[36:39], v[218:221], v[4:7], v[36:39]
	s_nop 1
	s_waitcnt lgkmcnt(12)
	v_mfma_f32_16x16x32_bf16 v[36:39], v[222:225], v[8:11], v[36:39]
	s_nop 1
	s_waitcnt lgkmcnt(10)
	v_mfma_f32_16x16x32_bf16 v[36:39], v[226:229], v[12:15], v[36:39]
	s_nop 0
	ds_read_b64_tr_b16 v[48:49], v64 offset:52416
	s_waitcnt lgkmcnt(9)
	v_mfma_f32_16x16x32_bf16 v[36:39], v[230:233], v[16:19], v[36:39]
	ds_read_b64_tr_b16 v[50:51], v64 offset:56768
	s_nop 1
	global_store_dwordx2 v[32:33], v[52:53], off offset:160
	s_waitcnt lgkmcnt(8)
	v_mfma_f32_16x16x32_bf16 v[36:39], v[234:237], v[24:27], v[36:39]
	s_waitcnt lgkmcnt(0)
	v_mfma_f32_16x16x32_bf16 v[36:39], v[48:51], v[28:31], v[36:39]
	s_nop 0
	v_mfma_f32_16x16x32_bf16 v[36:39], v[242:245], v[20:23], v[36:39]
	s_nop 7
	v_mul_f32_e32 v35, v34, v36
	v_mul_f32_e32 v36, v34, v37
	v_mul_f32_e32 v37, v34, v38
	v_mul_f32_e32 v38, v34, v39
	v_cvt_pk_bf16_f32 v48, v35, v36
	v_cvt_pk_bf16_f32 v49, v37, v38
	s_nop 1
	ds_read_b64_tr_b16 v[40:41], v64 offset:8928
	ds_read_b64_tr_b16 v[42:43], v64 offset:13280
	ds_read_b64_tr_b16 v[44:45], v64 offset:17632
	s_nop 0
	v_mfma_f32_16x16x32_bf16 v[0:3], v[246:249], v[0:3], 0
	ds_read_b64_tr_b16 v[46:47], v64 offset:21984
	ds_read_b64_tr_b16 v[36:37], v64 offset:26336
	s_waitcnt lgkmcnt(3)
	v_mfma_f32_16x16x32_bf16 v[0:3], v[40:43], v[4:7], v[0:3]
	ds_read_b64_tr_b16 v[38:39], v64 offset:30688
	s_nop 0
	s_waitcnt lgkmcnt(2)
	v_mfma_f32_16x16x32_bf16 v[0:3], v[44:47], v[8:11], v[0:3]
	s_nop 0
	ds_read_b64_tr_b16 v[8:9], v64 offset:43744
	s_waitcnt lgkmcnt(1)
	v_mfma_f32_16x16x32_bf16 v[0:3], v[36:39], v[12:15], v[0:3]
	ds_read_b64_tr_b16 v[10:11], v64 offset:48096
	ds_read_b64_tr_b16 v[12:13], v64 offset:52448
	s_nop 0
	v_mfma_f32_16x16x32_bf16 v[0:3], v[186:189], v[16:19], v[0:3]
	ds_read_b64_tr_b16 v[14:15], v64 offset:56800
	ds_read_b64_tr_b16 v[4:5], v64 offset:61152
	ds_read_b64_tr_b16 v[6:7], v64 offset:65504
	global_store_dwordx2 v[32:33], v[48:49], off offset:192
	s_waitcnt lgkmcnt(4)
	v_mfma_f32_16x16x32_bf16 v[0:3], v[8:11], v[24:27], v[0:3]
	s_waitcnt lgkmcnt(2)
	v_mfma_f32_16x16x32_bf16 v[0:3], v[12:15], v[28:31], v[0:3]
	s_waitcnt lgkmcnt(0)
	v_mfma_f32_16x16x32_bf16 v[0:3], v[4:7], v[20:23], v[0:3]
	s_nop 7
	v_mul_f32_e32 v0, v34, v0
	v_mul_f32_e32 v1, v34, v1
	v_mul_f32_e32 v2, v34, v2
	v_mul_f32_e32 v3, v34, v3
	v_cvt_pk_bf16_f32 v0, v0, v1
	v_cvt_pk_bf16_f32 v1, v2, v3
	global_store_dwordx2 v[32:33], v[0:1], off offset:224
	s_cbranch_scc1 .LBB0_2762
	s_nop 0
	s_nop 0
	s_barrier
	s_branch .LBB0_2727
